# barrier-first plus s_setprio 3 hoisted above the leading barrier (no instruction between barrier release and the first MFMA)
# baseline (speedup 1.0000x reference)
; #define PG8_STAGE(bufoff, gbase, voff) do { _Pragma("unroll") for (int _i = 0; _i < 2; ++_i) \
;         __builtin_amdgcn_global_load_lds((const unsigned*)((const char*)(gbase) + (voff)[_i]), (PG8_LAS unsigned*)(lds + (bufoff) + ldsw + _i * 8192), 16, 0, 0); } while (0)
; #define PG8_LDA(dst, b, h) do { _Pragma("unroll") for (int m = 0; m < 4; ++m) _Pragma("unroll") for (int k = 0; k < 2; ++k) dst[m][k] = *(const PG8_LAS bf16x8*)(lds + PG8_SA(b, h) + aoff + m * 2048 + k * 1024); } while (0)
; #define PG8_MMA(ai, bj, At, Bt) do { __builtin_amdgcn_s_setprio(3); _Pragma("unroll") for (int m = 0; m < 4; ++m) _Pragma("unroll") for (int n = 0; n < 2; ++n) _Pragma("unroll") for (int k = 0; k < 2; ++k) \
;         acc[ai][bj][m][n] = __builtin_amdgcn_mfma_f32_16x16x32_bf16(Bt[n][k], At[m][k], acc[ai][bj][m][n], 0, 0, 0); __builtin_amdgcn_s_setprio(0); } while (0)
; #define PG8_WAIT_V(n) asm volatile("s_waitcnt vmcnt(" #n ")" ::: "memory")
; #define PG8_WAIT_L(n) asm volatile("s_waitcnt lgkmcnt(" #n ")" ::: "memory")
; #define PG8_BAR __builtin_amdgcn_s_barrier()
; #define PG8_SCHED __builtin_amdgcn_sched_barrier(0)
; template <class Epi, class Sched, bool ALIGN_EPI = false, bool SP2 = false>
; __device__ __forceinline__ void gemm_phase(PG8_LAS unsigned char* lds, const Gemm g, const Sched& S, const Epi& E) {
;     ...
;             PG8_WAIT_V(8); PG8_WAIT_L(0); PG8_BAR; PG8_MMA(0, 0, At, B0); PG8_MMA(0, 1, At, B1); PG8_BAR; PG8_SCHED;
;             PG8_LDA(At, 0, 1); PG8_STAGE(PG8_SB(0, 0), b2, voffB); PG8_STAGE(PG8_SB(0, 1), b2 + hstepB, voffB); PG8_STAGE(PG8_SA(0, 0), a2, voffA);
;             PG8_WAIT_V(8); PG8_WAIT_L(0); PG8_BAR; PG8_MMA(1, 0, At, B0); PG8_MMA(1, 1, At, B1); PG8_BAR; PG8_SCHED;
.Lengw1_e:
	s_waitcnt lgkmcnt(0)
	s_setprio 3
	s_barrier
	v_mfma_f32_16x16x32_bf16 v[126:129], v[130:133], v[192:195], v[126:129]
	v_mfma_f32_16x16x32_bf16 v[126:129], v[134:137], v[196:199], v[126:129]
	v_mfma_f32_16x16x32_bf16 v[118:121], v[156:159], v[192:195], v[118:121]
	v_mfma_f32_16x16x32_bf16 v[118:121], v[172:175], v[196:199], v[118:121]
	v_mfma_f32_16x16x32_bf16 v[102:105], v[156:159], v[200:203], v[102:105]
	v_mfma_f32_16x16x32_bf16 v[102:105], v[172:175], v[204:207], v[102:105]
	v_mfma_f32_16x16x32_bf16 v[110:113], v[130:133], v[200:203], v[110:113]
	v_mfma_f32_16x16x32_bf16 v[110:113], v[134:137], v[204:207], v[110:113]
	v_mfma_f32_16x16x32_bf16 v[94:97], v[130:133], v[208:211], v[94:97]
	v_mfma_f32_16x16x32_bf16 v[94:97], v[134:137], v[212:215], v[94:97]
	v_mfma_f32_16x16x32_bf16 v[86:89], v[156:159], v[208:211], v[86:89]
	v_mfma_f32_16x16x32_bf16 v[86:89], v[172:175], v[212:215], v[86:89]
	v_mfma_f32_16x16x32_bf16 v[70:73], v[156:159], v[216:219], v[70:73]
	v_mfma_f32_16x16x32_bf16 v[70:73], v[172:175], v[220:223], v[70:73]
	v_mfma_f32_16x16x32_bf16 v[78:81], v[130:133], v[216:219], v[78:81]
	v_mfma_f32_16x16x32_bf16 v[78:81], v[134:137], v[220:223], v[78:81]
	v_mfma_f32_16x16x32_bf16 v[122:125], v[176:179], v[192:195], v[122:125]
	v_mfma_f32_16x16x32_bf16 v[122:125], v[180:183], v[196:199], v[122:125]
	v_mfma_f32_16x16x32_bf16 v[114:117], v[184:187], v[192:195], v[114:117]
	v_mfma_f32_16x16x32_bf16 v[114:117], v[188:191], v[196:199], v[114:117]
	v_mfma_f32_16x16x32_bf16 v[98:101], v[184:187], v[200:203], v[98:101]
	v_mfma_f32_16x16x32_bf16 v[98:101], v[188:191], v[204:207], v[98:101]
	v_mfma_f32_16x16x32_bf16 v[106:109], v[176:179], v[200:203], v[106:109]
	v_mfma_f32_16x16x32_bf16 v[106:109], v[180:183], v[204:207], v[106:109]
	v_mfma_f32_16x16x32_bf16 v[90:93], v[176:179], v[208:211], v[90:93]
	v_mfma_f32_16x16x32_bf16 v[90:93], v[180:183], v[212:215], v[90:93]
	v_mfma_f32_16x16x32_bf16 v[82:85], v[184:187], v[208:211], v[82:85]
	v_mfma_f32_16x16x32_bf16 v[82:85], v[188:191], v[212:215], v[82:85]
	v_mfma_f32_16x16x32_bf16 v[66:69], v[184:187], v[216:219], v[66:69]
	v_mfma_f32_16x16x32_bf16 v[66:69], v[188:191], v[220:223], v[66:69]
	v_mfma_f32_16x16x32_bf16 v[74:77], v[176:179], v[216:219], v[74:77]
	v_mfma_f32_16x16x32_bf16 v[74:77], v[180:183], v[220:223], v[74:77]
	s_barrier
	s_setprio 0
	s_add_i32 s56, s83, s66
	v_lshl_add_u64 v[160:161], s[8:9], 0, v[140:141]
	s_mov_b32 m0, s56
	ds_read_b128 v[192:195], v169 offset:16384
	ds_read_b128 v[196:199], v169 offset:17408
	ds_read_b128 v[200:203], v169 offset:18432
	ds_read_b128 v[204:207], v169 offset:19456
	ds_read_b128 v[208:211], v169 offset:20480
	ds_read_b128 v[212:215], v169 offset:21504
	ds_read_b128 v[216:219], v169 offset:22528
	ds_read_b128 v[220:223], v169 offset:23552
	global_load_lds_dwordx4 v[160:161], off
	s_add_i32 m0, s56, 0x2000
	s_add_u32 s56, s8, 0x100000
	v_lshl_add_u64 v[224:225], s[8:9], 0, v[144:145]
	s_addc_u32 s57, s9, 0
	s_add_i32 s58, s89, s66
	global_load_lds_dwordx4 v[224:225], off
	v_lshl_add_u64 v[226:227], s[56:57], 0, v[140:141]
	s_mov_b32 m0, s58
	v_lshl_add_u64 v[228:229], s[36:37], 0, v[142:143]
	global_load_lds_dwordx4 v[226:227], off
	v_lshl_add_u64 v[226:227], s[56:57], 0, v[144:145]
	s_add_i32 m0, s58, 0x2000
	s_nop 0
	global_load_lds_dwordx4 v[226:227], off
	v_lshl_add_u64 v[226:227], s[36:37], 0, v[138:139]
	s_mov_b32 m0, s55
	s_nop 0
	global_load_lds_dwordx4 v[226:227], off
	s_mov_b32 m0, s67
	s_nop 0
	global_load_lds_dwordx4 v[228:229], off
	s_cmp_eq_u32 s97, 0
	s_cbranch_scc1 .Lengw2_a
	s_cmp_eq_u32 s97, 2
	s_cbranch_scc1 .Lengw2_b
	s_cmp_eq_u32 s97, 4
	s_cbranch_scc1 .Lengw2_c
	s_waitcnt vmcnt(16)
	s_branch .Lengw2_e

; #define PG8_STAGE(bufoff, gbase, voff) do { _Pragma("unroll") for (int _i = 0; _i < 2; ++_i) \
;         __builtin_amdgcn_global_load_lds((const unsigned*)((const char*)(gbase) + (voff)[_i]), (PG8_LAS unsigned*)(lds + (bufoff) + ldsw + _i * 8192), 16, 0, 0); } while (0)
; #define PG8_LDA(dst, b, h) do { _Pragma("unroll") for (int m = 0; m < 4; ++m) _Pragma("unroll") for (int k = 0; k < 2; ++k) dst[m][k] = *(const PG8_LAS bf16x8*)(lds + PG8_SA(b, h) + aoff + m * 2048 + k * 1024); } while (0)
; #define PG8_LDB(dst, b, h) do { _Pragma("unroll") for (int n = 0; n < 2; ++n) _Pragma("unroll") for (int k = 0; k < 2; ++k) dst[n][k] = *(const PG8_LAS bf16x8*)(lds + PG8_SB(b, h) + boff + n * 2048 + k * 1024); } while (0)
; #define PG8_MMA(ai, bj, At, Bt) do { __builtin_amdgcn_s_setprio(3); _Pragma("unroll") for (int m = 0; m < 4; ++m) _Pragma("unroll") for (int n = 0; n < 2; ++n) _Pragma("unroll") for (int k = 0; k < 2; ++k) \
;         acc[ai][bj][m][n] = __builtin_amdgcn_mfma_f32_16x16x32_bf16(Bt[n][k], At[m][k], acc[ai][bj][m][n], 0, 0, 0); __builtin_amdgcn_s_setprio(0); } while (0)
; #define PG8_WAIT_V(n) asm volatile("s_waitcnt vmcnt(" #n ")" ::: "memory")
; #define PG8_WAIT_L(n) asm volatile("s_waitcnt lgkmcnt(" #n ")" ::: "memory")
; #define PG8_BAR __builtin_amdgcn_s_barrier()
; #define PG8_SCHED __builtin_amdgcn_sched_barrier(0)
; template <class Epi, class Sched, bool ALIGN_EPI = false, bool SP2 = false>
; __device__ __forceinline__ void gemm_phase(PG8_LAS unsigned char* lds, const Gemm g, const Sched& S, const Epi& E) {
;     ...
;             PG8_WAIT_V(8); PG8_WAIT_L(0); PG8_BAR; PG8_MMA(1, 0, At, B0); PG8_MMA(1, 1, At, B1); PG8_BAR; PG8_SCHED;
;             PG8_LDB(B0, 1, 0); PG8_LDB(B1, 1, 1); PG8_SCHED; PG8_LDA(At, 1, 0); PG8_STAGE(PG8_SA(0, 1), a2 + hstepA, voffA);
;             PG8_WAIT_V(8); PG8_WAIT_L(0); PG8_BAR; PG8_MMA(0, 0, At, B0); PG8_MMA(0, 1, At, B1); PG8_BAR; PG8_SCHED;
.Lengw2_e:
	s_waitcnt lgkmcnt(0)
	s_setprio 3
	s_barrier
	v_mfma_f32_16x16x32_bf16 v[62:65], v[130:133], v[192:195], v[62:65]
	v_mfma_f32_16x16x32_bf16 v[62:65], v[134:137], v[196:199], v[62:65]
	v_mfma_f32_16x16x32_bf16 v[54:57], v[156:159], v[192:195], v[54:57]
	v_mfma_f32_16x16x32_bf16 v[54:57], v[172:175], v[196:199], v[54:57]
	v_mfma_f32_16x16x32_bf16 v[38:41], v[156:159], v[200:203], v[38:41]
	v_mfma_f32_16x16x32_bf16 v[38:41], v[172:175], v[204:207], v[38:41]
	v_mfma_f32_16x16x32_bf16 v[46:49], v[130:133], v[200:203], v[46:49]
	v_mfma_f32_16x16x32_bf16 v[46:49], v[134:137], v[204:207], v[46:49]
	v_mfma_f32_16x16x32_bf16 v[30:33], v[130:133], v[208:211], v[30:33]
	v_mfma_f32_16x16x32_bf16 v[30:33], v[134:137], v[212:215], v[30:33]
	v_mfma_f32_16x16x32_bf16 v[22:25], v[156:159], v[208:211], v[22:25]
	v_mfma_f32_16x16x32_bf16 v[22:25], v[172:175], v[212:215], v[22:25]
	v_mfma_f32_16x16x32_bf16 v[6:9], v[156:159], v[216:219], v[6:9]
	v_mfma_f32_16x16x32_bf16 v[6:9], v[172:175], v[220:223], v[6:9]
	v_mfma_f32_16x16x32_bf16 v[14:17], v[130:133], v[216:219], v[14:17]
	v_mfma_f32_16x16x32_bf16 v[14:17], v[134:137], v[220:223], v[14:17]
	v_mfma_f32_16x16x32_bf16 v[58:61], v[176:179], v[192:195], v[58:61]
	v_mfma_f32_16x16x32_bf16 v[58:61], v[180:183], v[196:199], v[58:61]
	v_mfma_f32_16x16x32_bf16 v[50:53], v[184:187], v[192:195], v[50:53]
	v_mfma_f32_16x16x32_bf16 v[50:53], v[188:191], v[196:199], v[50:53]
	v_mfma_f32_16x16x32_bf16 v[34:37], v[184:187], v[200:203], v[34:37]
	v_mfma_f32_16x16x32_bf16 v[34:37], v[188:191], v[204:207], v[34:37]
	v_mfma_f32_16x16x32_bf16 v[42:45], v[176:179], v[200:203], v[42:45]
	v_mfma_f32_16x16x32_bf16 v[42:45], v[180:183], v[204:207], v[42:45]
	v_mfma_f32_16x16x32_bf16 v[26:29], v[176:179], v[208:211], v[26:29]
	v_mfma_f32_16x16x32_bf16 v[26:29], v[180:183], v[212:215], v[26:29]
	v_mfma_f32_16x16x32_bf16 v[18:21], v[184:187], v[208:211], v[18:21]
	v_mfma_f32_16x16x32_bf16 v[18:21], v[188:191], v[212:215], v[18:21]
	v_mfma_f32_16x16x32_bf16 v[2:5], v[184:187], v[216:219], v[2:5]
	v_mfma_f32_16x16x32_bf16 v[2:5], v[188:191], v[220:223], v[2:5]
	v_mfma_f32_16x16x32_bf16 v[10:13], v[176:179], v[216:219], v[10:13]
	v_mfma_f32_16x16x32_bf16 v[10:13], v[180:183], v[220:223], v[10:13]
	s_barrier
	s_setprio 0
	s_add_i32 s56, 0, 0x18000
	v_add_u32_e32 v146, s56, v164
	s_add_i32 s57, 0, 0x1c000
	ds_read_b128 v[130:133], v146
	ds_read_b128 v[134:137], v146 offset:1024
	ds_read_b128 v[156:159], v146 offset:2048
	ds_read_b128 v[172:175], v146 offset:3072
	v_add_u32_e32 v146, s57, v164
	ds_read_b128 v[176:179], v146
	ds_read_b128 v[180:183], v146 offset:1024
	ds_read_b128 v[184:187], v146 offset:2048
	ds_read_b128 v[188:191], v146 offset:3072
	s_add_u32 s36, s36, 0x100000
	s_addc_u32 s37, s37, 0
	s_mov_b32 m0, s72
	v_lshl_add_u64 v[230:231], s[36:37], 0, v[138:139]
	ds_read_b128 v[192:195], v169 offset:32768
	ds_read_b128 v[196:199], v169 offset:33792
	ds_read_b128 v[200:203], v169 offset:34816
	ds_read_b128 v[204:207], v169 offset:35840
	ds_read_b128 v[208:211], v169 offset:36864
	ds_read_b128 v[212:215], v169 offset:37888
	ds_read_b128 v[216:219], v169 offset:38912
	ds_read_b128 v[220:223], v169 offset:39936
	global_load_lds_dwordx4 v[230:231], off
	v_lshl_add_u64 v[230:231], s[36:37], 0, v[142:143]
	s_mov_b32 m0, s73
	s_nop 0
	global_load_lds_dwordx4 v[230:231], off
	s_cmp_eq_u32 s97, 4
	s_cbranch_scc1 .Lengw3_c
	s_cmp_eq_u32 s97, 8
	s_cbranch_scc1 .Lengw3_d
	s_waitcnt vmcnt(8)
	s_branch .Lengw3_e

; #define PG8_STAGE(bufoff, gbase, voff) do { _Pragma("unroll") for (int _i = 0; _i < 2; ++_i) \
;         __builtin_amdgcn_global_load_lds((const unsigned*)((const char*)(gbase) + (voff)[_i]), (PG8_LAS unsigned*)(lds + (bufoff) + ldsw + _i * 8192), 16, 0, 0); } while (0)
; #define PG8_LDA(dst, b, h) do { _Pragma("unroll") for (int m = 0; m < 4; ++m) _Pragma("unroll") for (int k = 0; k < 2; ++k) dst[m][k] = *(const PG8_LAS bf16x8*)(lds + PG8_SA(b, h) + aoff + m * 2048 + k * 1024); } while (0)
; #define PG8_LDB(dst, b, h) do { _Pragma("unroll") for (int n = 0; n < 2; ++n) _Pragma("unroll") for (int k = 0; k < 2; ++k) dst[n][k] = *(const PG8_LAS bf16x8*)(lds + PG8_SB(b, h) + boff + n * 2048 + k * 1024); } while (0)
; #define PG8_MMA(ai, bj, At, Bt) do { __builtin_amdgcn_s_setprio(3); _Pragma("unroll") for (int m = 0; m < 4; ++m) _Pragma("unroll") for (int n = 0; n < 2; ++n) _Pragma("unroll") for (int k = 0; k < 2; ++k) \
;         acc[ai][bj][m][n] = __builtin_amdgcn_mfma_f32_16x16x32_bf16(Bt[n][k], At[m][k], acc[ai][bj][m][n], 0, 0, 0); __builtin_amdgcn_s_setprio(0); } while (0)
; #define PG8_WAIT_V(n) asm volatile("s_waitcnt vmcnt(" #n ")" ::: "memory")
; #define PG8_WAIT_L(n) asm volatile("s_waitcnt lgkmcnt(" #n ")" ::: "memory")
; #define PG8_BAR __builtin_amdgcn_s_barrier()
; #define PG8_SCHED __builtin_amdgcn_sched_barrier(0)
; template <class Epi, class Sched, bool ALIGN_EPI = false, bool SP2 = false>
; __device__ __forceinline__ void gemm_phase(PG8_LAS unsigned char* lds, const Gemm g, const Sched& S, const Epi& E) {
;     ...
;             PG8_LDB(B0, 1, 0); PG8_LDB(B1, 1, 1); PG8_SCHED; PG8_LDA(At, 1, 0); PG8_STAGE(PG8_SA(0, 1), a2 + hstepA, voffA);
;             PG8_WAIT_V(8); PG8_WAIT_L(0); PG8_BAR; PG8_MMA(0, 0, At, B0); PG8_MMA(0, 1, At, B1); PG8_BAR; PG8_SCHED;
;             PG8_LDA(At, 1, 1); PG8_STAGE(PG8_SB(1, 0), b3, voffB); PG8_STAGE(PG8_SB(1, 1), b3 + hstepB, voffB); PG8_STAGE(PG8_SA(1, 0), a3, voffA);
;             PG8_WAIT_V(8); PG8_WAIT_L(0); PG8_BAR; PG8_MMA(1, 0, At, B0); PG8_MMA(1, 1, At, B1); PG8_BAR; PG8_SCHED;
.Lengw3_e:
	s_waitcnt lgkmcnt(0)
	s_setprio 3
	s_barrier
	v_mfma_f32_16x16x32_bf16 v[126:129], v[130:133], v[192:195], v[126:129]
	v_mfma_f32_16x16x32_bf16 v[126:129], v[134:137], v[196:199], v[126:129]
	v_mfma_f32_16x16x32_bf16 v[118:121], v[156:159], v[192:195], v[118:121]
	v_mfma_f32_16x16x32_bf16 v[118:121], v[172:175], v[196:199], v[118:121]
	v_mfma_f32_16x16x32_bf16 v[102:105], v[156:159], v[200:203], v[102:105]
	v_mfma_f32_16x16x32_bf16 v[102:105], v[172:175], v[204:207], v[102:105]
	v_mfma_f32_16x16x32_bf16 v[110:113], v[130:133], v[200:203], v[110:113]
	v_mfma_f32_16x16x32_bf16 v[110:113], v[134:137], v[204:207], v[110:113]
	v_mfma_f32_16x16x32_bf16 v[94:97], v[130:133], v[208:211], v[94:97]
	v_mfma_f32_16x16x32_bf16 v[94:97], v[134:137], v[212:215], v[94:97]
	v_mfma_f32_16x16x32_bf16 v[86:89], v[156:159], v[208:211], v[86:89]
	v_mfma_f32_16x16x32_bf16 v[86:89], v[172:175], v[212:215], v[86:89]
	v_mfma_f32_16x16x32_bf16 v[70:73], v[156:159], v[216:219], v[70:73]
	v_mfma_f32_16x16x32_bf16 v[70:73], v[172:175], v[220:223], v[70:73]
	v_mfma_f32_16x16x32_bf16 v[78:81], v[130:133], v[216:219], v[78:81]
	v_mfma_f32_16x16x32_bf16 v[78:81], v[134:137], v[220:223], v[78:81]
	v_mfma_f32_16x16x32_bf16 v[122:125], v[176:179], v[192:195], v[122:125]
	v_mfma_f32_16x16x32_bf16 v[122:125], v[180:183], v[196:199], v[122:125]
	v_mfma_f32_16x16x32_bf16 v[114:117], v[184:187], v[192:195], v[114:117]
	v_mfma_f32_16x16x32_bf16 v[114:117], v[188:191], v[196:199], v[114:117]
	v_mfma_f32_16x16x32_bf16 v[98:101], v[184:187], v[200:203], v[98:101]
	v_mfma_f32_16x16x32_bf16 v[98:101], v[188:191], v[204:207], v[98:101]
	v_mfma_f32_16x16x32_bf16 v[106:109], v[176:179], v[200:203], v[106:109]
	v_mfma_f32_16x16x32_bf16 v[106:109], v[180:183], v[204:207], v[106:109]
	v_mfma_f32_16x16x32_bf16 v[90:93], v[176:179], v[208:211], v[90:93]
	v_mfma_f32_16x16x32_bf16 v[90:93], v[180:183], v[212:215], v[90:93]
	v_mfma_f32_16x16x32_bf16 v[82:85], v[184:187], v[208:211], v[82:85]
	v_mfma_f32_16x16x32_bf16 v[82:85], v[188:191], v[212:215], v[82:85]
	v_mfma_f32_16x16x32_bf16 v[66:69], v[184:187], v[216:219], v[66:69]
	v_mfma_f32_16x16x32_bf16 v[66:69], v[188:191], v[220:223], v[66:69]
	v_mfma_f32_16x16x32_bf16 v[74:77], v[176:179], v[216:219], v[74:77]
	v_mfma_f32_16x16x32_bf16 v[74:77], v[180:183], v[220:223], v[74:77]
	s_barrier
	s_setprio 0
	s_add_i32 s36, s56, s66
	v_lshl_add_u64 v[160:161], v[160:161], 0, s[18:19]
	s_mov_b32 m0, s36
	ds_read_b128 v[192:195], v169 offset:49152
	ds_read_b128 v[196:199], v169 offset:50176
	ds_read_b128 v[200:203], v169 offset:51200
	ds_read_b128 v[204:207], v169 offset:52224
	ds_read_b128 v[208:211], v169 offset:53248
	ds_read_b128 v[212:215], v169 offset:54272
	ds_read_b128 v[216:219], v169 offset:55296
	ds_read_b128 v[220:223], v169 offset:56320
	global_load_lds_dwordx4 v[160:161], off
	s_add_i32 m0, s36, 0x2000
	s_add_u32 s8, s8, 0x100080
	v_lshl_add_u64 v[160:161], v[224:225], 0, s[18:19]
	s_addc_u32 s9, s9, 0
	s_add_i32 s36, s57, s66
	global_load_lds_dwordx4 v[160:161], off
	v_lshl_add_u64 v[160:161], s[8:9], 0, v[140:141]
	s_mov_b32 m0, s36
	s_nop 0
	global_load_lds_dwordx4 v[160:161], off
	v_lshl_add_u64 v[160:161], s[8:9], 0, v[144:145]
	s_add_i32 m0, s36, 0x2000
	s_nop 0
	global_load_lds_dwordx4 v[160:161], off
	v_lshl_add_u64 v[160:161], v[226:227], 0, s[18:19]
	s_mov_b32 m0, s75
	s_nop 0
	global_load_lds_dwordx4 v[160:161], off
	v_lshl_add_u64 v[160:161], v[228:229], 0, s[18:19]
	s_mov_b32 m0, s76
	s_nop 0
	global_load_lds_dwordx4 v[160:161], off
	s_waitcnt vmcnt(8)
	s_waitcnt lgkmcnt(0)
	s_setprio 3
	s_barrier
	v_mfma_f32_16x16x32_bf16 v[62:65], v[130:133], v[192:195], v[62:65]
	v_mfma_f32_16x16x32_bf16 v[62:65], v[134:137], v[196:199], v[62:65]
	v_mfma_f32_16x16x32_bf16 v[54:57], v[156:159], v[192:195], v[54:57]
	v_mfma_f32_16x16x32_bf16 v[54:57], v[172:175], v[196:199], v[54:57]
	v_mfma_f32_16x16x32_bf16 v[38:41], v[156:159], v[200:203], v[38:41]
	v_mfma_f32_16x16x32_bf16 v[38:41], v[172:175], v[204:207], v[38:41]
	v_mfma_f32_16x16x32_bf16 v[46:49], v[130:133], v[200:203], v[46:49]
	v_mfma_f32_16x16x32_bf16 v[46:49], v[134:137], v[204:207], v[46:49]
	v_mfma_f32_16x16x32_bf16 v[30:33], v[130:133], v[208:211], v[30:33]
	v_mfma_f32_16x16x32_bf16 v[30:33], v[134:137], v[212:215], v[30:33]
	v_mfma_f32_16x16x32_bf16 v[22:25], v[156:159], v[208:211], v[22:25]
	v_mfma_f32_16x16x32_bf16 v[22:25], v[172:175], v[212:215], v[22:25]
	v_mfma_f32_16x16x32_bf16 v[6:9], v[156:159], v[216:219], v[6:9]
	v_mfma_f32_16x16x32_bf16 v[6:9], v[172:175], v[220:223], v[6:9]
	v_mfma_f32_16x16x32_bf16 v[14:17], v[130:133], v[216:219], v[14:17]
	v_mfma_f32_16x16x32_bf16 v[14:17], v[134:137], v[220:223], v[14:17]
	v_mfma_f32_16x16x32_bf16 v[58:61], v[176:179], v[192:195], v[58:61]
	v_mfma_f32_16x16x32_bf16 v[58:61], v[180:183], v[196:199], v[58:61]
	v_mfma_f32_16x16x32_bf16 v[50:53], v[184:187], v[192:195], v[50:53]
	v_mfma_f32_16x16x32_bf16 v[50:53], v[188:191], v[196:199], v[50:53]
	v_mfma_f32_16x16x32_bf16 v[34:37], v[184:187], v[200:203], v[34:37]
	v_mfma_f32_16x16x32_bf16 v[34:37], v[188:191], v[204:207], v[34:37]
	v_mfma_f32_16x16x32_bf16 v[42:45], v[176:179], v[200:203], v[42:45]
	v_mfma_f32_16x16x32_bf16 v[42:45], v[180:183], v[204:207], v[42:45]
	v_mfma_f32_16x16x32_bf16 v[26:29], v[176:179], v[208:211], v[26:29]
	v_mfma_f32_16x16x32_bf16 v[26:29], v[180:183], v[212:215], v[26:29]
	v_mfma_f32_16x16x32_bf16 v[18:21], v[184:187], v[208:211], v[18:21]
	v_mfma_f32_16x16x32_bf16 v[18:21], v[188:191], v[212:215], v[18:21]
	v_mfma_f32_16x16x32_bf16 v[2:5], v[184:187], v[216:219], v[2:5]
	v_mfma_f32_16x16x32_bf16 v[2:5], v[188:191], v[220:223], v[2:5]
	v_mfma_f32_16x16x32_bf16 v[10:13], v[176:179], v[216:219], v[10:13]
	v_mfma_f32_16x16x32_bf16 v[10:13], v[180:183], v[220:223], v[10:13]
	s_barrier
	s_setprio 0
	s_add_i32 s45, s45, 2
	s_add_u32 s6, s6, 0x100
	s_addc_u32 s7, s7, 0
	s_add_u32 s33, s33, 0x100
	s_addc_u32 s44, s44, 0
	s_cmp_gt_u32 s45, 61
	s_cbranch_scc0 .LBB0_143
	s_and_b64 vcc, exec, s[20:21]
	s_cbranch_vccz .LBB0_148
	s_barrier
	v_lshl_add_u32 v156, s0, 8, v163
	s_cmp_lt_i32 s54, 40
	s_mov_b64 s[0:1], -1
	s_cbranch_scc1 .LBB0_149

; #define PG8_STAGE(bufoff, gbase, voff) do { _Pragma("unroll") for (int _i = 0; _i < 2; ++_i) \
;         __builtin_amdgcn_global_load_lds((const unsigned*)((const char*)(gbase) + (voff)[_i]), (PG8_LAS unsigned*)(lds + (bufoff) + ldsw + _i * 8192), 16, 0, 0); } while (0)
; #define PG8_LDA(dst, b, h) do { _Pragma("unroll") for (int m = 0; m < 4; ++m) _Pragma("unroll") for (int k = 0; k < 2; ++k) dst[m][k] = *(const PG8_LAS bf16x8*)(lds + PG8_SA(b, h) + aoff + m * 2048 + k * 1024); } while (0)
; #define PG8_LDB(dst, b, h) do { _Pragma("unroll") for (int n = 0; n < 2; ++n) _Pragma("unroll") for (int k = 0; k < 2; ++k) dst[n][k] = *(const PG8_LAS bf16x8*)(lds + PG8_SB(b, h) + boff + n * 2048 + k * 1024); } while (0)
; #define PG8_MMA(ai, bj, At, Bt) do { __builtin_amdgcn_s_setprio(3); _Pragma("unroll") for (int m = 0; m < 4; ++m) _Pragma("unroll") for (int n = 0; n < 2; ++n) _Pragma("unroll") for (int k = 0; k < 2; ++k) \
;         acc[ai][bj][m][n] = __builtin_amdgcn_mfma_f32_16x16x32_bf16(Bt[n][k], At[m][k], acc[ai][bj][m][n], 0, 0, 0); __builtin_amdgcn_s_setprio(0); } while (0)
; #define PG8_WAIT_V(n) asm volatile("s_waitcnt vmcnt(" #n ")" ::: "memory")
; template <class Epi, class Sched, bool ALIGN_EPI = false, bool SP2 = false>
; __device__ __forceinline__ void gemm_phase(PG8_LAS unsigned char* lds, const Gemm g, const Sched& S, const Epi& E) {
;     ...
;             const bool last = (t == nt - 2);
;             const char* a1 = cA + (size_t)(t + 1) * kstep;
;             const char* a2 = last ? nA : cA + (size_t)(t + 2) * kstep; const char* b2 = last ? nB : cB + (size_t)(t + 2) * kstep;
;             const char* a3 = a2 + kstep; const char* b3 = b2 + kstep;
;             if (last && has_next) S.a_ready(nxt);
;             if constexpr (Epi::MIDK) { if (t == E.midk_step(nt)) E.midk(acc, cur, wr, wc, fr, fq); }
;             if constexpr (SP2) {
;             PG8_LDB(B0, 0, 0); PG8_LDB(B1, 0, 1); PG8_SCHED; PG8_LDA(At, 0, 0); PG8_STAGE(PG8_SA(1, 1), a1 + hstepA, voffA);
;             PG8_WAIT_V(8); PG8_WAIT_L(0); PG8_BAR; PG8_MMA(0, 0, At, B0); PG8_MMA(0, 1, At, B1); PG8_BAR; PG8_SCHED;
;             PG8_LDA(At, 0, 1); PG8_STAGE(PG8_SB(0, 0), b2, voffB); PG8_STAGE(PG8_SB(0, 1), b2 + hstepB, voffB); PG8_STAGE(PG8_SA(0, 0), a2, voffA);
;             PG8_WAIT_V(8); PG8_WAIT_L(0); PG8_BAR; PG8_MMA(1, 0, At, B0); PG8_MMA(1, 1, At, B1); PG8_BAR; PG8_SCHED;
.LBB0_478:
	ds_read_b128 v[130:133], v170
	ds_read_b128 v[134:137], v170 offset:1024
	ds_read_b128 v[138:141], v170 offset:2048
	ds_read_b128 v[142:145], v170 offset:3072
	ds_read_b128 v[164:167], v171
	ds_read_b128 v[174:177], v171 offset:1024
	ds_read_b128 v[178:181], v171 offset:2048
	ds_read_b128 v[182:185], v171 offset:3072
	s_add_u32 s36, s6, 0xfff80080
	s_addc_u32 s37, s7, -1
	s_cmp_eq_u32 s79, 4
	s_cselect_b32 s59, s27, s37
	s_cselect_b32 s58, s26, s36
	s_cselect_b32 s37, s23, s78
	s_cselect_b32 s36, s25, s77
	v_lshl_add_u64 v[218:219], s[6:7], 0, v[154:155]
	s_add_i32 m0, s31, 0xc000
	ds_read_b128 v[186:189], v172
	ds_read_b128 v[190:193], v172 offset:1024
	ds_read_b128 v[194:197], v172 offset:2048
	ds_read_b128 v[198:201], v172 offset:3072
	ds_read_b128 v[202:205], v172 offset:4096
	ds_read_b128 v[206:209], v172 offset:5120
	ds_read_b128 v[210:213], v172 offset:6144
	ds_read_b128 v[214:217], v172 offset:7168
	global_load_lds_dwordx4 v[218:219], off
	v_lshl_add_u64 v[218:219], s[6:7], 0, v[156:157]
	s_add_i32 m0, s31, 0xe000
	s_nop 0
	global_load_lds_dwordx4 v[218:219], off
	s_waitcnt vmcnt(8)
	s_waitcnt lgkmcnt(0)
	s_setprio 3
	s_barrier
	v_mfma_f32_16x16x32_bf16 v[126:129], v[130:133], v[186:189], v[126:129]
	v_mfma_f32_16x16x32_bf16 v[126:129], v[134:137], v[190:193], v[126:129]
	v_mfma_f32_16x16x32_bf16 v[122:125], v[138:141], v[186:189], v[122:125]
	v_mfma_f32_16x16x32_bf16 v[122:125], v[142:145], v[190:193], v[122:125]
	v_mfma_f32_16x16x32_bf16 v[114:117], v[138:141], v[194:197], v[114:117]
	v_mfma_f32_16x16x32_bf16 v[114:117], v[142:145], v[198:201], v[114:117]
	v_mfma_f32_16x16x32_bf16 v[118:121], v[130:133], v[194:197], v[118:121]
	v_mfma_f32_16x16x32_bf16 v[118:121], v[134:137], v[198:201], v[118:121]
	v_mfma_f32_16x16x32_bf16 v[110:113], v[130:133], v[202:205], v[110:113]
	v_mfma_f32_16x16x32_bf16 v[110:113], v[134:137], v[206:209], v[110:113]
	v_mfma_f32_16x16x32_bf16 v[102:105], v[138:141], v[202:205], v[102:105]
	v_mfma_f32_16x16x32_bf16 v[102:105], v[142:145], v[206:209], v[102:105]
	v_mfma_f32_16x16x32_bf16 v[74:77], v[138:141], v[210:213], v[74:77]
	v_mfma_f32_16x16x32_bf16 v[74:77], v[142:145], v[214:217], v[74:77]
	v_mfma_f32_16x16x32_bf16 v[78:81], v[130:133], v[210:213], v[78:81]
	v_mfma_f32_16x16x32_bf16 v[78:81], v[134:137], v[214:217], v[78:81]
	v_mfma_f32_16x16x32_bf16 v[106:109], v[164:167], v[186:189], v[106:109]
	v_mfma_f32_16x16x32_bf16 v[106:109], v[174:177], v[190:193], v[106:109]
	v_mfma_f32_16x16x32_bf16 v[98:101], v[178:181], v[186:189], v[98:101]
	v_mfma_f32_16x16x32_bf16 v[98:101], v[182:185], v[190:193], v[98:101]
	v_mfma_f32_16x16x32_bf16 v[90:93], v[178:181], v[194:197], v[90:93]
	v_mfma_f32_16x16x32_bf16 v[90:93], v[182:185], v[198:201], v[90:93]
	v_mfma_f32_16x16x32_bf16 v[94:97], v[164:167], v[194:197], v[94:97]
	v_mfma_f32_16x16x32_bf16 v[94:97], v[174:177], v[198:201], v[94:97]
	v_mfma_f32_16x16x32_bf16 v[86:89], v[164:167], v[202:205], v[86:89]
	v_mfma_f32_16x16x32_bf16 v[86:89], v[174:177], v[206:209], v[86:89]
	v_mfma_f32_16x16x32_bf16 v[82:85], v[178:181], v[202:205], v[82:85]
	v_mfma_f32_16x16x32_bf16 v[82:85], v[182:185], v[206:209], v[82:85]
	v_mfma_f32_16x16x32_bf16 v[66:69], v[178:181], v[210:213], v[66:69]
	v_mfma_f32_16x16x32_bf16 v[66:69], v[182:185], v[214:217], v[66:69]
	v_mfma_f32_16x16x32_bf16 v[70:73], v[164:167], v[210:213], v[70:73]
	v_mfma_f32_16x16x32_bf16 v[70:73], v[174:177], v[214:217], v[70:73]
	s_barrier
	s_setprio 0
	s_add_i32 s83, s72, s44
	v_lshl_add_u64 v[218:219], s[36:37], 0, v[148:149]
	s_mov_b32 m0, s83
	ds_read_b128 v[186:189], v172 offset:16384
	ds_read_b128 v[190:193], v172 offset:17408
	ds_read_b128 v[194:197], v172 offset:18432
	ds_read_b128 v[198:201], v172 offset:19456
	ds_read_b128 v[202:205], v172 offset:20480
	ds_read_b128 v[206:209], v172 offset:21504
	ds_read_b128 v[210:213], v172 offset:22528
	ds_read_b128 v[214:217], v172 offset:23552
	global_load_lds_dwordx4 v[218:219], off
	s_add_i32 m0, s83, 0x2000
	s_add_u32 s84, s36, 0x20000
	v_lshl_add_u64 v[220:221], s[36:37], 0, v[152:153]
	s_addc_u32 s85, s37, 0
	s_add_i32 s83, s73, s44
	global_load_lds_dwordx4 v[220:221], off
	v_lshl_add_u64 v[222:223], s[84:85], 0, v[148:149]
	s_mov_b32 m0, s83
	v_lshl_add_u64 v[224:225], s[58:59], 0, v[150:151]
	global_load_lds_dwordx4 v[222:223], off
	v_lshl_add_u64 v[222:223], s[84:85], 0, v[152:153]
	s_add_i32 m0, s83, 0x2000
	s_nop 0
	global_load_lds_dwordx4 v[222:223], off
	v_lshl_add_u64 v[222:223], s[58:59], 0, v[146:147]
	s_mov_b32 m0, s31
	s_nop 0
	global_load_lds_dwordx4 v[222:223], off
	s_mov_b32 m0, s45
	s_nop 0
	global_load_lds_dwordx4 v[224:225], off
	s_waitcnt vmcnt(8)
	s_waitcnt lgkmcnt(0)
	s_setprio 3
	s_barrier
; #define PG8_STAGE(bufoff, gbase, voff) do { _Pragma("unroll") for (int _i = 0; _i < 2; ++_i) \
;         __builtin_amdgcn_global_load_lds((const unsigned*)((const char*)(gbase) + (voff)[_i]), (PG8_LAS unsigned*)(lds + (bufoff) + ldsw + _i * 8192), 16, 0, 0); } while (0)
; #define PG8_LDA(dst, b, h) do { _Pragma("unroll") for (int m = 0; m < 4; ++m) _Pragma("unroll") for (int k = 0; k < 2; ++k) dst[m][k] = *(const PG8_LAS bf16x8*)(lds + PG8_SA(b, h) + aoff + m * 2048 + k * 1024); } while (0)
; #define PG8_LDB(dst, b, h) do { _Pragma("unroll") for (int n = 0; n < 2; ++n) _Pragma("unroll") for (int k = 0; k < 2; ++k) dst[n][k] = *(const PG8_LAS bf16x8*)(lds + PG8_SB(b, h) + boff + n * 2048 + k * 1024); } while (0)
; #define PG8_MMA(ai, bj, At, Bt) do { __builtin_amdgcn_s_setprio(3); _Pragma("unroll") for (int m = 0; m < 4; ++m) _Pragma("unroll") for (int n = 0; n < 2; ++n) _Pragma("unroll") for (int k = 0; k < 2; ++k) \
;         acc[ai][bj][m][n] = __builtin_amdgcn_mfma_f32_16x16x32_bf16(Bt[n][k], At[m][k], acc[ai][bj][m][n], 0, 0, 0); __builtin_amdgcn_s_setprio(0); } while (0)
; #define PG8_WAIT_V(n) asm volatile("s_waitcnt vmcnt(" #n ")" ::: "memory")
; #define PG8_WAIT_L(n) asm volatile("s_waitcnt lgkmcnt(" #n ")" ::: "memory")
; #define PG8_BAR __builtin_amdgcn_s_barrier()
; #define PG8_SCHED __builtin_amdgcn_sched_barrier(0)
; template <class Epi, class Sched, bool ALIGN_EPI = false, bool SP2 = false>
; __device__ __forceinline__ void gemm_phase(PG8_LAS unsigned char* lds, const Gemm g, const Sched& S, const Epi& E) {
;     ...
;             PG8_WAIT_V(8); PG8_WAIT_L(0); PG8_BAR; PG8_MMA(1, 0, At, B0); PG8_MMA(1, 1, At, B1); PG8_BAR; PG8_SCHED;
;             PG8_LDB(B0, 1, 0); PG8_LDB(B1, 1, 1); PG8_SCHED; PG8_LDA(At, 1, 0); PG8_STAGE(PG8_SA(0, 1), a2 + hstepA, voffA);
;             PG8_WAIT_V(8); PG8_WAIT_L(0); PG8_BAR; PG8_MMA(0, 0, At, B0); PG8_MMA(0, 1, At, B1); PG8_BAR; PG8_SCHED;
	v_mfma_f32_16x16x32_bf16 v[62:65], v[130:133], v[186:189], v[62:65]
	v_mfma_f32_16x16x32_bf16 v[62:65], v[134:137], v[190:193], v[62:65]
	v_mfma_f32_16x16x32_bf16 v[58:61], v[138:141], v[186:189], v[58:61]
	v_mfma_f32_16x16x32_bf16 v[58:61], v[142:145], v[190:193], v[58:61]
	v_mfma_f32_16x16x32_bf16 v[46:49], v[138:141], v[194:197], v[46:49]
	v_mfma_f32_16x16x32_bf16 v[46:49], v[142:145], v[198:201], v[46:49]
	v_mfma_f32_16x16x32_bf16 v[54:57], v[130:133], v[194:197], v[54:57]
	v_mfma_f32_16x16x32_bf16 v[54:57], v[134:137], v[198:201], v[54:57]
	v_mfma_f32_16x16x32_bf16 v[38:41], v[130:133], v[202:205], v[38:41]
	v_mfma_f32_16x16x32_bf16 v[38:41], v[134:137], v[206:209], v[38:41]
	v_mfma_f32_16x16x32_bf16 v[30:33], v[138:141], v[202:205], v[30:33]
	v_mfma_f32_16x16x32_bf16 v[30:33], v[142:145], v[206:209], v[30:33]
	v_mfma_f32_16x16x32_bf16 v[14:17], v[138:141], v[210:213], v[14:17]
	v_mfma_f32_16x16x32_bf16 v[14:17], v[142:145], v[214:217], v[14:17]
	v_mfma_f32_16x16x32_bf16 v[22:25], v[130:133], v[210:213], v[22:25]
	v_mfma_f32_16x16x32_bf16 v[22:25], v[134:137], v[214:217], v[22:25]
	v_mfma_f32_16x16x32_bf16 v[50:53], v[164:167], v[186:189], v[50:53]
	v_mfma_f32_16x16x32_bf16 v[50:53], v[174:177], v[190:193], v[50:53]
	v_mfma_f32_16x16x32_bf16 v[42:45], v[178:181], v[186:189], v[42:45]
	v_mfma_f32_16x16x32_bf16 v[42:45], v[182:185], v[190:193], v[42:45]
	v_mfma_f32_16x16x32_bf16 v[26:29], v[178:181], v[194:197], v[26:29]
	v_mfma_f32_16x16x32_bf16 v[26:29], v[182:185], v[198:201], v[26:29]
	v_mfma_f32_16x16x32_bf16 v[34:37], v[164:167], v[194:197], v[34:37]
	v_mfma_f32_16x16x32_bf16 v[34:37], v[174:177], v[198:201], v[34:37]
	v_mfma_f32_16x16x32_bf16 v[18:21], v[164:167], v[202:205], v[18:21]
	v_mfma_f32_16x16x32_bf16 v[18:21], v[174:177], v[206:209], v[18:21]
	v_mfma_f32_16x16x32_bf16 v[10:13], v[178:181], v[202:205], v[10:13]
	v_mfma_f32_16x16x32_bf16 v[10:13], v[182:185], v[206:209], v[10:13]
	v_mfma_f32_16x16x32_bf16 v[2:5], v[178:181], v[210:213], v[2:5]
	v_mfma_f32_16x16x32_bf16 v[2:5], v[182:185], v[214:217], v[2:5]
	v_mfma_f32_16x16x32_bf16 v[6:9], v[164:167], v[210:213], v[6:9]
	v_mfma_f32_16x16x32_bf16 v[6:9], v[174:177], v[214:217], v[6:9]
	s_barrier
	s_setprio 0
	s_add_i32 s83, 0, 0x18000
	s_add_i32 s84, 0, 0x1c000
	v_add_u32_e32 v142, s83, v168
	v_add_u32_e32 v173, s84, v168
	ds_read_b128 v[130:133], v142
	ds_read_b128 v[134:137], v142 offset:1024
	ds_read_b128 v[138:141], v142 offset:2048
	ds_read_b128 v[142:145], v142 offset:3072
	ds_read_b128 v[164:167], v173
	ds_read_b128 v[174:177], v173 offset:1024
	ds_read_b128 v[178:181], v173 offset:2048
	ds_read_b128 v[182:185], v173 offset:3072
	s_add_u32 s58, s58, 0x80000
	s_addc_u32 s59, s59, 0
	s_mov_b32 m0, s54
	v_lshl_add_u64 v[226:227], s[58:59], 0, v[146:147]
	ds_read_b128 v[186:189], v172 offset:32768
	ds_read_b128 v[190:193], v172 offset:33792
	ds_read_b128 v[194:197], v172 offset:34816
	ds_read_b128 v[198:201], v172 offset:35840
	ds_read_b128 v[202:205], v172 offset:36864
	ds_read_b128 v[206:209], v172 offset:37888
	ds_read_b128 v[210:213], v172 offset:38912
	ds_read_b128 v[214:217], v172 offset:39936
	global_load_lds_dwordx4 v[226:227], off
	v_lshl_add_u64 v[226:227], s[58:59], 0, v[150:151]
	s_mov_b32 m0, s55
	s_nop 0
	global_load_lds_dwordx4 v[226:227], off
	s_waitcnt vmcnt(8)
	s_waitcnt lgkmcnt(0)
	s_setprio 3
	s_barrier
	v_mfma_f32_16x16x32_bf16 v[126:129], v[130:133], v[186:189], v[126:129]
	v_mfma_f32_16x16x32_bf16 v[126:129], v[134:137], v[190:193], v[126:129]
	v_mfma_f32_16x16x32_bf16 v[122:125], v[138:141], v[186:189], v[122:125]
	v_mfma_f32_16x16x32_bf16 v[122:125], v[142:145], v[190:193], v[122:125]
	v_mfma_f32_16x16x32_bf16 v[114:117], v[138:141], v[194:197], v[114:117]
	v_mfma_f32_16x16x32_bf16 v[114:117], v[142:145], v[198:201], v[114:117]
	v_mfma_f32_16x16x32_bf16 v[118:121], v[130:133], v[194:197], v[118:121]
	v_mfma_f32_16x16x32_bf16 v[118:121], v[134:137], v[198:201], v[118:121]
	v_mfma_f32_16x16x32_bf16 v[110:113], v[130:133], v[202:205], v[110:113]
	v_mfma_f32_16x16x32_bf16 v[110:113], v[134:137], v[206:209], v[110:113]
	v_mfma_f32_16x16x32_bf16 v[102:105], v[138:141], v[202:205], v[102:105]
	v_mfma_f32_16x16x32_bf16 v[102:105], v[142:145], v[206:209], v[102:105]
	v_mfma_f32_16x16x32_bf16 v[74:77], v[138:141], v[210:213], v[74:77]
	v_mfma_f32_16x16x32_bf16 v[74:77], v[142:145], v[214:217], v[74:77]
	v_mfma_f32_16x16x32_bf16 v[78:81], v[130:133], v[210:213], v[78:81]
	v_mfma_f32_16x16x32_bf16 v[78:81], v[134:137], v[214:217], v[78:81]
	v_mfma_f32_16x16x32_bf16 v[106:109], v[164:167], v[186:189], v[106:109]
	v_mfma_f32_16x16x32_bf16 v[106:109], v[174:177], v[190:193], v[106:109]
	v_mfma_f32_16x16x32_bf16 v[98:101], v[178:181], v[186:189], v[98:101]
	v_mfma_f32_16x16x32_bf16 v[98:101], v[182:185], v[190:193], v[98:101]
	v_mfma_f32_16x16x32_bf16 v[90:93], v[178:181], v[194:197], v[90:93]
	v_mfma_f32_16x16x32_bf16 v[90:93], v[182:185], v[198:201], v[90:93]
	v_mfma_f32_16x16x32_bf16 v[94:97], v[164:167], v[194:197], v[94:97]
	v_mfma_f32_16x16x32_bf16 v[94:97], v[174:177], v[198:201], v[94:97]
	v_mfma_f32_16x16x32_bf16 v[86:89], v[164:167], v[202:205], v[86:89]
	v_mfma_f32_16x16x32_bf16 v[86:89], v[174:177], v[206:209], v[86:89]
	v_mfma_f32_16x16x32_bf16 v[82:85], v[178:181], v[202:205], v[82:85]
	v_mfma_f32_16x16x32_bf16 v[82:85], v[182:185], v[206:209], v[82:85]
	v_mfma_f32_16x16x32_bf16 v[66:69], v[178:181], v[210:213], v[66:69]
	v_mfma_f32_16x16x32_bf16 v[66:69], v[182:185], v[214:217], v[66:69]
	v_mfma_f32_16x16x32_bf16 v[70:73], v[164:167], v[210:213], v[70:73]
	v_mfma_f32_16x16x32_bf16 v[70:73], v[174:177], v[214:217], v[70:73]
	s_barrier
; #define PG8_STAGE(bufoff, gbase, voff) do { _Pragma("unroll") for (int _i = 0; _i < 2; ++_i) \
;         __builtin_amdgcn_global_load_lds((const unsigned*)((const char*)(gbase) + (voff)[_i]), (PG8_LAS unsigned*)(lds + (bufoff) + ldsw + _i * 8192), 16, 0, 0); } while (0)
; #define PG8_LDA(dst, b, h) do { _Pragma("unroll") for (int m = 0; m < 4; ++m) _Pragma("unroll") for (int k = 0; k < 2; ++k) dst[m][k] = *(const PG8_LAS bf16x8*)(lds + PG8_SA(b, h) + aoff + m * 2048 + k * 1024); } while (0)
; #define PG8_MMA(ai, bj, At, Bt) do { __builtin_amdgcn_s_setprio(3); _Pragma("unroll") for (int m = 0; m < 4; ++m) _Pragma("unroll") for (int n = 0; n < 2; ++n) _Pragma("unroll") for (int k = 0; k < 2; ++k) \
;         acc[ai][bj][m][n] = __builtin_amdgcn_mfma_f32_16x16x32_bf16(Bt[n][k], At[m][k], acc[ai][bj][m][n], 0, 0, 0); __builtin_amdgcn_s_setprio(0); } while (0)
; #define PG8_WAIT_V(n) asm volatile("s_waitcnt vmcnt(" #n ")" ::: "memory")
; #define PG8_WAIT_L(n) asm volatile("s_waitcnt lgkmcnt(" #n ")" ::: "memory")
; #define PG8_BAR __builtin_amdgcn_s_barrier()
; #define PG8_SCHED __builtin_amdgcn_sched_barrier(0)
; template <class Epi, class Sched, bool ALIGN_EPI = false, bool SP2 = false>
; __device__ __forceinline__ void gemm_phase(PG8_LAS unsigned char* lds, const Gemm g, const Sched& S, const Epi& E) {
;     ...
;             PG8_LDA(At, 1, 1); PG8_STAGE(PG8_SB(1, 0), b3, voffB); PG8_STAGE(PG8_SB(1, 1), b3 + hstepB, voffB); PG8_STAGE(PG8_SA(1, 0), a3, voffA);
;             PG8_WAIT_V(8); PG8_WAIT_L(0); PG8_BAR; PG8_MMA(1, 0, At, B0); PG8_MMA(1, 1, At, B1); PG8_BAR; PG8_SCHED;
	s_setprio 0
	s_add_i32 s58, s83, s44
	v_lshl_add_u64 v[218:219], v[218:219], 0, s[18:19]
	s_mov_b32 m0, s58
	ds_read_b128 v[186:189], v172 offset:49152
	ds_read_b128 v[190:193], v172 offset:50176
	ds_read_b128 v[194:197], v172 offset:51200
	ds_read_b128 v[198:201], v172 offset:52224
	ds_read_b128 v[202:205], v172 offset:53248
	ds_read_b128 v[206:209], v172 offset:54272
	ds_read_b128 v[210:213], v172 offset:55296
	ds_read_b128 v[214:217], v172 offset:56320
	global_load_lds_dwordx4 v[218:219], off
	s_add_i32 m0, s58, 0x2000
	s_add_u32 s36, s36, 0x20080
	v_lshl_add_u64 v[218:219], v[220:221], 0, s[18:19]
	s_addc_u32 s37, s37, 0
	s_add_i32 s58, s84, s44
	global_load_lds_dwordx4 v[218:219], off
	v_lshl_add_u64 v[218:219], s[36:37], 0, v[148:149]
	s_mov_b32 m0, s58
	s_nop 0
	global_load_lds_dwordx4 v[218:219], off
	v_lshl_add_u64 v[218:219], s[36:37], 0, v[152:153]
	s_add_i32 m0, s58, 0x2000
	s_nop 0
	global_load_lds_dwordx4 v[218:219], off
	v_lshl_add_u64 v[218:219], v[222:223], 0, s[18:19]
	s_mov_b32 m0, s63
	s_nop 0
	global_load_lds_dwordx4 v[218:219], off
	v_lshl_add_u64 v[218:219], v[224:225], 0, s[18:19]
	s_mov_b32 m0, s66
	s_nop 0
	global_load_lds_dwordx4 v[218:219], off
	s_waitcnt vmcnt(8)
	s_waitcnt lgkmcnt(0)
	s_setprio 3
	s_barrier
	v_mfma_f32_16x16x32_bf16 v[62:65], v[130:133], v[186:189], v[62:65]
	v_mfma_f32_16x16x32_bf16 v[62:65], v[134:137], v[190:193], v[62:65]
	v_mfma_f32_16x16x32_bf16 v[58:61], v[138:141], v[186:189], v[58:61]
	v_mfma_f32_16x16x32_bf16 v[58:61], v[142:145], v[190:193], v[58:61]
	v_mfma_f32_16x16x32_bf16 v[46:49], v[138:141], v[194:197], v[46:49]
	v_mfma_f32_16x16x32_bf16 v[46:49], v[142:145], v[198:201], v[46:49]
	v_mfma_f32_16x16x32_bf16 v[54:57], v[130:133], v[194:197], v[54:57]
	v_mfma_f32_16x16x32_bf16 v[54:57], v[134:137], v[198:201], v[54:57]
	v_mfma_f32_16x16x32_bf16 v[38:41], v[130:133], v[202:205], v[38:41]
	v_mfma_f32_16x16x32_bf16 v[38:41], v[134:137], v[206:209], v[38:41]
	v_mfma_f32_16x16x32_bf16 v[30:33], v[138:141], v[202:205], v[30:33]
	v_mfma_f32_16x16x32_bf16 v[30:33], v[142:145], v[206:209], v[30:33]
	v_mfma_f32_16x16x32_bf16 v[14:17], v[138:141], v[210:213], v[14:17]
	v_mfma_f32_16x16x32_bf16 v[14:17], v[142:145], v[214:217], v[14:17]
	v_mfma_f32_16x16x32_bf16 v[22:25], v[130:133], v[210:213], v[22:25]
	v_mfma_f32_16x16x32_bf16 v[22:25], v[134:137], v[214:217], v[22:25]
	v_mfma_f32_16x16x32_bf16 v[50:53], v[164:167], v[186:189], v[50:53]
	v_mfma_f32_16x16x32_bf16 v[50:53], v[174:177], v[190:193], v[50:53]
	v_mfma_f32_16x16x32_bf16 v[42:45], v[178:181], v[186:189], v[42:45]
	v_mfma_f32_16x16x32_bf16 v[42:45], v[182:185], v[190:193], v[42:45]
	v_mfma_f32_16x16x32_bf16 v[26:29], v[178:181], v[194:197], v[26:29]
	v_mfma_f32_16x16x32_bf16 v[26:29], v[182:185], v[198:201], v[26:29]
	v_mfma_f32_16x16x32_bf16 v[34:37], v[164:167], v[194:197], v[34:37]
	v_mfma_f32_16x16x32_bf16 v[34:37], v[174:177], v[198:201], v[34:37]
	v_mfma_f32_16x16x32_bf16 v[18:21], v[164:167], v[202:205], v[18:21]
	v_mfma_f32_16x16x32_bf16 v[18:21], v[174:177], v[206:209], v[18:21]
	v_mfma_f32_16x16x32_bf16 v[10:13], v[178:181], v[202:205], v[10:13]
	v_mfma_f32_16x16x32_bf16 v[10:13], v[182:185], v[206:209], v[10:13]
	v_mfma_f32_16x16x32_bf16 v[2:5], v[178:181], v[210:213], v[2:5]
	v_mfma_f32_16x16x32_bf16 v[2:5], v[182:185], v[214:217], v[2:5]
	v_mfma_f32_16x16x32_bf16 v[6:9], v[164:167], v[210:213], v[6:9]
	v_mfma_f32_16x16x32_bf16 v[6:9], v[174:177], v[214:217], v[6:9]
	s_barrier
	s_setprio 0
	s_add_i32 s79, s79, 2
	s_add_u32 s6, s6, 0x100
	s_addc_u32 s7, s7, 0
	s_add_u32 s77, s77, 0x100
	s_addc_u32 s78, s78, 0
	s_cmp_gt_u32 s79, 5
	s_cbranch_scc0 .LBB0_478
	s_and_b64 vcc, exec, s[20:21]
	s_cbranch_vccz .LBB0_481
	s_barrier

; #define PG8_STAGE(bufoff, gbase, voff) do { _Pragma("unroll") for (int _i = 0; _i < 2; ++_i) \
;         __builtin_amdgcn_global_load_lds((const unsigned*)((const char*)(gbase) + (voff)[_i]), (PG8_LAS unsigned*)(lds + (bufoff) + ldsw + _i * 8192), 16, 0, 0); } while (0)
; #define PG8_LDA(dst, b, h) do { _Pragma("unroll") for (int m = 0; m < 4; ++m) _Pragma("unroll") for (int k = 0; k < 2; ++k) dst[m][k] = *(const PG8_LAS bf16x8*)(lds + PG8_SA(b, h) + aoff + m * 2048 + k * 1024); } while (0)
; #define PG8_LDB(dst, b, h) do { _Pragma("unroll") for (int n = 0; n < 2; ++n) _Pragma("unroll") for (int k = 0; k < 2; ++k) dst[n][k] = *(const PG8_LAS bf16x8*)(lds + PG8_SB(b, h) + boff + n * 2048 + k * 1024); } while (0)
; #define PG8_MMA(ai, bj, At, Bt) do { __builtin_amdgcn_s_setprio(3); _Pragma("unroll") for (int m = 0; m < 4; ++m) _Pragma("unroll") for (int n = 0; n < 2; ++n) _Pragma("unroll") for (int k = 0; k < 2; ++k) \
;         acc[ai][bj][m][n] = __builtin_amdgcn_mfma_f32_16x16x32_bf16(Bt[n][k], At[m][k], acc[ai][bj][m][n], 0, 0, 0); __builtin_amdgcn_s_setprio(0); } while (0)
; #define PG8_WAIT_V(n) asm volatile("s_waitcnt vmcnt(" #n ")" ::: "memory")
; template <class Epi, class Sched, bool ALIGN_EPI = false, bool SP2 = false>
; __device__ __forceinline__ void gemm_phase(PG8_LAS unsigned char* lds, const Gemm g, const Sched& S, const Epi& E) {
;     ...
;             const bool last = (t == nt - 2);
;             const char* a1 = cA + (size_t)(t + 1) * kstep;
;             const char* a2 = last ? nA : cA + (size_t)(t + 2) * kstep; const char* b2 = last ? nB : cB + (size_t)(t + 2) * kstep;
;             const char* a3 = a2 + kstep; const char* b3 = b2 + kstep;
;             if (last && has_next) S.a_ready(nxt);
;             if constexpr (Epi::MIDK) { if (t == E.midk_step(nt)) E.midk(acc, cur, wr, wc, fr, fq); }
;             if constexpr (SP2) {
;             PG8_LDB(B0, 0, 0); PG8_LDB(B1, 0, 1); PG8_SCHED; PG8_LDA(At, 0, 0); PG8_STAGE(PG8_SA(1, 1), a1 + hstepA, voffA);
;             PG8_WAIT_V(8); PG8_WAIT_L(0); PG8_BAR; PG8_MMA(0, 0, At, B0); PG8_MMA(0, 1, At, B1); PG8_BAR; PG8_SCHED;
;             PG8_LDA(At, 0, 1); PG8_STAGE(PG8_SB(0, 0), b2, voffB); PG8_STAGE(PG8_SB(0, 1), b2 + hstepB, voffB); PG8_STAGE(PG8_SA(0, 0), a2, voffA);
;             PG8_WAIT_V(8); PG8_WAIT_L(0); PG8_BAR; PG8_MMA(1, 0, At, B0); PG8_MMA(1, 1, At, B1); PG8_BAR; PG8_SCHED;
.LBB0_727:
	v_add_u32_e32 v160, s66, v157
	ds_read_b128 v[130:133], v160
	ds_read_b128 v[164:167], v160 offset:1024
	ds_read_b128 v[168:171], v160 offset:2048
	ds_read_b128 v[172:175], v160 offset:3072
	v_add_u32_e32 v160, s67, v157
	s_add_u32 s0, s28, s30
	ds_read_b128 v[176:179], v160
	ds_read_b128 v[180:183], v160 offset:1024
	ds_read_b128 v[184:187], v160 offset:2048
	ds_read_b128 v[188:191], v160 offset:3072
	s_addc_u32 s1, s29, s31
	s_add_u32 s0, s0, 0x100
	s_addc_u32 s1, s1, 0
	s_add_u32 s84, s79, s30
	s_addc_u32 s85, s81, s31
	s_cmpk_eq_i32 s30, 0x1f00
	s_cselect_b32 s37, s23, s1
	s_cselect_b32 s36, s72, s0
	s_cselect_b32 s1, s75, s85
	s_cselect_b32 s0, s76, s84
	v_lshl_add_u64 v[160:161], v[150:151], 0, s[30:31]
	s_add_i32 m0, s44, 0xc000
	ds_read_b128 v[192:195], v159
	ds_read_b128 v[196:199], v159 offset:1024
	ds_read_b128 v[200:203], v159 offset:2048
	ds_read_b128 v[204:207], v159 offset:3072
	ds_read_b128 v[208:211], v159 offset:4096
	ds_read_b128 v[212:215], v159 offset:5120
	ds_read_b128 v[216:219], v159 offset:6144
	ds_read_b128 v[220:223], v159 offset:7168
	global_load_lds_dwordx4 v[160:161], off
	v_lshl_add_u64 v[160:161], v[152:153], 0, s[30:31]
	s_add_i32 m0, s44, 0xe000
	s_nop 0
	global_load_lds_dwordx4 v[160:161], off
	s_waitcnt vmcnt(8)
	s_waitcnt lgkmcnt(0)
	s_setprio 3
	s_barrier
	v_mfma_f32_16x16x32_bf16 v[126:129], v[130:133], v[192:195], v[126:129]
	v_mfma_f32_16x16x32_bf16 v[126:129], v[164:167], v[196:199], v[126:129]
	v_mfma_f32_16x16x32_bf16 v[122:125], v[168:171], v[192:195], v[122:125]
	v_mfma_f32_16x16x32_bf16 v[122:125], v[172:175], v[196:199], v[122:125]
	v_mfma_f32_16x16x32_bf16 v[106:109], v[168:171], v[200:203], v[106:109]
	v_mfma_f32_16x16x32_bf16 v[106:109], v[172:175], v[204:207], v[106:109]
	v_mfma_f32_16x16x32_bf16 v[110:113], v[130:133], v[200:203], v[110:113]
	v_mfma_f32_16x16x32_bf16 v[110:113], v[164:167], v[204:207], v[110:113]
	v_mfma_f32_16x16x32_bf16 v[94:97], v[130:133], v[208:211], v[94:97]
	v_mfma_f32_16x16x32_bf16 v[94:97], v[164:167], v[212:215], v[94:97]
	v_mfma_f32_16x16x32_bf16 v[90:93], v[168:171], v[208:211], v[90:93]
	v_mfma_f32_16x16x32_bf16 v[90:93], v[172:175], v[212:215], v[90:93]
	v_mfma_f32_16x16x32_bf16 v[74:77], v[168:171], v[216:219], v[74:77]
	v_mfma_f32_16x16x32_bf16 v[74:77], v[172:175], v[220:223], v[74:77]
	v_mfma_f32_16x16x32_bf16 v[78:81], v[130:133], v[216:219], v[78:81]
	v_mfma_f32_16x16x32_bf16 v[78:81], v[164:167], v[220:223], v[78:81]
	v_mfma_f32_16x16x32_bf16 v[118:121], v[176:179], v[192:195], v[118:121]
	v_mfma_f32_16x16x32_bf16 v[118:121], v[180:183], v[196:199], v[118:121]
	v_mfma_f32_16x16x32_bf16 v[114:117], v[184:187], v[192:195], v[114:117]
	v_mfma_f32_16x16x32_bf16 v[114:117], v[188:191], v[196:199], v[114:117]
	v_mfma_f32_16x16x32_bf16 v[98:101], v[184:187], v[200:203], v[98:101]
	v_mfma_f32_16x16x32_bf16 v[98:101], v[188:191], v[204:207], v[98:101]
	v_mfma_f32_16x16x32_bf16 v[102:105], v[176:179], v[200:203], v[102:105]
	v_mfma_f32_16x16x32_bf16 v[102:105], v[180:183], v[204:207], v[102:105]
	v_mfma_f32_16x16x32_bf16 v[86:89], v[176:179], v[208:211], v[86:89]
	v_mfma_f32_16x16x32_bf16 v[86:89], v[180:183], v[212:215], v[86:89]
	v_mfma_f32_16x16x32_bf16 v[82:85], v[184:187], v[208:211], v[82:85]
	v_mfma_f32_16x16x32_bf16 v[82:85], v[188:191], v[212:215], v[82:85]
	v_mfma_f32_16x16x32_bf16 v[66:69], v[184:187], v[216:219], v[66:69]
	v_mfma_f32_16x16x32_bf16 v[66:69], v[188:191], v[220:223], v[66:69]
	v_mfma_f32_16x16x32_bf16 v[70:73], v[176:179], v[216:219], v[70:73]
	v_mfma_f32_16x16x32_bf16 v[70:73], v[180:183], v[220:223], v[70:73]
	s_barrier
	s_setprio 0
	s_add_i32 s84, s66, s33
	v_lshl_add_u64 v[160:161], s[0:1], 0, v[136:137]
	s_mov_b32 m0, s84
	ds_read_b128 v[192:195], v159 offset:16384
	ds_read_b128 v[196:199], v159 offset:17408
	ds_read_b128 v[200:203], v159 offset:18432
	ds_read_b128 v[204:207], v159 offset:19456
	ds_read_b128 v[208:211], v159 offset:20480
	ds_read_b128 v[212:215], v159 offset:21504
	ds_read_b128 v[216:219], v159 offset:22528
	ds_read_b128 v[220:223], v159 offset:23552
	global_load_lds_dwordx4 v[160:161], off
	s_add_i32 m0, s84, 0x2000
	s_add_u32 s84, s0, 0x100000
	v_lshl_add_u64 v[224:225], s[0:1], 0, v[140:141]
	s_addc_u32 s85, s1, 0
	s_add_i32 s86, s67, s33
	global_load_lds_dwordx4 v[224:225], off
	v_lshl_add_u64 v[226:227], s[84:85], 0, v[136:137]
	s_mov_b32 m0, s86
	v_lshl_add_u64 v[228:229], s[36:37], 0, v[138:139]
	global_load_lds_dwordx4 v[226:227], off
	v_lshl_add_u64 v[226:227], s[84:85], 0, v[140:141]
	s_add_i32 m0, s86, 0x2000
	s_nop 0
	global_load_lds_dwordx4 v[226:227], off
	v_lshl_add_u64 v[226:227], s[36:37], 0, v[134:135]
	s_mov_b32 m0, s44
	s_nop 0
	global_load_lds_dwordx4 v[226:227], off
	s_mov_b32 m0, s45
	s_nop 0
	global_load_lds_dwordx4 v[228:229], off
	s_waitcnt vmcnt(8)
	s_waitcnt lgkmcnt(0)
	s_setprio 3
	s_barrier
; #define PG8_STAGE(bufoff, gbase, voff) do { _Pragma("unroll") for (int _i = 0; _i < 2; ++_i) \
;         __builtin_amdgcn_global_load_lds((const unsigned*)((const char*)(gbase) + (voff)[_i]), (PG8_LAS unsigned*)(lds + (bufoff) + ldsw + _i * 8192), 16, 0, 0); } while (0)
; #define PG8_LDA(dst, b, h) do { _Pragma("unroll") for (int m = 0; m < 4; ++m) _Pragma("unroll") for (int k = 0; k < 2; ++k) dst[m][k] = *(const PG8_LAS bf16x8*)(lds + PG8_SA(b, h) + aoff + m * 2048 + k * 1024); } while (0)
; #define PG8_LDB(dst, b, h) do { _Pragma("unroll") for (int n = 0; n < 2; ++n) _Pragma("unroll") for (int k = 0; k < 2; ++k) dst[n][k] = *(const PG8_LAS bf16x8*)(lds + PG8_SB(b, h) + boff + n * 2048 + k * 1024); } while (0)
; #define PG8_MMA(ai, bj, At, Bt) do { __builtin_amdgcn_s_setprio(3); _Pragma("unroll") for (int m = 0; m < 4; ++m) _Pragma("unroll") for (int n = 0; n < 2; ++n) _Pragma("unroll") for (int k = 0; k < 2; ++k) \
;         acc[ai][bj][m][n] = __builtin_amdgcn_mfma_f32_16x16x32_bf16(Bt[n][k], At[m][k], acc[ai][bj][m][n], 0, 0, 0); __builtin_amdgcn_s_setprio(0); } while (0)
; #define PG8_WAIT_V(n) asm volatile("s_waitcnt vmcnt(" #n ")" ::: "memory")
; #define PG8_WAIT_L(n) asm volatile("s_waitcnt lgkmcnt(" #n ")" ::: "memory")
; #define PG8_BAR __builtin_amdgcn_s_barrier()
; #define PG8_SCHED __builtin_amdgcn_sched_barrier(0)
; template <class Epi, class Sched, bool ALIGN_EPI = false, bool SP2 = false>
; __device__ __forceinline__ void gemm_phase(PG8_LAS unsigned char* lds, const Gemm g, const Sched& S, const Epi& E) {
;     ...
;             PG8_WAIT_V(8); PG8_WAIT_L(0); PG8_BAR; PG8_MMA(1, 0, At, B0); PG8_MMA(1, 1, At, B1); PG8_BAR; PG8_SCHED;
;             PG8_LDB(B0, 1, 0); PG8_LDB(B1, 1, 1); PG8_SCHED; PG8_LDA(At, 1, 0); PG8_STAGE(PG8_SA(0, 1), a2 + hstepA, voffA);
;             PG8_WAIT_V(8); PG8_WAIT_L(0); PG8_BAR; PG8_MMA(0, 0, At, B0); PG8_MMA(0, 1, At, B1); PG8_BAR; PG8_SCHED;
	v_mfma_f32_16x16x32_bf16 v[62:65], v[130:133], v[192:195], v[62:65]
	v_mfma_f32_16x16x32_bf16 v[62:65], v[164:167], v[196:199], v[62:65]
	v_mfma_f32_16x16x32_bf16 v[58:61], v[168:171], v[192:195], v[58:61]
	v_mfma_f32_16x16x32_bf16 v[58:61], v[172:175], v[196:199], v[58:61]
	v_mfma_f32_16x16x32_bf16 v[42:45], v[168:171], v[200:203], v[42:45]
	v_mfma_f32_16x16x32_bf16 v[42:45], v[172:175], v[204:207], v[42:45]
	v_mfma_f32_16x16x32_bf16 v[46:49], v[130:133], v[200:203], v[46:49]
	v_mfma_f32_16x16x32_bf16 v[46:49], v[164:167], v[204:207], v[46:49]
	v_mfma_f32_16x16x32_bf16 v[30:33], v[130:133], v[208:211], v[30:33]
	v_mfma_f32_16x16x32_bf16 v[30:33], v[164:167], v[212:215], v[30:33]
	v_mfma_f32_16x16x32_bf16 v[26:29], v[168:171], v[208:211], v[26:29]
	v_mfma_f32_16x16x32_bf16 v[26:29], v[172:175], v[212:215], v[26:29]
	v_mfma_f32_16x16x32_bf16 v[10:13], v[168:171], v[216:219], v[10:13]
	v_mfma_f32_16x16x32_bf16 v[10:13], v[172:175], v[220:223], v[10:13]
	v_mfma_f32_16x16x32_bf16 v[14:17], v[130:133], v[216:219], v[14:17]
	v_mfma_f32_16x16x32_bf16 v[14:17], v[164:167], v[220:223], v[14:17]
	v_mfma_f32_16x16x32_bf16 v[54:57], v[176:179], v[192:195], v[54:57]
	v_mfma_f32_16x16x32_bf16 v[54:57], v[180:183], v[196:199], v[54:57]
	v_mfma_f32_16x16x32_bf16 v[50:53], v[184:187], v[192:195], v[50:53]
	v_mfma_f32_16x16x32_bf16 v[50:53], v[188:191], v[196:199], v[50:53]
	v_mfma_f32_16x16x32_bf16 v[34:37], v[184:187], v[200:203], v[34:37]
	v_mfma_f32_16x16x32_bf16 v[34:37], v[188:191], v[204:207], v[34:37]
	v_mfma_f32_16x16x32_bf16 v[38:41], v[176:179], v[200:203], v[38:41]
	v_mfma_f32_16x16x32_bf16 v[38:41], v[180:183], v[204:207], v[38:41]
	v_mfma_f32_16x16x32_bf16 v[22:25], v[176:179], v[208:211], v[22:25]
	v_mfma_f32_16x16x32_bf16 v[22:25], v[180:183], v[212:215], v[22:25]
	v_mfma_f32_16x16x32_bf16 v[18:21], v[184:187], v[208:211], v[18:21]
	v_mfma_f32_16x16x32_bf16 v[18:21], v[188:191], v[212:215], v[18:21]
	v_mfma_f32_16x16x32_bf16 v[2:5], v[184:187], v[216:219], v[2:5]
	v_mfma_f32_16x16x32_bf16 v[2:5], v[188:191], v[220:223], v[2:5]
	v_mfma_f32_16x16x32_bf16 v[6:9], v[176:179], v[216:219], v[6:9]
	v_mfma_f32_16x16x32_bf16 v[6:9], v[180:183], v[220:223], v[6:9]
	s_barrier
	s_setprio 0
	s_add_i32 s84, 0, 0x18000
	v_add_u32_e32 v163, s84, v157
	s_add_i32 s85, 0, 0x1c000
	ds_read_b128 v[130:133], v163
	ds_read_b128 v[164:167], v163 offset:1024
	ds_read_b128 v[168:171], v163 offset:2048
	ds_read_b128 v[172:175], v163 offset:3072
	v_add_u32_e32 v163, s85, v157
	ds_read_b128 v[176:179], v163
	ds_read_b128 v[180:183], v163 offset:1024
	ds_read_b128 v[184:187], v163 offset:2048
	ds_read_b128 v[188:191], v163 offset:3072
	s_add_u32 s36, s36, 0x100000
	s_addc_u32 s37, s37, 0
	s_mov_b32 m0, s54
	v_lshl_add_u64 v[230:231], s[36:37], 0, v[134:135]
	ds_read_b128 v[192:195], v159 offset:32768
	ds_read_b128 v[196:199], v159 offset:33792
	ds_read_b128 v[200:203], v159 offset:34816
	ds_read_b128 v[204:207], v159 offset:35840
	ds_read_b128 v[208:211], v159 offset:36864
	ds_read_b128 v[212:215], v159 offset:37888
	ds_read_b128 v[216:219], v159 offset:38912
	ds_read_b128 v[220:223], v159 offset:39936
	global_load_lds_dwordx4 v[230:231], off
	v_lshl_add_u64 v[230:231], s[36:37], 0, v[138:139]
	s_mov_b32 m0, s55
	s_nop 0
	global_load_lds_dwordx4 v[230:231], off
	s_waitcnt vmcnt(8)
	s_waitcnt lgkmcnt(0)
	s_setprio 3
	s_barrier
	v_mfma_f32_16x16x32_bf16 v[126:129], v[130:133], v[192:195], v[126:129]
	v_mfma_f32_16x16x32_bf16 v[126:129], v[164:167], v[196:199], v[126:129]
	v_mfma_f32_16x16x32_bf16 v[122:125], v[168:171], v[192:195], v[122:125]
	v_mfma_f32_16x16x32_bf16 v[122:125], v[172:175], v[196:199], v[122:125]
	v_mfma_f32_16x16x32_bf16 v[106:109], v[168:171], v[200:203], v[106:109]
	v_mfma_f32_16x16x32_bf16 v[106:109], v[172:175], v[204:207], v[106:109]
	v_mfma_f32_16x16x32_bf16 v[110:113], v[130:133], v[200:203], v[110:113]
	v_mfma_f32_16x16x32_bf16 v[110:113], v[164:167], v[204:207], v[110:113]
	v_mfma_f32_16x16x32_bf16 v[94:97], v[130:133], v[208:211], v[94:97]
	v_mfma_f32_16x16x32_bf16 v[94:97], v[164:167], v[212:215], v[94:97]
	v_mfma_f32_16x16x32_bf16 v[90:93], v[168:171], v[208:211], v[90:93]
	v_mfma_f32_16x16x32_bf16 v[90:93], v[172:175], v[212:215], v[90:93]
	v_mfma_f32_16x16x32_bf16 v[74:77], v[168:171], v[216:219], v[74:77]
	v_mfma_f32_16x16x32_bf16 v[74:77], v[172:175], v[220:223], v[74:77]
	v_mfma_f32_16x16x32_bf16 v[78:81], v[130:133], v[216:219], v[78:81]
	v_mfma_f32_16x16x32_bf16 v[78:81], v[164:167], v[220:223], v[78:81]
	v_mfma_f32_16x16x32_bf16 v[118:121], v[176:179], v[192:195], v[118:121]
	v_mfma_f32_16x16x32_bf16 v[118:121], v[180:183], v[196:199], v[118:121]
	v_mfma_f32_16x16x32_bf16 v[114:117], v[184:187], v[192:195], v[114:117]
	v_mfma_f32_16x16x32_bf16 v[114:117], v[188:191], v[196:199], v[114:117]
	v_mfma_f32_16x16x32_bf16 v[98:101], v[184:187], v[200:203], v[98:101]
	v_mfma_f32_16x16x32_bf16 v[98:101], v[188:191], v[204:207], v[98:101]
	v_mfma_f32_16x16x32_bf16 v[102:105], v[176:179], v[200:203], v[102:105]
	v_mfma_f32_16x16x32_bf16 v[102:105], v[180:183], v[204:207], v[102:105]
	v_mfma_f32_16x16x32_bf16 v[86:89], v[176:179], v[208:211], v[86:89]
	v_mfma_f32_16x16x32_bf16 v[86:89], v[180:183], v[212:215], v[86:89]
	v_mfma_f32_16x16x32_bf16 v[82:85], v[184:187], v[208:211], v[82:85]
	v_mfma_f32_16x16x32_bf16 v[82:85], v[188:191], v[212:215], v[82:85]
	v_mfma_f32_16x16x32_bf16 v[66:69], v[184:187], v[216:219], v[66:69]
	v_mfma_f32_16x16x32_bf16 v[66:69], v[188:191], v[220:223], v[66:69]
	v_mfma_f32_16x16x32_bf16 v[70:73], v[176:179], v[216:219], v[70:73]
	v_mfma_f32_16x16x32_bf16 v[70:73], v[180:183], v[220:223], v[70:73]
	s_barrier
; #define PG8_STAGE(bufoff, gbase, voff) do { _Pragma("unroll") for (int _i = 0; _i < 2; ++_i) \
;         __builtin_amdgcn_global_load_lds((const unsigned*)((const char*)(gbase) + (voff)[_i]), (PG8_LAS unsigned*)(lds + (bufoff) + ldsw + _i * 8192), 16, 0, 0); } while (0)
; #define PG8_LDA(dst, b, h) do { _Pragma("unroll") for (int m = 0; m < 4; ++m) _Pragma("unroll") for (int k = 0; k < 2; ++k) dst[m][k] = *(const PG8_LAS bf16x8*)(lds + PG8_SA(b, h) + aoff + m * 2048 + k * 1024); } while (0)
; #define PG8_MMA(ai, bj, At, Bt) do { __builtin_amdgcn_s_setprio(3); _Pragma("unroll") for (int m = 0; m < 4; ++m) _Pragma("unroll") for (int n = 0; n < 2; ++n) _Pragma("unroll") for (int k = 0; k < 2; ++k) \
;         acc[ai][bj][m][n] = __builtin_amdgcn_mfma_f32_16x16x32_bf16(Bt[n][k], At[m][k], acc[ai][bj][m][n], 0, 0, 0); __builtin_amdgcn_s_setprio(0); } while (0)
; #define PG8_WAIT_V(n) asm volatile("s_waitcnt vmcnt(" #n ")" ::: "memory")
; #define PG8_WAIT_L(n) asm volatile("s_waitcnt lgkmcnt(" #n ")" ::: "memory")
; #define PG8_BAR __builtin_amdgcn_s_barrier()
; #define PG8_SCHED __builtin_amdgcn_sched_barrier(0)
; template <class Epi, class Sched, bool ALIGN_EPI = false, bool SP2 = false>
; __device__ __forceinline__ void gemm_phase(PG8_LAS unsigned char* lds, const Gemm g, const Sched& S, const Epi& E) {
;     ...
;             PG8_LDA(At, 1, 1); PG8_STAGE(PG8_SB(1, 0), b3, voffB); PG8_STAGE(PG8_SB(1, 1), b3 + hstepB, voffB); PG8_STAGE(PG8_SA(1, 0), a3, voffA);
;             PG8_WAIT_V(8); PG8_WAIT_L(0); PG8_BAR; PG8_MMA(1, 0, At, B0); PG8_MMA(1, 1, At, B1); PG8_BAR; PG8_SCHED;
	s_setprio 0
	s_add_i32 s36, s84, s33
	v_lshl_add_u64 v[160:161], v[160:161], 0, s[10:11]
	s_mov_b32 m0, s36
	ds_read_b128 v[192:195], v159 offset:49152
	ds_read_b128 v[196:199], v159 offset:50176
	ds_read_b128 v[200:203], v159 offset:51200
	ds_read_b128 v[204:207], v159 offset:52224
	ds_read_b128 v[208:211], v159 offset:53248
	ds_read_b128 v[212:215], v159 offset:54272
	ds_read_b128 v[216:219], v159 offset:55296
	ds_read_b128 v[220:223], v159 offset:56320
	global_load_lds_dwordx4 v[160:161], off
	s_add_i32 m0, s36, 0x2000
	s_add_u32 s0, s0, 0x100080
	v_lshl_add_u64 v[160:161], v[224:225], 0, s[10:11]
	s_addc_u32 s1, s1, 0
	s_add_i32 s36, s85, s33
	global_load_lds_dwordx4 v[160:161], off
	v_lshl_add_u64 v[160:161], s[0:1], 0, v[136:137]
	s_mov_b32 m0, s36
	s_nop 0
	global_load_lds_dwordx4 v[160:161], off
	v_lshl_add_u64 v[160:161], s[0:1], 0, v[140:141]
	s_add_i32 m0, s36, 0x2000
	s_nop 0
	global_load_lds_dwordx4 v[160:161], off
	v_lshl_add_u64 v[160:161], v[226:227], 0, s[10:11]
	s_mov_b32 m0, s61
	s_nop 0
	global_load_lds_dwordx4 v[160:161], off
	v_lshl_add_u64 v[160:161], v[228:229], 0, s[10:11]
	s_mov_b32 m0, s62
	s_nop 0
	global_load_lds_dwordx4 v[160:161], off
	s_waitcnt vmcnt(8)
	s_waitcnt lgkmcnt(0)
	s_setprio 3
	s_barrier
	v_mfma_f32_16x16x32_bf16 v[62:65], v[130:133], v[192:195], v[62:65]
	v_mfma_f32_16x16x32_bf16 v[62:65], v[164:167], v[196:199], v[62:65]
	v_mfma_f32_16x16x32_bf16 v[58:61], v[168:171], v[192:195], v[58:61]
	v_mfma_f32_16x16x32_bf16 v[58:61], v[172:175], v[196:199], v[58:61]
	v_mfma_f32_16x16x32_bf16 v[42:45], v[168:171], v[200:203], v[42:45]
	v_mfma_f32_16x16x32_bf16 v[42:45], v[172:175], v[204:207], v[42:45]
	v_mfma_f32_16x16x32_bf16 v[46:49], v[130:133], v[200:203], v[46:49]
	v_mfma_f32_16x16x32_bf16 v[46:49], v[164:167], v[204:207], v[46:49]
	v_mfma_f32_16x16x32_bf16 v[30:33], v[130:133], v[208:211], v[30:33]
	v_mfma_f32_16x16x32_bf16 v[30:33], v[164:167], v[212:215], v[30:33]
	v_mfma_f32_16x16x32_bf16 v[26:29], v[168:171], v[208:211], v[26:29]
	v_mfma_f32_16x16x32_bf16 v[26:29], v[172:175], v[212:215], v[26:29]
	v_mfma_f32_16x16x32_bf16 v[10:13], v[168:171], v[216:219], v[10:13]
	v_mfma_f32_16x16x32_bf16 v[10:13], v[172:175], v[220:223], v[10:13]
	v_mfma_f32_16x16x32_bf16 v[14:17], v[130:133], v[216:219], v[14:17]
	v_mfma_f32_16x16x32_bf16 v[14:17], v[164:167], v[220:223], v[14:17]
	v_mfma_f32_16x16x32_bf16 v[54:57], v[176:179], v[192:195], v[54:57]
	v_mfma_f32_16x16x32_bf16 v[54:57], v[180:183], v[196:199], v[54:57]
	v_mfma_f32_16x16x32_bf16 v[50:53], v[184:187], v[192:195], v[50:53]
	v_mfma_f32_16x16x32_bf16 v[50:53], v[188:191], v[196:199], v[50:53]
	v_mfma_f32_16x16x32_bf16 v[34:37], v[184:187], v[200:203], v[34:37]
	v_mfma_f32_16x16x32_bf16 v[34:37], v[188:191], v[204:207], v[34:37]
	v_mfma_f32_16x16x32_bf16 v[38:41], v[176:179], v[200:203], v[38:41]
	v_mfma_f32_16x16x32_bf16 v[38:41], v[180:183], v[204:207], v[38:41]
	v_mfma_f32_16x16x32_bf16 v[22:25], v[176:179], v[208:211], v[22:25]
	v_mfma_f32_16x16x32_bf16 v[22:25], v[180:183], v[212:215], v[22:25]
	v_mfma_f32_16x16x32_bf16 v[18:21], v[184:187], v[208:211], v[18:21]
	v_mfma_f32_16x16x32_bf16 v[18:21], v[188:191], v[212:215], v[18:21]
	v_mfma_f32_16x16x32_bf16 v[2:5], v[184:187], v[216:219], v[2:5]
	v_mfma_f32_16x16x32_bf16 v[2:5], v[188:191], v[220:223], v[2:5]
	v_mfma_f32_16x16x32_bf16 v[6:9], v[176:179], v[216:219], v[6:9]
	v_mfma_f32_16x16x32_bf16 v[6:9], v[180:183], v[220:223], v[6:9]
	s_barrier
	s_setprio 0
	s_add_i32 s83, s83, 2
	s_add_u32 s30, s30, 0x100
	s_addc_u32 s31, s31, 0
	s_cmp_gt_u32 s83, 61
	s_cbranch_scc1 .LBB0_730

; #define PG8_STAGE(bufoff, gbase, voff) do { _Pragma("unroll") for (int _i = 0; _i < 2; ++_i) \
;         __builtin_amdgcn_global_load_lds((const unsigned*)((const char*)(gbase) + (voff)[_i]), (PG8_LAS unsigned*)(lds + (bufoff) + ldsw + _i * 8192), 16, 0, 0); } while (0)
; #define PG8_LDA(dst, b, h) do { _Pragma("unroll") for (int m = 0; m < 4; ++m) _Pragma("unroll") for (int k = 0; k < 2; ++k) dst[m][k] = *(const PG8_LAS bf16x8*)(lds + PG8_SA(b, h) + aoff + m * 2048 + k * 1024); } while (0)
; #define PG8_LDB(dst, b, h) do { _Pragma("unroll") for (int n = 0; n < 2; ++n) _Pragma("unroll") for (int k = 0; k < 2; ++k) dst[n][k] = *(const PG8_LAS bf16x8*)(lds + PG8_SB(b, h) + boff + n * 2048 + k * 1024); } while (0)
; #define PG8_MMA(ai, bj, At, Bt) do { __builtin_amdgcn_s_setprio(3); _Pragma("unroll") for (int m = 0; m < 4; ++m) _Pragma("unroll") for (int n = 0; n < 2; ++n) _Pragma("unroll") for (int k = 0; k < 2; ++k) \
;         acc[ai][bj][m][n] = __builtin_amdgcn_mfma_f32_16x16x32_bf16(Bt[n][k], At[m][k], acc[ai][bj][m][n], 0, 0, 0); __builtin_amdgcn_s_setprio(0); } while (0)
; #define PG8_WAIT_V(n) asm volatile("s_waitcnt vmcnt(" #n ")" ::: "memory")
; template <class Epi, class Sched, bool ALIGN_EPI = false, bool SP2 = false>
; __device__ __forceinline__ void gemm_phase(PG8_LAS unsigned char* lds, const Gemm g, const Sched& S, const Epi& E) {
;     ...
;             const bool last = (t == nt - 2);
;             const char* a1 = cA + (size_t)(t + 1) * kstep;
;             const char* a2 = last ? nA : cA + (size_t)(t + 2) * kstep; const char* b2 = last ? nB : cB + (size_t)(t + 2) * kstep;
;             const char* a3 = a2 + kstep; const char* b3 = b2 + kstep;
;             if (last && has_next) S.a_ready(nxt);
;             if constexpr (Epi::MIDK) { if (t == E.midk_step(nt)) E.midk(acc, cur, wr, wc, fr, fq); }
;             if constexpr (SP2) {
;             PG8_LDB(B0, 0, 0); PG8_LDB(B1, 0, 1); PG8_SCHED; PG8_LDA(At, 0, 0); PG8_STAGE(PG8_SA(1, 1), a1 + hstepA, voffA);
;             PG8_WAIT_V(8); PG8_WAIT_L(0); PG8_BAR; PG8_MMA(0, 0, At, B0); PG8_MMA(0, 1, At, B1); PG8_BAR; PG8_SCHED;
;             PG8_LDA(At, 0, 1); PG8_STAGE(PG8_SB(0, 0), b2, voffB); PG8_STAGE(PG8_SB(0, 1), b2 + hstepB, voffB); PG8_STAGE(PG8_SA(0, 0), a2, voffA);
;             PG8_WAIT_V(8); PG8_WAIT_L(0); PG8_BAR; PG8_MMA(1, 0, At, B0); PG8_MMA(1, 1, At, B1); PG8_BAR; PG8_SCHED;
.LBB0_808:
	v_add_u32_e32 v3, s65, v186
	ds_read_b128 v[134:137], v3
	ds_read_b128 v[138:141], v3 offset:1024
	ds_read_b128 v[142:145], v3 offset:2048
	ds_read_b128 v[146:149], v3 offset:3072
	v_add_u32_e32 v3, s66, v186
	s_add_u32 s36, s28, s30
	ds_read_b128 v[150:153], v3
	ds_read_b128 v[154:157], v3 offset:1024
	ds_read_b128 v[158:161], v3 offset:2048
	ds_read_b128 v[190:193], v3 offset:3072
	s_addc_u32 s37, s29, s31
	s_add_u32 s36, s36, 0x100
	s_addc_u32 s37, s37, 0
	s_add_u32 s86, s83, s30
	s_addc_u32 s87, s84, s31
	s_cmpk_eq_i32 s30, 0x1f00
	s_cselect_b32 s41, s23, s37
	s_cselect_b32 s40, s75, s36
	s_cselect_b32 s37, s77, s87
	s_cselect_b32 s36, s78, s86
	v_lshl_add_u64 v[4:5], v[180:181], 0, s[30:31]
	s_add_i32 m0, s42, 0xc000
	ds_read_b128 v[194:197], v188
	ds_read_b128 v[198:201], v188 offset:1024
	ds_read_b128 v[202:205], v188 offset:2048
	ds_read_b128 v[206:209], v188 offset:3072
	ds_read_b128 v[210:213], v188 offset:4096
	ds_read_b128 v[214:217], v188 offset:5120
	ds_read_b128 v[218:221], v188 offset:6144
	ds_read_b128 v[222:225], v188 offset:7168
	global_load_lds_dwordx4 v[4:5], off
	v_lshl_add_u64 v[4:5], v[182:183], 0, s[30:31]
	s_add_i32 m0, s42, 0xe000
	s_nop 0
	global_load_lds_dwordx4 v[4:5], off
	s_waitcnt vmcnt(8)
	s_waitcnt lgkmcnt(0)
	s_setprio 3
	s_barrier
	v_mfma_f32_16x16x32_bf16 v[130:133], v[134:137], v[194:197], v[130:133]
	v_mfma_f32_16x16x32_bf16 v[130:133], v[138:141], v[198:201], v[130:133]
	v_mfma_f32_16x16x32_bf16 v[126:129], v[142:145], v[194:197], v[126:129]
	v_mfma_f32_16x16x32_bf16 v[126:129], v[146:149], v[198:201], v[126:129]
	v_mfma_f32_16x16x32_bf16 v[110:113], v[142:145], v[202:205], v[110:113]
	v_mfma_f32_16x16x32_bf16 v[110:113], v[146:149], v[206:209], v[110:113]
	v_mfma_f32_16x16x32_bf16 v[114:117], v[134:137], v[202:205], v[114:117]
	v_mfma_f32_16x16x32_bf16 v[114:117], v[138:141], v[206:209], v[114:117]
	v_mfma_f32_16x16x32_bf16 v[98:101], v[134:137], v[210:213], v[98:101]
	v_mfma_f32_16x16x32_bf16 v[98:101], v[138:141], v[214:217], v[98:101]
	v_mfma_f32_16x16x32_bf16 v[94:97], v[142:145], v[210:213], v[94:97]
	v_mfma_f32_16x16x32_bf16 v[94:97], v[146:149], v[214:217], v[94:97]
	v_mfma_f32_16x16x32_bf16 v[78:81], v[142:145], v[218:221], v[78:81]
	v_mfma_f32_16x16x32_bf16 v[78:81], v[146:149], v[222:225], v[78:81]
	v_mfma_f32_16x16x32_bf16 v[82:85], v[134:137], v[218:221], v[82:85]
	v_mfma_f32_16x16x32_bf16 v[82:85], v[138:141], v[222:225], v[82:85]
	v_mfma_f32_16x16x32_bf16 v[122:125], v[150:153], v[194:197], v[122:125]
	v_mfma_f32_16x16x32_bf16 v[122:125], v[154:157], v[198:201], v[122:125]
	v_mfma_f32_16x16x32_bf16 v[118:121], v[158:161], v[194:197], v[118:121]
	v_mfma_f32_16x16x32_bf16 v[118:121], v[190:193], v[198:201], v[118:121]
	v_mfma_f32_16x16x32_bf16 v[102:105], v[158:161], v[202:205], v[102:105]
	v_mfma_f32_16x16x32_bf16 v[102:105], v[190:193], v[206:209], v[102:105]
	v_mfma_f32_16x16x32_bf16 v[106:109], v[150:153], v[202:205], v[106:109]
	v_mfma_f32_16x16x32_bf16 v[106:109], v[154:157], v[206:209], v[106:109]
	v_mfma_f32_16x16x32_bf16 v[90:93], v[150:153], v[210:213], v[90:93]
	v_mfma_f32_16x16x32_bf16 v[90:93], v[154:157], v[214:217], v[90:93]
	v_mfma_f32_16x16x32_bf16 v[86:89], v[158:161], v[210:213], v[86:89]
	v_mfma_f32_16x16x32_bf16 v[86:89], v[190:193], v[214:217], v[86:89]
	v_mfma_f32_16x16x32_bf16 v[70:73], v[158:161], v[218:221], v[70:73]
	v_mfma_f32_16x16x32_bf16 v[70:73], v[190:193], v[222:225], v[70:73]
	v_mfma_f32_16x16x32_bf16 v[74:77], v[150:153], v[218:221], v[74:77]
	v_mfma_f32_16x16x32_bf16 v[74:77], v[154:157], v[222:225], v[74:77]
	s_barrier
	s_setprio 0
	s_add_i32 s86, s65, s33
	v_lshl_add_u64 v[226:227], s[36:37], 0, v[166:167]
	s_mov_b32 m0, s86
	ds_read_b128 v[194:197], v188 offset:16384
	ds_read_b128 v[198:201], v188 offset:17408
	ds_read_b128 v[202:205], v188 offset:18432
	ds_read_b128 v[206:209], v188 offset:19456
	ds_read_b128 v[210:213], v188 offset:20480
	ds_read_b128 v[214:217], v188 offset:21504
	ds_read_b128 v[218:221], v188 offset:22528
	ds_read_b128 v[222:225], v188 offset:23552
	global_load_lds_dwordx4 v[226:227], off
	s_add_i32 m0, s86, 0x2000
	s_add_u32 s86, s36, 0x100000
	v_lshl_add_u64 v[228:229], s[36:37], 0, v[170:171]
	s_addc_u32 s87, s37, 0
	s_add_i32 s88, s66, s33
	global_load_lds_dwordx4 v[228:229], off
	v_lshl_add_u64 v[4:5], s[86:87], 0, v[166:167]
	s_mov_b32 m0, s88
	v_lshl_add_u64 v[230:231], s[40:41], 0, v[164:165]
	global_load_lds_dwordx4 v[4:5], off
	v_lshl_add_u64 v[4:5], s[86:87], 0, v[170:171]
	s_add_i32 m0, s88, 0x2000
	v_lshl_add_u64 v[232:233], s[40:41], 0, v[168:169]
	global_load_lds_dwordx4 v[4:5], off
	s_mov_b32 m0, s42
	s_nop 0
	global_load_lds_dwordx4 v[230:231], off
	s_mov_b32 m0, s43
	s_nop 0
	global_load_lds_dwordx4 v[232:233], off
	s_waitcnt vmcnt(8)
	s_waitcnt lgkmcnt(0)
	s_setprio 3
	s_barrier
; #define PG8_STAGE(bufoff, gbase, voff) do { _Pragma("unroll") for (int _i = 0; _i < 2; ++_i) \
;         __builtin_amdgcn_global_load_lds((const unsigned*)((const char*)(gbase) + (voff)[_i]), (PG8_LAS unsigned*)(lds + (bufoff) + ldsw + _i * 8192), 16, 0, 0); } while (0)
; #define PG8_LDA(dst, b, h) do { _Pragma("unroll") for (int m = 0; m < 4; ++m) _Pragma("unroll") for (int k = 0; k < 2; ++k) dst[m][k] = *(const PG8_LAS bf16x8*)(lds + PG8_SA(b, h) + aoff + m * 2048 + k * 1024); } while (0)
; #define PG8_LDB(dst, b, h) do { _Pragma("unroll") for (int n = 0; n < 2; ++n) _Pragma("unroll") for (int k = 0; k < 2; ++k) dst[n][k] = *(const PG8_LAS bf16x8*)(lds + PG8_SB(b, h) + boff + n * 2048 + k * 1024); } while (0)
; #define PG8_MMA(ai, bj, At, Bt) do { __builtin_amdgcn_s_setprio(3); _Pragma("unroll") for (int m = 0; m < 4; ++m) _Pragma("unroll") for (int n = 0; n < 2; ++n) _Pragma("unroll") for (int k = 0; k < 2; ++k) \
;         acc[ai][bj][m][n] = __builtin_amdgcn_mfma_f32_16x16x32_bf16(Bt[n][k], At[m][k], acc[ai][bj][m][n], 0, 0, 0); __builtin_amdgcn_s_setprio(0); } while (0)
; #define PG8_WAIT_V(n) asm volatile("s_waitcnt vmcnt(" #n ")" ::: "memory")
; #define PG8_WAIT_L(n) asm volatile("s_waitcnt lgkmcnt(" #n ")" ::: "memory")
; #define PG8_BAR __builtin_amdgcn_s_barrier()
; #define PG8_SCHED __builtin_amdgcn_sched_barrier(0)
; template <class Epi, class Sched, bool ALIGN_EPI = false, bool SP2 = false>
; __device__ __forceinline__ void gemm_phase(PG8_LAS unsigned char* lds, const Gemm g, const Sched& S, const Epi& E) {
;     ...
;             PG8_WAIT_V(8); PG8_WAIT_L(0); PG8_BAR; PG8_MMA(1, 0, At, B0); PG8_MMA(1, 1, At, B1); PG8_BAR; PG8_SCHED;
;             PG8_LDB(B0, 1, 0); PG8_LDB(B1, 1, 1); PG8_SCHED; PG8_LDA(At, 1, 0); PG8_STAGE(PG8_SA(0, 1), a2 + hstepA, voffA);
;             PG8_WAIT_V(8); PG8_WAIT_L(0); PG8_BAR; PG8_MMA(0, 0, At, B0); PG8_MMA(0, 1, At, B1); PG8_BAR; PG8_SCHED;
	v_mfma_f32_16x16x32_bf16 v[66:69], v[134:137], v[194:197], v[66:69]
	v_mfma_f32_16x16x32_bf16 v[66:69], v[138:141], v[198:201], v[66:69]
	v_mfma_f32_16x16x32_bf16 v[62:65], v[142:145], v[194:197], v[62:65]
	v_mfma_f32_16x16x32_bf16 v[62:65], v[146:149], v[198:201], v[62:65]
	v_mfma_f32_16x16x32_bf16 v[46:49], v[142:145], v[202:205], v[46:49]
	v_mfma_f32_16x16x32_bf16 v[46:49], v[146:149], v[206:209], v[46:49]
	v_mfma_f32_16x16x32_bf16 v[50:53], v[134:137], v[202:205], v[50:53]
	v_mfma_f32_16x16x32_bf16 v[50:53], v[138:141], v[206:209], v[50:53]
	v_mfma_f32_16x16x32_bf16 v[34:37], v[134:137], v[210:213], v[34:37]
	v_mfma_f32_16x16x32_bf16 v[34:37], v[138:141], v[214:217], v[34:37]
	v_mfma_f32_16x16x32_bf16 v[30:33], v[142:145], v[210:213], v[30:33]
	v_mfma_f32_16x16x32_bf16 v[30:33], v[146:149], v[214:217], v[30:33]
	v_mfma_f32_16x16x32_bf16 v[14:17], v[142:145], v[218:221], v[14:17]
	v_mfma_f32_16x16x32_bf16 v[14:17], v[146:149], v[222:225], v[14:17]
	v_mfma_f32_16x16x32_bf16 v[18:21], v[134:137], v[218:221], v[18:21]
	v_mfma_f32_16x16x32_bf16 v[18:21], v[138:141], v[222:225], v[18:21]
	v_mfma_f32_16x16x32_bf16 v[58:61], v[150:153], v[194:197], v[58:61]
	v_mfma_f32_16x16x32_bf16 v[58:61], v[154:157], v[198:201], v[58:61]
	v_mfma_f32_16x16x32_bf16 v[54:57], v[158:161], v[194:197], v[54:57]
	v_mfma_f32_16x16x32_bf16 v[54:57], v[190:193], v[198:201], v[54:57]
	v_mfma_f32_16x16x32_bf16 v[38:41], v[158:161], v[202:205], v[38:41]
	v_mfma_f32_16x16x32_bf16 v[38:41], v[190:193], v[206:209], v[38:41]
	v_mfma_f32_16x16x32_bf16 v[42:45], v[150:153], v[202:205], v[42:45]
	v_mfma_f32_16x16x32_bf16 v[42:45], v[154:157], v[206:209], v[42:45]
	v_mfma_f32_16x16x32_bf16 v[26:29], v[150:153], v[210:213], v[26:29]
	v_mfma_f32_16x16x32_bf16 v[26:29], v[154:157], v[214:217], v[26:29]
	v_mfma_f32_16x16x32_bf16 v[22:25], v[158:161], v[210:213], v[22:25]
	v_mfma_f32_16x16x32_bf16 v[22:25], v[190:193], v[214:217], v[22:25]
	v_mfma_f32_16x16x32_bf16 v[4:7], v[158:161], v[218:221], v[6:9]
	v_mfma_f32_16x16x32_bf16 v[4:7], v[190:193], v[222:225], v[4:7]
	v_mfma_f32_16x16x32_bf16 v[10:13], v[150:153], v[218:221], v[10:13]
	v_mfma_f32_16x16x32_bf16 v[10:13], v[154:157], v[222:225], v[10:13]
	s_barrier
	s_setprio 0
	s_add_i32 s86, 0, 0x18000
	v_add_u32_e32 v3, s86, v186
	s_add_i32 s87, 0, 0x1c000
	ds_read_b128 v[134:137], v3
	ds_read_b128 v[138:141], v3 offset:1024
	ds_read_b128 v[142:145], v3 offset:2048
	ds_read_b128 v[146:149], v3 offset:3072
	v_add_u32_e32 v3, s87, v186
	ds_read_b128 v[150:153], v3
	ds_read_b128 v[154:157], v3 offset:1024
	ds_read_b128 v[158:161], v3 offset:2048
	ds_read_b128 v[190:193], v3 offset:3072
	s_add_u32 s40, s40, 0x100000
	s_addc_u32 s41, s41, 0
	s_mov_b32 m0, s44
	v_lshl_add_u64 v[8:9], s[40:41], 0, v[164:165]
	ds_read_b128 v[194:197], v188 offset:32768
	ds_read_b128 v[198:201], v188 offset:33792
	ds_read_b128 v[202:205], v188 offset:34816
	ds_read_b128 v[206:209], v188 offset:35840
	ds_read_b128 v[210:213], v188 offset:36864
	ds_read_b128 v[214:217], v188 offset:37888
	ds_read_b128 v[218:221], v188 offset:38912
	ds_read_b128 v[222:225], v188 offset:39936
	global_load_lds_dwordx4 v[8:9], off
	v_lshl_add_u64 v[8:9], s[40:41], 0, v[168:169]
	s_mov_b32 m0, s45
	s_nop 0
	global_load_lds_dwordx4 v[8:9], off
	s_waitcnt vmcnt(8)
	s_waitcnt lgkmcnt(0)
	s_setprio 3
	s_barrier
	v_mfma_f32_16x16x32_bf16 v[130:133], v[134:137], v[194:197], v[130:133]
	v_mfma_f32_16x16x32_bf16 v[130:133], v[138:141], v[198:201], v[130:133]
	v_mfma_f32_16x16x32_bf16 v[126:129], v[142:145], v[194:197], v[126:129]
	v_mfma_f32_16x16x32_bf16 v[126:129], v[146:149], v[198:201], v[126:129]
	v_mfma_f32_16x16x32_bf16 v[110:113], v[142:145], v[202:205], v[110:113]
	v_mfma_f32_16x16x32_bf16 v[110:113], v[146:149], v[206:209], v[110:113]
	v_mfma_f32_16x16x32_bf16 v[114:117], v[134:137], v[202:205], v[114:117]
	v_mfma_f32_16x16x32_bf16 v[114:117], v[138:141], v[206:209], v[114:117]
	v_mfma_f32_16x16x32_bf16 v[98:101], v[134:137], v[210:213], v[98:101]
	v_mfma_f32_16x16x32_bf16 v[98:101], v[138:141], v[214:217], v[98:101]
	v_mfma_f32_16x16x32_bf16 v[94:97], v[142:145], v[210:213], v[94:97]
	v_mfma_f32_16x16x32_bf16 v[94:97], v[146:149], v[214:217], v[94:97]
	v_mfma_f32_16x16x32_bf16 v[78:81], v[142:145], v[218:221], v[78:81]
	v_mfma_f32_16x16x32_bf16 v[78:81], v[146:149], v[222:225], v[78:81]
	v_mfma_f32_16x16x32_bf16 v[82:85], v[134:137], v[218:221], v[82:85]
	v_mfma_f32_16x16x32_bf16 v[82:85], v[138:141], v[222:225], v[82:85]
	v_mfma_f32_16x16x32_bf16 v[122:125], v[150:153], v[194:197], v[122:125]
	v_mfma_f32_16x16x32_bf16 v[122:125], v[154:157], v[198:201], v[122:125]
	v_mfma_f32_16x16x32_bf16 v[118:121], v[158:161], v[194:197], v[118:121]
	v_mfma_f32_16x16x32_bf16 v[118:121], v[190:193], v[198:201], v[118:121]
	v_mfma_f32_16x16x32_bf16 v[102:105], v[158:161], v[202:205], v[102:105]
	v_mfma_f32_16x16x32_bf16 v[102:105], v[190:193], v[206:209], v[102:105]
	v_mfma_f32_16x16x32_bf16 v[106:109], v[150:153], v[202:205], v[106:109]
	v_mfma_f32_16x16x32_bf16 v[106:109], v[154:157], v[206:209], v[106:109]
	v_mfma_f32_16x16x32_bf16 v[90:93], v[150:153], v[210:213], v[90:93]
	v_mfma_f32_16x16x32_bf16 v[90:93], v[154:157], v[214:217], v[90:93]
	v_mfma_f32_16x16x32_bf16 v[86:89], v[158:161], v[210:213], v[86:89]
	v_mfma_f32_16x16x32_bf16 v[86:89], v[190:193], v[214:217], v[86:89]
	v_mfma_f32_16x16x32_bf16 v[70:73], v[158:161], v[218:221], v[70:73]
	v_mfma_f32_16x16x32_bf16 v[70:73], v[190:193], v[222:225], v[70:73]
	v_mfma_f32_16x16x32_bf16 v[74:77], v[150:153], v[218:221], v[74:77]
	v_mfma_f32_16x16x32_bf16 v[74:77], v[154:157], v[222:225], v[74:77]
	s_barrier
; #define PG8_STAGE(bufoff, gbase, voff) do { _Pragma("unroll") for (int _i = 0; _i < 2; ++_i) \
;         __builtin_amdgcn_global_load_lds((const unsigned*)((const char*)(gbase) + (voff)[_i]), (PG8_LAS unsigned*)(lds + (bufoff) + ldsw + _i * 8192), 16, 0, 0); } while (0)
; #define PG8_LDA(dst, b, h) do { _Pragma("unroll") for (int m = 0; m < 4; ++m) _Pragma("unroll") for (int k = 0; k < 2; ++k) dst[m][k] = *(const PG8_LAS bf16x8*)(lds + PG8_SA(b, h) + aoff + m * 2048 + k * 1024); } while (0)
; #define PG8_MMA(ai, bj, At, Bt) do { __builtin_amdgcn_s_setprio(3); _Pragma("unroll") for (int m = 0; m < 4; ++m) _Pragma("unroll") for (int n = 0; n < 2; ++n) _Pragma("unroll") for (int k = 0; k < 2; ++k) \
;         acc[ai][bj][m][n] = __builtin_amdgcn_mfma_f32_16x16x32_bf16(Bt[n][k], At[m][k], acc[ai][bj][m][n], 0, 0, 0); __builtin_amdgcn_s_setprio(0); } while (0)
; #define PG8_WAIT_V(n) asm volatile("s_waitcnt vmcnt(" #n ")" ::: "memory")
; #define PG8_WAIT_L(n) asm volatile("s_waitcnt lgkmcnt(" #n ")" ::: "memory")
; #define PG8_BAR __builtin_amdgcn_s_barrier()
; #define PG8_SCHED __builtin_amdgcn_sched_barrier(0)
; template <class Epi, class Sched, bool ALIGN_EPI = false, bool SP2 = false>
; __device__ __forceinline__ void gemm_phase(PG8_LAS unsigned char* lds, const Gemm g, const Sched& S, const Epi& E) {
;     ...
;             PG8_LDA(At, 1, 1); PG8_STAGE(PG8_SB(1, 0), b3, voffB); PG8_STAGE(PG8_SB(1, 1), b3 + hstepB, voffB); PG8_STAGE(PG8_SA(1, 0), a3, voffA);
;             PG8_WAIT_V(8); PG8_WAIT_L(0); PG8_BAR; PG8_MMA(1, 0, At, B0); PG8_MMA(1, 1, At, B1); PG8_BAR; PG8_SCHED;
	s_setprio 0
	s_add_i32 s40, s86, s33
	v_lshl_add_u64 v[8:9], v[226:227], 0, s[10:11]
	s_mov_b32 m0, s40
	ds_read_b128 v[194:197], v188 offset:49152
	ds_read_b128 v[198:201], v188 offset:50176
	ds_read_b128 v[202:205], v188 offset:51200
	ds_read_b128 v[206:209], v188 offset:52224
	ds_read_b128 v[210:213], v188 offset:53248
	ds_read_b128 v[214:217], v188 offset:54272
	ds_read_b128 v[218:221], v188 offset:55296
	ds_read_b128 v[222:225], v188 offset:56320
	global_load_lds_dwordx4 v[8:9], off
	s_add_i32 m0, s40, 0x2000
	s_add_u32 s36, s36, 0x100080
	v_lshl_add_u64 v[8:9], v[228:229], 0, s[10:11]
	s_addc_u32 s37, s37, 0
	s_add_i32 s40, s87, s33
	global_load_lds_dwordx4 v[8:9], off
	v_lshl_add_u64 v[8:9], s[36:37], 0, v[166:167]
	s_mov_b32 m0, s40
	s_nop 0
	global_load_lds_dwordx4 v[8:9], off
	v_lshl_add_u64 v[8:9], s[36:37], 0, v[170:171]
	s_add_i32 m0, s40, 0x2000
	s_nop 0
	global_load_lds_dwordx4 v[8:9], off
	v_lshl_add_u64 v[8:9], v[230:231], 0, s[10:11]
	s_mov_b32 m0, s60
	s_nop 0
	global_load_lds_dwordx4 v[8:9], off
	v_lshl_add_u64 v[8:9], v[232:233], 0, s[10:11]
	s_mov_b32 m0, s61
	s_nop 0
	global_load_lds_dwordx4 v[8:9], off
	s_waitcnt vmcnt(8)
	s_waitcnt lgkmcnt(0)
	s_setprio 3
	s_barrier
	v_mfma_f32_16x16x32_bf16 v[66:69], v[134:137], v[194:197], v[66:69]
	v_mfma_f32_16x16x32_bf16 v[66:69], v[138:141], v[198:201], v[66:69]
	v_mfma_f32_16x16x32_bf16 v[62:65], v[142:145], v[194:197], v[62:65]
	v_mfma_f32_16x16x32_bf16 v[62:65], v[146:149], v[198:201], v[62:65]
	v_mfma_f32_16x16x32_bf16 v[46:49], v[142:145], v[202:205], v[46:49]
	v_mfma_f32_16x16x32_bf16 v[46:49], v[146:149], v[206:209], v[46:49]
	v_mfma_f32_16x16x32_bf16 v[50:53], v[134:137], v[202:205], v[50:53]
	v_mfma_f32_16x16x32_bf16 v[50:53], v[138:141], v[206:209], v[50:53]
	v_mfma_f32_16x16x32_bf16 v[34:37], v[134:137], v[210:213], v[34:37]
	v_mfma_f32_16x16x32_bf16 v[34:37], v[138:141], v[214:217], v[34:37]
	v_mfma_f32_16x16x32_bf16 v[30:33], v[142:145], v[210:213], v[30:33]
	v_mfma_f32_16x16x32_bf16 v[30:33], v[146:149], v[214:217], v[30:33]
	v_mfma_f32_16x16x32_bf16 v[14:17], v[142:145], v[218:221], v[14:17]
	v_mfma_f32_16x16x32_bf16 v[14:17], v[146:149], v[222:225], v[14:17]
	v_mfma_f32_16x16x32_bf16 v[18:21], v[134:137], v[218:221], v[18:21]
	v_mfma_f32_16x16x32_bf16 v[18:21], v[138:141], v[222:225], v[18:21]
	v_mfma_f32_16x16x32_bf16 v[58:61], v[150:153], v[194:197], v[58:61]
	v_mfma_f32_16x16x32_bf16 v[54:57], v[158:161], v[194:197], v[54:57]
	v_mfma_f32_16x16x32_bf16 v[42:45], v[150:153], v[202:205], v[42:45]
	v_mfma_f32_16x16x32_bf16 v[38:41], v[158:161], v[202:205], v[38:41]
	v_mfma_f32_16x16x32_bf16 v[26:29], v[150:153], v[210:213], v[26:29]
	v_mfma_f32_16x16x32_bf16 v[22:25], v[158:161], v[210:213], v[22:25]
	v_mfma_f32_16x16x32_bf16 v[8:11], v[150:153], v[218:221], v[10:13]
	v_mfma_f32_16x16x32_bf16 v[4:7], v[158:161], v[218:221], v[4:7]
	v_mfma_f32_16x16x32_bf16 v[58:61], v[154:157], v[198:201], v[58:61]
	v_mfma_f32_16x16x32_bf16 v[54:57], v[190:193], v[198:201], v[54:57]
	v_mfma_f32_16x16x32_bf16 v[42:45], v[154:157], v[206:209], v[42:45]
	v_mfma_f32_16x16x32_bf16 v[38:41], v[190:193], v[206:209], v[38:41]
	v_mfma_f32_16x16x32_bf16 v[26:29], v[154:157], v[214:217], v[26:29]
	v_mfma_f32_16x16x32_bf16 v[22:25], v[190:193], v[214:217], v[22:25]
	v_mfma_f32_16x16x32_bf16 v[10:13], v[154:157], v[222:225], v[8:11]
	v_mfma_f32_16x16x32_bf16 v[6:9], v[190:193], v[222:225], v[4:7]
	s_barrier
	s_setprio 0
	s_add_i32 s85, s85, 2
	s_add_u32 s30, s30, 0x100
	s_addc_u32 s31, s31, 0
	s_cmp_gt_u32 s85, 61
	s_cbranch_scc1 .LBB0_811

; #define PG8_STAGE(bufoff, gbase, voff) do { _Pragma("unroll") for (int _i = 0; _i < 2; ++_i) \
;         __builtin_amdgcn_global_load_lds((const unsigned*)((const char*)(gbase) + (voff)[_i]), (PG8_LAS unsigned*)(lds + (bufoff) + ldsw + _i * 8192), 16, 0, 0); } while (0)
; #define PG8_LDA(dst, b, h) do { _Pragma("unroll") for (int m = 0; m < 4; ++m) _Pragma("unroll") for (int k = 0; k < 2; ++k) dst[m][k] = *(const PG8_LAS bf16x8*)(lds + PG8_SA(b, h) + aoff + m * 2048 + k * 1024); } while (0)
; #define PG8_LDB(dst, b, h) do { _Pragma("unroll") for (int n = 0; n < 2; ++n) _Pragma("unroll") for (int k = 0; k < 2; ++k) dst[n][k] = *(const PG8_LAS bf16x8*)(lds + PG8_SB(b, h) + boff + n * 2048 + k * 1024); } while (0)
; #define PG8_MMA(ai, bj, At, Bt) do { __builtin_amdgcn_s_setprio(3); _Pragma("unroll") for (int m = 0; m < 4; ++m) _Pragma("unroll") for (int n = 0; n < 2; ++n) _Pragma("unroll") for (int k = 0; k < 2; ++k) \
;         acc[ai][bj][m][n] = __builtin_amdgcn_mfma_f32_16x16x32_bf16(Bt[n][k], At[m][k], acc[ai][bj][m][n], 0, 0, 0); __builtin_amdgcn_s_setprio(0); } while (0)
; #define PG8_WAIT_V(n) asm volatile("s_waitcnt vmcnt(" #n ")" ::: "memory")
; template <class Epi, class Sched, bool ALIGN_EPI = false, bool SP2 = false>
; __device__ __forceinline__ void gemm_phase(PG8_LAS unsigned char* lds, const Gemm g, const Sched& S, const Epi& E) {
;     ...
;             const bool last = (t == nt - 2);
;             const char* a1 = cA + (size_t)(t + 1) * kstep;
;             const char* a2 = last ? nA : cA + (size_t)(t + 2) * kstep; const char* b2 = last ? nB : cB + (size_t)(t + 2) * kstep;
;             const char* a3 = a2 + kstep; const char* b3 = b2 + kstep;
;             if (last && has_next) S.a_ready(nxt);
;             if constexpr (Epi::MIDK) { if (t == E.midk_step(nt)) E.midk(acc, cur, wr, wc, fr, fq); }
;             if constexpr (SP2) {
;             PG8_LDB(B0, 0, 0); PG8_LDB(B1, 0, 1); PG8_SCHED; PG8_LDA(At, 0, 0); PG8_STAGE(PG8_SA(1, 1), a1 + hstepA, voffA);
;             PG8_WAIT_V(8); PG8_WAIT_L(0); PG8_BAR; PG8_MMA(0, 0, At, B0); PG8_MMA(0, 1, At, B1); PG8_BAR; PG8_SCHED;
;             PG8_LDA(At, 0, 1); PG8_STAGE(PG8_SB(0, 0), b2, voffB); PG8_STAGE(PG8_SB(0, 1), b2 + hstepB, voffB); PG8_STAGE(PG8_SA(0, 0), a2, voffA);
;             PG8_WAIT_V(8); PG8_WAIT_L(0); PG8_BAR; PG8_MMA(1, 0, At, B0); PG8_MMA(1, 1, At, B1); PG8_BAR; PG8_SCHED;
.LBB0_908:
	ds_read_b128 v[158:161], v155
	ds_read_b128 v[164:167], v155 offset:1024
	ds_read_b128 v[168:171], v155 offset:2048
	ds_read_b128 v[172:175], v155 offset:3072
	ds_read_b128 v[176:179], v156
	ds_read_b128 v[180:183], v156 offset:1024
	ds_read_b128 v[184:187], v156 offset:2048
	ds_read_b128 v[188:191], v156 offset:3072
	s_add_u32 s26, s24, 0xfff00080
	s_addc_u32 s27, s25, -1
	s_cmp_eq_u32 s55, 60
	s_cselect_b32 s29, s17, s27
	s_cselect_b32 s28, s47, s26
	s_cselect_b32 s27, s15, s54
	s_cselect_b32 s26, s52, s53
	v_lshl_add_u64 v[146:147], s[24:25], 0, v[138:139]
	s_add_i32 m0, s23, 0xc000
	ds_read_b128 v[192:195], v157
	ds_read_b128 v[196:199], v157 offset:1024
	ds_read_b128 v[200:203], v157 offset:2048
	ds_read_b128 v[204:207], v157 offset:3072
	ds_read_b128 v[208:211], v157 offset:4096
	ds_read_b128 v[212:215], v157 offset:5120
	ds_read_b128 v[216:219], v157 offset:6144
	ds_read_b128 v[220:223], v157 offset:7168
	global_load_lds_dwordx4 v[146:147], off
	v_lshl_add_u64 v[146:147], s[24:25], 0, v[140:141]
	s_add_i32 m0, s23, 0xe000
	s_nop 0
	global_load_lds_dwordx4 v[146:147], off
	s_waitcnt vmcnt(8)
	s_waitcnt lgkmcnt(0)
	s_setprio 3
	s_barrier
	v_mfma_f32_16x16x32_bf16 v[126:129], v[158:161], v[192:195], v[126:129]
	v_mfma_f32_16x16x32_bf16 v[126:129], v[164:167], v[196:199], v[126:129]
	v_mfma_f32_16x16x32_bf16 v[122:125], v[168:171], v[192:195], v[122:125]
	v_mfma_f32_16x16x32_bf16 v[122:125], v[172:175], v[196:199], v[122:125]
	v_mfma_f32_16x16x32_bf16 v[106:109], v[168:171], v[200:203], v[106:109]
	v_mfma_f32_16x16x32_bf16 v[106:109], v[172:175], v[204:207], v[106:109]
	v_mfma_f32_16x16x32_bf16 v[114:117], v[158:161], v[200:203], v[114:117]
	v_mfma_f32_16x16x32_bf16 v[114:117], v[164:167], v[204:207], v[114:117]
	v_mfma_f32_16x16x32_bf16 v[98:101], v[158:161], v[208:211], v[98:101]
	v_mfma_f32_16x16x32_bf16 v[98:101], v[164:167], v[212:215], v[98:101]
	v_mfma_f32_16x16x32_bf16 v[90:93], v[168:171], v[208:211], v[90:93]
	v_mfma_f32_16x16x32_bf16 v[90:93], v[172:175], v[212:215], v[90:93]
	v_mfma_f32_16x16x32_bf16 v[74:77], v[168:171], v[216:219], v[74:77]
	v_mfma_f32_16x16x32_bf16 v[74:77], v[172:175], v[220:223], v[74:77]
	v_mfma_f32_16x16x32_bf16 v[82:85], v[158:161], v[216:219], v[82:85]
	v_mfma_f32_16x16x32_bf16 v[82:85], v[164:167], v[220:223], v[82:85]
	v_mfma_f32_16x16x32_bf16 v[118:121], v[176:179], v[192:195], v[118:121]
	v_mfma_f32_16x16x32_bf16 v[118:121], v[180:183], v[196:199], v[118:121]
	v_mfma_f32_16x16x32_bf16 v[110:113], v[184:187], v[192:195], v[110:113]
	v_mfma_f32_16x16x32_bf16 v[110:113], v[188:191], v[196:199], v[110:113]
	v_mfma_f32_16x16x32_bf16 v[94:97], v[184:187], v[200:203], v[94:97]
	v_mfma_f32_16x16x32_bf16 v[94:97], v[188:191], v[204:207], v[94:97]
	v_mfma_f32_16x16x32_bf16 v[102:105], v[176:179], v[200:203], v[102:105]
	v_mfma_f32_16x16x32_bf16 v[102:105], v[180:183], v[204:207], v[102:105]
	v_mfma_f32_16x16x32_bf16 v[86:89], v[176:179], v[208:211], v[86:89]
	v_mfma_f32_16x16x32_bf16 v[86:89], v[180:183], v[212:215], v[86:89]
	v_mfma_f32_16x16x32_bf16 v[78:81], v[184:187], v[208:211], v[78:81]
	v_mfma_f32_16x16x32_bf16 v[78:81], v[188:191], v[212:215], v[78:81]
	v_mfma_f32_16x16x32_bf16 v[66:69], v[184:187], v[216:219], v[66:69]
	v_mfma_f32_16x16x32_bf16 v[66:69], v[188:191], v[220:223], v[66:69]
	v_mfma_f32_16x16x32_bf16 v[70:73], v[176:179], v[216:219], v[70:73]
	v_mfma_f32_16x16x32_bf16 v[70:73], v[180:183], v[220:223], v[70:73]
	s_barrier
	s_setprio 0
	s_add_i32 s56, s42, s30
	v_lshl_add_u64 v[146:147], s[26:27], 0, v[134:135]
	s_mov_b32 m0, s56
	ds_read_b128 v[192:195], v157 offset:16384
	ds_read_b128 v[196:199], v157 offset:17408
	ds_read_b128 v[200:203], v157 offset:18432
	ds_read_b128 v[204:207], v157 offset:19456
	ds_read_b128 v[208:211], v157 offset:20480
	ds_read_b128 v[212:215], v157 offset:21504
	ds_read_b128 v[216:219], v157 offset:22528
	ds_read_b128 v[220:223], v157 offset:23552
	global_load_lds_dwordx4 v[146:147], off
	s_add_i32 m0, s56, 0x2000
	s_add_u32 s56, s26, 0x100000
	v_lshl_add_u64 v[224:225], s[26:27], 0, v[130:131]
	s_addc_u32 s57, s27, 0
	s_add_i32 s58, s43, s30
	global_load_lds_dwordx4 v[224:225], off
	v_lshl_add_u64 v[226:227], s[56:57], 0, v[134:135]
	s_mov_b32 m0, s58
	v_lshl_add_u64 v[228:229], s[28:29], 0, v[132:133]
	global_load_lds_dwordx4 v[226:227], off
	v_lshl_add_u64 v[226:227], s[56:57], 0, v[130:131]
	s_add_i32 m0, s58, 0x2000
	s_nop 0
	global_load_lds_dwordx4 v[226:227], off
	v_lshl_add_u64 v[226:227], s[28:29], 0, v[136:137]
	s_mov_b32 m0, s23
	s_nop 0
	global_load_lds_dwordx4 v[226:227], off
	s_mov_b32 m0, s33
	s_nop 0
	global_load_lds_dwordx4 v[228:229], off
	s_waitcnt vmcnt(8)
	s_waitcnt lgkmcnt(0)
	s_setprio 3
	s_barrier
; #define PG8_STAGE(bufoff, gbase, voff) do { _Pragma("unroll") for (int _i = 0; _i < 2; ++_i) \
;         __builtin_amdgcn_global_load_lds((const unsigned*)((const char*)(gbase) + (voff)[_i]), (PG8_LAS unsigned*)(lds + (bufoff) + ldsw + _i * 8192), 16, 0, 0); } while (0)
; #define PG8_LDA(dst, b, h) do { _Pragma("unroll") for (int m = 0; m < 4; ++m) _Pragma("unroll") for (int k = 0; k < 2; ++k) dst[m][k] = *(const PG8_LAS bf16x8*)(lds + PG8_SA(b, h) + aoff + m * 2048 + k * 1024); } while (0)
; #define PG8_LDB(dst, b, h) do { _Pragma("unroll") for (int n = 0; n < 2; ++n) _Pragma("unroll") for (int k = 0; k < 2; ++k) dst[n][k] = *(const PG8_LAS bf16x8*)(lds + PG8_SB(b, h) + boff + n * 2048 + k * 1024); } while (0)
; #define PG8_MMA(ai, bj, At, Bt) do { __builtin_amdgcn_s_setprio(3); _Pragma("unroll") for (int m = 0; m < 4; ++m) _Pragma("unroll") for (int n = 0; n < 2; ++n) _Pragma("unroll") for (int k = 0; k < 2; ++k) \
;         acc[ai][bj][m][n] = __builtin_amdgcn_mfma_f32_16x16x32_bf16(Bt[n][k], At[m][k], acc[ai][bj][m][n], 0, 0, 0); __builtin_amdgcn_s_setprio(0); } while (0)
; #define PG8_WAIT_V(n) asm volatile("s_waitcnt vmcnt(" #n ")" ::: "memory")
; #define PG8_WAIT_L(n) asm volatile("s_waitcnt lgkmcnt(" #n ")" ::: "memory")
; #define PG8_BAR __builtin_amdgcn_s_barrier()
; #define PG8_SCHED __builtin_amdgcn_sched_barrier(0)
; template <class Epi, class Sched, bool ALIGN_EPI = false, bool SP2 = false>
; __device__ __forceinline__ void gemm_phase(PG8_LAS unsigned char* lds, const Gemm g, const Sched& S, const Epi& E) {
;     ...
;             PG8_WAIT_V(8); PG8_WAIT_L(0); PG8_BAR; PG8_MMA(1, 0, At, B0); PG8_MMA(1, 1, At, B1); PG8_BAR; PG8_SCHED;
;             PG8_LDB(B0, 1, 0); PG8_LDB(B1, 1, 1); PG8_SCHED; PG8_LDA(At, 1, 0); PG8_STAGE(PG8_SA(0, 1), a2 + hstepA, voffA);
;             PG8_WAIT_V(8); PG8_WAIT_L(0); PG8_BAR; PG8_MMA(0, 0, At, B0); PG8_MMA(0, 1, At, B1); PG8_BAR; PG8_SCHED;
	v_mfma_f32_16x16x32_bf16 v[62:65], v[158:161], v[192:195], v[62:65]
	v_mfma_f32_16x16x32_bf16 v[62:65], v[164:167], v[196:199], v[62:65]
	v_mfma_f32_16x16x32_bf16 v[58:61], v[168:171], v[192:195], v[58:61]
	v_mfma_f32_16x16x32_bf16 v[58:61], v[172:175], v[196:199], v[58:61]
	v_mfma_f32_16x16x32_bf16 v[42:45], v[168:171], v[200:203], v[42:45]
	v_mfma_f32_16x16x32_bf16 v[42:45], v[172:175], v[204:207], v[42:45]
	v_mfma_f32_16x16x32_bf16 v[50:53], v[158:161], v[200:203], v[50:53]
	v_mfma_f32_16x16x32_bf16 v[50:53], v[164:167], v[204:207], v[50:53]
	v_mfma_f32_16x16x32_bf16 v[34:37], v[158:161], v[208:211], v[34:37]
	v_mfma_f32_16x16x32_bf16 v[34:37], v[164:167], v[212:215], v[34:37]
	v_mfma_f32_16x16x32_bf16 v[26:29], v[168:171], v[208:211], v[26:29]
	v_mfma_f32_16x16x32_bf16 v[26:29], v[172:175], v[212:215], v[26:29]
	v_mfma_f32_16x16x32_bf16 v[10:13], v[168:171], v[216:219], v[10:13]
	v_mfma_f32_16x16x32_bf16 v[10:13], v[172:175], v[220:223], v[10:13]
	v_mfma_f32_16x16x32_bf16 v[14:17], v[158:161], v[216:219], v[14:17]
	v_mfma_f32_16x16x32_bf16 v[14:17], v[164:167], v[220:223], v[14:17]
	v_mfma_f32_16x16x32_bf16 v[54:57], v[176:179], v[192:195], v[54:57]
	v_mfma_f32_16x16x32_bf16 v[54:57], v[180:183], v[196:199], v[54:57]
	v_mfma_f32_16x16x32_bf16 v[46:49], v[184:187], v[192:195], v[46:49]
	v_mfma_f32_16x16x32_bf16 v[46:49], v[188:191], v[196:199], v[46:49]
	v_mfma_f32_16x16x32_bf16 v[30:33], v[184:187], v[200:203], v[30:33]
	v_mfma_f32_16x16x32_bf16 v[30:33], v[188:191], v[204:207], v[30:33]
	v_mfma_f32_16x16x32_bf16 v[38:41], v[176:179], v[200:203], v[38:41]
	v_mfma_f32_16x16x32_bf16 v[38:41], v[180:183], v[204:207], v[38:41]
	v_mfma_f32_16x16x32_bf16 v[22:25], v[176:179], v[208:211], v[22:25]
	v_mfma_f32_16x16x32_bf16 v[22:25], v[180:183], v[212:215], v[22:25]
	v_mfma_f32_16x16x32_bf16 v[18:21], v[184:187], v[208:211], v[18:21]
	v_mfma_f32_16x16x32_bf16 v[18:21], v[188:191], v[212:215], v[18:21]
	v_mfma_f32_16x16x32_bf16 v[2:5], v[184:187], v[216:219], v[2:5]
	v_mfma_f32_16x16x32_bf16 v[2:5], v[188:191], v[220:223], v[2:5]
	v_mfma_f32_16x16x32_bf16 v[6:9], v[176:179], v[216:219], v[6:9]
	v_mfma_f32_16x16x32_bf16 v[6:9], v[180:183], v[220:223], v[6:9]
	s_barrier
	s_setprio 0
	s_add_i32 s56, 0, 0x18000
	v_add_u32_e32 v148, s56, v151
	s_add_i32 s57, 0, 0x1c000
	ds_read_b128 v[158:161], v148
	ds_read_b128 v[164:167], v148 offset:1024
	ds_read_b128 v[168:171], v148 offset:2048
	ds_read_b128 v[172:175], v148 offset:3072
	v_add_u32_e32 v148, s57, v151
	ds_read_b128 v[176:179], v148
	ds_read_b128 v[180:183], v148 offset:1024
	ds_read_b128 v[184:187], v148 offset:2048
	ds_read_b128 v[188:191], v148 offset:3072
	s_add_u32 s28, s28, 0x100000
	s_addc_u32 s29, s29, 0
	s_mov_b32 m0, s36
	v_lshl_add_u64 v[230:231], s[28:29], 0, v[136:137]
	ds_read_b128 v[192:195], v157 offset:32768
	ds_read_b128 v[196:199], v157 offset:33792
	ds_read_b128 v[200:203], v157 offset:34816
	ds_read_b128 v[204:207], v157 offset:35840
	ds_read_b128 v[208:211], v157 offset:36864
	ds_read_b128 v[212:215], v157 offset:37888
	ds_read_b128 v[216:219], v157 offset:38912
	ds_read_b128 v[220:223], v157 offset:39936
	global_load_lds_dwordx4 v[230:231], off
	v_lshl_add_u64 v[230:231], s[28:29], 0, v[132:133]
	s_mov_b32 m0, s37
	s_nop 0
	global_load_lds_dwordx4 v[230:231], off
	s_waitcnt vmcnt(8)
	s_waitcnt lgkmcnt(0)
	s_setprio 3
	s_barrier
	v_mfma_f32_16x16x32_bf16 v[126:129], v[158:161], v[192:195], v[126:129]
	v_mfma_f32_16x16x32_bf16 v[126:129], v[164:167], v[196:199], v[126:129]
	v_mfma_f32_16x16x32_bf16 v[122:125], v[168:171], v[192:195], v[122:125]
	v_mfma_f32_16x16x32_bf16 v[122:125], v[172:175], v[196:199], v[122:125]
	v_mfma_f32_16x16x32_bf16 v[106:109], v[168:171], v[200:203], v[106:109]
	v_mfma_f32_16x16x32_bf16 v[106:109], v[172:175], v[204:207], v[106:109]
	v_mfma_f32_16x16x32_bf16 v[114:117], v[158:161], v[200:203], v[114:117]
	v_mfma_f32_16x16x32_bf16 v[114:117], v[164:167], v[204:207], v[114:117]
	v_mfma_f32_16x16x32_bf16 v[98:101], v[158:161], v[208:211], v[98:101]
	v_mfma_f32_16x16x32_bf16 v[98:101], v[164:167], v[212:215], v[98:101]
	v_mfma_f32_16x16x32_bf16 v[90:93], v[168:171], v[208:211], v[90:93]
	v_mfma_f32_16x16x32_bf16 v[90:93], v[172:175], v[212:215], v[90:93]
	v_mfma_f32_16x16x32_bf16 v[74:77], v[168:171], v[216:219], v[74:77]
	v_mfma_f32_16x16x32_bf16 v[74:77], v[172:175], v[220:223], v[74:77]
	v_mfma_f32_16x16x32_bf16 v[82:85], v[158:161], v[216:219], v[82:85]
	v_mfma_f32_16x16x32_bf16 v[82:85], v[164:167], v[220:223], v[82:85]
	v_mfma_f32_16x16x32_bf16 v[118:121], v[176:179], v[192:195], v[118:121]
	v_mfma_f32_16x16x32_bf16 v[118:121], v[180:183], v[196:199], v[118:121]
	v_mfma_f32_16x16x32_bf16 v[110:113], v[184:187], v[192:195], v[110:113]
	v_mfma_f32_16x16x32_bf16 v[110:113], v[188:191], v[196:199], v[110:113]
	v_mfma_f32_16x16x32_bf16 v[94:97], v[184:187], v[200:203], v[94:97]
	v_mfma_f32_16x16x32_bf16 v[94:97], v[188:191], v[204:207], v[94:97]
	v_mfma_f32_16x16x32_bf16 v[102:105], v[176:179], v[200:203], v[102:105]
	v_mfma_f32_16x16x32_bf16 v[102:105], v[180:183], v[204:207], v[102:105]
	v_mfma_f32_16x16x32_bf16 v[86:89], v[176:179], v[208:211], v[86:89]
	v_mfma_f32_16x16x32_bf16 v[86:89], v[180:183], v[212:215], v[86:89]
	v_mfma_f32_16x16x32_bf16 v[78:81], v[184:187], v[208:211], v[78:81]
	v_mfma_f32_16x16x32_bf16 v[78:81], v[188:191], v[212:215], v[78:81]
	v_mfma_f32_16x16x32_bf16 v[66:69], v[184:187], v[216:219], v[66:69]
	v_mfma_f32_16x16x32_bf16 v[66:69], v[188:191], v[220:223], v[66:69]
	v_mfma_f32_16x16x32_bf16 v[70:73], v[176:179], v[216:219], v[70:73]
	v_mfma_f32_16x16x32_bf16 v[70:73], v[180:183], v[220:223], v[70:73]
	s_barrier
; #define PG8_STAGE(bufoff, gbase, voff) do { _Pragma("unroll") for (int _i = 0; _i < 2; ++_i) \
;         __builtin_amdgcn_global_load_lds((const unsigned*)((const char*)(gbase) + (voff)[_i]), (PG8_LAS unsigned*)(lds + (bufoff) + ldsw + _i * 8192), 16, 0, 0); } while (0)
; #define PG8_LDA(dst, b, h) do { _Pragma("unroll") for (int m = 0; m < 4; ++m) _Pragma("unroll") for (int k = 0; k < 2; ++k) dst[m][k] = *(const PG8_LAS bf16x8*)(lds + PG8_SA(b, h) + aoff + m * 2048 + k * 1024); } while (0)
; #define PG8_MMA(ai, bj, At, Bt) do { __builtin_amdgcn_s_setprio(3); _Pragma("unroll") for (int m = 0; m < 4; ++m) _Pragma("unroll") for (int n = 0; n < 2; ++n) _Pragma("unroll") for (int k = 0; k < 2; ++k) \
;         acc[ai][bj][m][n] = __builtin_amdgcn_mfma_f32_16x16x32_bf16(Bt[n][k], At[m][k], acc[ai][bj][m][n], 0, 0, 0); __builtin_amdgcn_s_setprio(0); } while (0)
; #define PG8_WAIT_V(n) asm volatile("s_waitcnt vmcnt(" #n ")" ::: "memory")
; #define PG8_WAIT_L(n) asm volatile("s_waitcnt lgkmcnt(" #n ")" ::: "memory")
; #define PG8_BAR __builtin_amdgcn_s_barrier()
; #define PG8_SCHED __builtin_amdgcn_sched_barrier(0)
; template <class Epi, class Sched, bool ALIGN_EPI = false, bool SP2 = false>
; __device__ __forceinline__ void gemm_phase(PG8_LAS unsigned char* lds, const Gemm g, const Sched& S, const Epi& E) {
;     ...
;             PG8_LDA(At, 1, 1); PG8_STAGE(PG8_SB(1, 0), b3, voffB); PG8_STAGE(PG8_SB(1, 1), b3 + hstepB, voffB); PG8_STAGE(PG8_SA(1, 0), a3, voffA);
;             PG8_WAIT_V(8); PG8_WAIT_L(0); PG8_BAR; PG8_MMA(1, 0, At, B0); PG8_MMA(1, 1, At, B1); PG8_BAR; PG8_SCHED;
	s_setprio 0
	s_add_i32 s28, s56, s30
	v_lshl_add_u64 v[146:147], v[146:147], 0, s[12:13]
	s_mov_b32 m0, s28
	ds_read_b128 v[192:195], v157 offset:49152
	ds_read_b128 v[196:199], v157 offset:50176
	ds_read_b128 v[200:203], v157 offset:51200
	ds_read_b128 v[204:207], v157 offset:52224
	ds_read_b128 v[208:211], v157 offset:53248
	ds_read_b128 v[212:215], v157 offset:54272
	ds_read_b128 v[216:219], v157 offset:55296
	ds_read_b128 v[220:223], v157 offset:56320
	global_load_lds_dwordx4 v[146:147], off
	s_add_i32 m0, s28, 0x2000
	s_add_u32 s26, s26, 0x100080
	v_lshl_add_u64 v[146:147], v[224:225], 0, s[12:13]
	s_addc_u32 s27, s27, 0
	s_add_i32 s28, s57, s30
	global_load_lds_dwordx4 v[146:147], off
	v_lshl_add_u64 v[146:147], s[26:27], 0, v[134:135]
	s_mov_b32 m0, s28
	s_nop 0
	global_load_lds_dwordx4 v[146:147], off
	v_lshl_add_u64 v[146:147], s[26:27], 0, v[130:131]
	s_add_i32 m0, s28, 0x2000
	s_nop 0
	global_load_lds_dwordx4 v[146:147], off
	v_lshl_add_u64 v[146:147], v[226:227], 0, s[12:13]
	s_mov_b32 m0, s39
	s_nop 0
	global_load_lds_dwordx4 v[146:147], off
	v_lshl_add_u64 v[146:147], v[228:229], 0, s[12:13]
	s_mov_b32 m0, s40
	s_nop 0
	global_load_lds_dwordx4 v[146:147], off
	s_waitcnt vmcnt(8)
	s_waitcnt lgkmcnt(0)
	s_setprio 3
	s_barrier
	v_mfma_f32_16x16x32_bf16 v[62:65], v[158:161], v[192:195], v[62:65]
	v_mfma_f32_16x16x32_bf16 v[62:65], v[164:167], v[196:199], v[62:65]
	v_mfma_f32_16x16x32_bf16 v[58:61], v[168:171], v[192:195], v[58:61]
	v_mfma_f32_16x16x32_bf16 v[58:61], v[172:175], v[196:199], v[58:61]
	v_mfma_f32_16x16x32_bf16 v[42:45], v[168:171], v[200:203], v[42:45]
	v_mfma_f32_16x16x32_bf16 v[42:45], v[172:175], v[204:207], v[42:45]
	v_mfma_f32_16x16x32_bf16 v[50:53], v[158:161], v[200:203], v[50:53]
	v_mfma_f32_16x16x32_bf16 v[50:53], v[164:167], v[204:207], v[50:53]
	v_mfma_f32_16x16x32_bf16 v[34:37], v[158:161], v[208:211], v[34:37]
	v_mfma_f32_16x16x32_bf16 v[34:37], v[164:167], v[212:215], v[34:37]
	v_mfma_f32_16x16x32_bf16 v[26:29], v[168:171], v[208:211], v[26:29]
	v_mfma_f32_16x16x32_bf16 v[26:29], v[172:175], v[212:215], v[26:29]
	v_mfma_f32_16x16x32_bf16 v[10:13], v[168:171], v[216:219], v[10:13]
	v_mfma_f32_16x16x32_bf16 v[10:13], v[172:175], v[220:223], v[10:13]
	v_mfma_f32_16x16x32_bf16 v[14:17], v[158:161], v[216:219], v[14:17]
	v_mfma_f32_16x16x32_bf16 v[14:17], v[164:167], v[220:223], v[14:17]
	v_mfma_f32_16x16x32_bf16 v[54:57], v[176:179], v[192:195], v[54:57]
	v_mfma_f32_16x16x32_bf16 v[54:57], v[180:183], v[196:199], v[54:57]
	v_mfma_f32_16x16x32_bf16 v[46:49], v[184:187], v[192:195], v[46:49]
	v_mfma_f32_16x16x32_bf16 v[46:49], v[188:191], v[196:199], v[46:49]
	v_mfma_f32_16x16x32_bf16 v[30:33], v[184:187], v[200:203], v[30:33]
	v_mfma_f32_16x16x32_bf16 v[30:33], v[188:191], v[204:207], v[30:33]
	v_mfma_f32_16x16x32_bf16 v[38:41], v[176:179], v[200:203], v[38:41]
	v_mfma_f32_16x16x32_bf16 v[38:41], v[180:183], v[204:207], v[38:41]
	v_mfma_f32_16x16x32_bf16 v[22:25], v[176:179], v[208:211], v[22:25]
	v_mfma_f32_16x16x32_bf16 v[22:25], v[180:183], v[212:215], v[22:25]
	v_mfma_f32_16x16x32_bf16 v[18:21], v[184:187], v[208:211], v[18:21]
	v_mfma_f32_16x16x32_bf16 v[18:21], v[188:191], v[212:215], v[18:21]
	v_mfma_f32_16x16x32_bf16 v[2:5], v[184:187], v[216:219], v[2:5]
	v_mfma_f32_16x16x32_bf16 v[2:5], v[188:191], v[220:223], v[2:5]
	v_mfma_f32_16x16x32_bf16 v[6:9], v[176:179], v[216:219], v[6:9]
	v_mfma_f32_16x16x32_bf16 v[6:9], v[180:183], v[220:223], v[6:9]
	s_barrier
	s_setprio 0
	s_add_i32 s55, s55, 2
	s_add_u32 s24, s24, 0x100
	s_addc_u32 s25, s25, 0
	s_add_u32 s53, s53, 0x100
	s_addc_u32 s54, s54, 0
	s_cmp_gt_u32 s55, 61
	s_cbranch_scc0 .LBB0_908
	s_and_b64 vcc, exec, s[0:1]
	s_cbranch_vccz .LBB0_911
	s_barrier

; #define PG8_STAGE(bufoff, gbase, voff) do { _Pragma("unroll") for (int _i = 0; _i < 2; ++_i) \
;         __builtin_amdgcn_global_load_lds((const unsigned*)((const char*)(gbase) + (voff)[_i]), (PG8_LAS unsigned*)(lds + (bufoff) + ldsw + _i * 8192), 16, 0, 0); } while (0)
; #define PG8_LDA(dst, b, h) do { _Pragma("unroll") for (int m = 0; m < 4; ++m) _Pragma("unroll") for (int k = 0; k < 2; ++k) dst[m][k] = *(const PG8_LAS bf16x8*)(lds + PG8_SA(b, h) + aoff + m * 2048 + k * 1024); } while (0)
; #define PG8_LDB(dst, b, h) do { _Pragma("unroll") for (int n = 0; n < 2; ++n) _Pragma("unroll") for (int k = 0; k < 2; ++k) dst[n][k] = *(const PG8_LAS bf16x8*)(lds + PG8_SB(b, h) + boff + n * 2048 + k * 1024); } while (0)
; #define PG8_MMA(ai, bj, At, Bt) do { __builtin_amdgcn_s_setprio(3); _Pragma("unroll") for (int m = 0; m < 4; ++m) _Pragma("unroll") for (int n = 0; n < 2; ++n) _Pragma("unroll") for (int k = 0; k < 2; ++k) \
;         acc[ai][bj][m][n] = __builtin_amdgcn_mfma_f32_16x16x32_bf16(Bt[n][k], At[m][k], acc[ai][bj][m][n], 0, 0, 0); __builtin_amdgcn_s_setprio(0); } while (0)
; #define PG8_WAIT_V(n) asm volatile("s_waitcnt vmcnt(" #n ")" ::: "memory")
; template <class Epi, class Sched, bool ALIGN_EPI = false, bool SP2 = false>
; __device__ __forceinline__ void gemm_phase(PG8_LAS unsigned char* lds, const Gemm g, const Sched& S, const Epi& E) {
;     ...
;             const bool last = (t == nt - 2);
;             const char* a1 = cA + (size_t)(t + 1) * kstep;
;             const char* a2 = last ? nA : cA + (size_t)(t + 2) * kstep; const char* b2 = last ? nB : cB + (size_t)(t + 2) * kstep;
;             const char* a3 = a2 + kstep; const char* b3 = b2 + kstep;
;             if (last && has_next) S.a_ready(nxt);
;             if constexpr (Epi::MIDK) { if (t == E.midk_step(nt)) E.midk(acc, cur, wr, wc, fr, fq); }
;             if constexpr (SP2) {
;             PG8_LDB(B0, 0, 0); PG8_LDB(B1, 0, 1); PG8_SCHED; PG8_LDA(At, 0, 0); PG8_STAGE(PG8_SA(1, 1), a1 + hstepA, voffA);
;             PG8_WAIT_V(8); PG8_WAIT_L(0); PG8_BAR; PG8_MMA(0, 0, At, B0); PG8_MMA(0, 1, At, B1); PG8_BAR; PG8_SCHED;
;             PG8_LDA(At, 0, 1); PG8_STAGE(PG8_SB(0, 0), b2, voffB); PG8_STAGE(PG8_SB(0, 1), b2 + hstepB, voffB); PG8_STAGE(PG8_SA(0, 0), a2, voffA);
;             PG8_WAIT_V(8); PG8_WAIT_L(0); PG8_BAR; PG8_MMA(1, 0, At, B0); PG8_MMA(1, 1, At, B1); PG8_BAR; PG8_SCHED;
.LBB0_975:
	v_add_u32_e32 v144, s46, v206
	v_add_u32_e32 v160, s47, v206
	s_add_u32 s28, s2, s12
	ds_read_b128 v[132:135], v144
	ds_read_b128 v[136:139], v144 offset:1024
	ds_read_b128 v[140:143], v144 offset:2048
	ds_read_b128 v[144:147], v144 offset:3072
	ds_read_b128 v[148:151], v160
	ds_read_b128 v[152:155], v160 offset:1024
	ds_read_b128 v[156:159], v160 offset:2048
	ds_read_b128 v[160:163], v160 offset:3072
	s_addc_u32 s29, s3, s13
	s_add_u32 s28, s28, 0x21500100
	s_addc_u32 s29, s29, 0
	s_add_u32 s81, s44, s12
	s_addc_u32 s82, s45, s13
	s_cmpk_eq_i32 s12, 0x5500
	s_cselect_b32 s31, s1, s29
	s_cselect_b32 s30, s0, s28
	s_cselect_b32 s29, s11, s82
	s_cselect_b32 s28, s10, s81
	s_mov_b32 m0, s71
	v_lshl_add_u64 v[234:235], v[2:3], 0, s[12:13]
	ds_read_b128 v[164:167], v207
	ds_read_b128 v[168:171], v207 offset:1024
	ds_read_b128 v[210:213], v207 offset:2048
	ds_read_b128 v[214:217], v207 offset:3072
	ds_read_b128 v[218:221], v207 offset:4096
	ds_read_b128 v[222:225], v207 offset:5120
	ds_read_b128 v[226:229], v207 offset:6144
	ds_read_b128 v[230:233], v207 offset:7168
	global_load_lds_dwordx4 v[234:235], off
	v_lshl_add_u64 v[234:235], v[200:201], 0, s[12:13]
	s_mov_b32 m0, s72
	s_nop 0
	global_load_lds_dwordx4 v[234:235], off
	s_waitcnt vmcnt(8)
	s_waitcnt lgkmcnt(0)
	s_setprio 3
	s_barrier
	v_mfma_f32_16x16x32_bf16 v[128:131], v[132:135], v[164:167], v[128:131]
	v_mfma_f32_16x16x32_bf16 v[128:131], v[136:139], v[168:171], v[128:131]
	v_mfma_f32_16x16x32_bf16 v[124:127], v[140:143], v[164:167], v[124:127]
	v_mfma_f32_16x16x32_bf16 v[124:127], v[144:147], v[168:171], v[124:127]
	v_mfma_f32_16x16x32_bf16 v[96:99], v[140:143], v[210:213], v[96:99]
	v_mfma_f32_16x16x32_bf16 v[96:99], v[144:147], v[214:217], v[96:99]
	v_mfma_f32_16x16x32_bf16 v[100:103], v[132:135], v[210:213], v[100:103]
	v_mfma_f32_16x16x32_bf16 v[100:103], v[136:139], v[214:217], v[100:103]
	v_mfma_f32_16x16x32_bf16 v[112:115], v[132:135], v[218:221], v[112:115]
	v_mfma_f32_16x16x32_bf16 v[112:115], v[136:139], v[222:225], v[112:115]
	v_mfma_f32_16x16x32_bf16 v[108:111], v[140:143], v[218:221], v[108:111]
	v_mfma_f32_16x16x32_bf16 v[108:111], v[144:147], v[222:225], v[108:111]
	v_mfma_f32_16x16x32_bf16 v[76:79], v[140:143], v[226:229], v[76:79]
	v_mfma_f32_16x16x32_bf16 v[76:79], v[144:147], v[230:233], v[76:79]
	v_mfma_f32_16x16x32_bf16 v[80:83], v[132:135], v[226:229], v[80:83]
	v_mfma_f32_16x16x32_bf16 v[80:83], v[136:139], v[230:233], v[80:83]
	v_mfma_f32_16x16x32_bf16 v[120:123], v[148:151], v[164:167], v[120:123]
	v_mfma_f32_16x16x32_bf16 v[120:123], v[152:155], v[168:171], v[120:123]
	v_mfma_f32_16x16x32_bf16 v[116:119], v[156:159], v[164:167], v[116:119]
	v_mfma_f32_16x16x32_bf16 v[116:119], v[160:163], v[168:171], v[116:119]
	v_mfma_f32_16x16x32_bf16 v[88:91], v[156:159], v[210:213], v[88:91]
	v_mfma_f32_16x16x32_bf16 v[88:91], v[160:163], v[214:217], v[88:91]
	v_mfma_f32_16x16x32_bf16 v[92:95], v[148:151], v[210:213], v[92:95]
	v_mfma_f32_16x16x32_bf16 v[92:95], v[152:155], v[214:217], v[92:95]
	v_mfma_f32_16x16x32_bf16 v[104:107], v[148:151], v[218:221], v[104:107]
	v_mfma_f32_16x16x32_bf16 v[104:107], v[152:155], v[222:225], v[104:107]
	v_mfma_f32_16x16x32_bf16 v[84:87], v[156:159], v[218:221], v[84:87]
	v_mfma_f32_16x16x32_bf16 v[84:87], v[160:163], v[222:225], v[84:87]
	v_mfma_f32_16x16x32_bf16 v[68:71], v[156:159], v[226:229], v[68:71]
	v_mfma_f32_16x16x32_bf16 v[68:71], v[160:163], v[230:233], v[68:71]
	v_mfma_f32_16x16x32_bf16 v[72:75], v[148:151], v[226:229], v[72:75]
	v_mfma_f32_16x16x32_bf16 v[72:75], v[152:155], v[230:233], v[72:75]
	s_barrier
	s_setprio 0
	s_mov_b32 m0, s73
	v_lshl_add_u64 v[234:235], s[28:29], 0, v[174:175]
	s_add_u32 s82, s28, 0x2b0000
	ds_read_b128 v[164:167], v207 offset:16384
	ds_read_b128 v[168:171], v207 offset:17408
	ds_read_b128 v[210:213], v207 offset:18432
	ds_read_b128 v[214:217], v207 offset:19456
	ds_read_b128 v[218:221], v207 offset:20480
	ds_read_b128 v[222:225], v207 offset:21504
	ds_read_b128 v[226:229], v207 offset:22528
	ds_read_b128 v[230:233], v207 offset:23552
	global_load_lds_dwordx4 v[234:235], off
	v_lshl_add_u64 v[236:237], s[28:29], 0, v[178:179]
	s_mov_b32 m0, s74
	s_addc_u32 s83, s29, 0
	global_load_lds_dwordx4 v[236:237], off
	v_lshl_add_u64 v[238:239], s[82:83], 0, v[174:175]
	s_mov_b32 m0, s75
	v_lshl_add_u64 v[240:241], s[30:31], 0, v[176:177]
	global_load_lds_dwordx4 v[238:239], off
	v_lshl_add_u64 v[238:239], s[82:83], 0, v[178:179]
	s_mov_b32 m0, s76
	s_nop 0
	global_load_lds_dwordx4 v[238:239], off
	v_lshl_add_u64 v[238:239], s[30:31], 0, v[172:173]
	s_mov_b32 m0, s42
	s_nop 0
	global_load_lds_dwordx4 v[238:239], off
	s_mov_b32 m0, s54
	s_nop 0
	global_load_lds_dwordx4 v[240:241], off
	s_waitcnt vmcnt(8)
	s_waitcnt lgkmcnt(0)
	s_setprio 3
	s_barrier
; #define PG8_STAGE(bufoff, gbase, voff) do { _Pragma("unroll") for (int _i = 0; _i < 2; ++_i) \
;         __builtin_amdgcn_global_load_lds((const unsigned*)((const char*)(gbase) + (voff)[_i]), (PG8_LAS unsigned*)(lds + (bufoff) + ldsw + _i * 8192), 16, 0, 0); } while (0)
; #define PG8_LDA(dst, b, h) do { _Pragma("unroll") for (int m = 0; m < 4; ++m) _Pragma("unroll") for (int k = 0; k < 2; ++k) dst[m][k] = *(const PG8_LAS bf16x8*)(lds + PG8_SA(b, h) + aoff + m * 2048 + k * 1024); } while (0)
; #define PG8_LDB(dst, b, h) do { _Pragma("unroll") for (int n = 0; n < 2; ++n) _Pragma("unroll") for (int k = 0; k < 2; ++k) dst[n][k] = *(const PG8_LAS bf16x8*)(lds + PG8_SB(b, h) + boff + n * 2048 + k * 1024); } while (0)
; #define PG8_MMA(ai, bj, At, Bt) do { __builtin_amdgcn_s_setprio(3); _Pragma("unroll") for (int m = 0; m < 4; ++m) _Pragma("unroll") for (int n = 0; n < 2; ++n) _Pragma("unroll") for (int k = 0; k < 2; ++k) \
;         acc[ai][bj][m][n] = __builtin_amdgcn_mfma_f32_16x16x32_bf16(Bt[n][k], At[m][k], acc[ai][bj][m][n], 0, 0, 0); __builtin_amdgcn_s_setprio(0); } while (0)
; #define PG8_WAIT_V(n) asm volatile("s_waitcnt vmcnt(" #n ")" ::: "memory")
; #define PG8_WAIT_L(n) asm volatile("s_waitcnt lgkmcnt(" #n ")" ::: "memory")
; #define PG8_BAR __builtin_amdgcn_s_barrier()
; #define PG8_SCHED __builtin_amdgcn_sched_barrier(0)
; template <class Epi, class Sched, bool ALIGN_EPI = false, bool SP2 = false>
; __device__ __forceinline__ void gemm_phase(PG8_LAS unsigned char* lds, const Gemm g, const Sched& S, const Epi& E) {
;     ...
;             PG8_WAIT_V(8); PG8_WAIT_L(0); PG8_BAR; PG8_MMA(1, 0, At, B0); PG8_MMA(1, 1, At, B1); PG8_BAR; PG8_SCHED;
;             PG8_LDB(B0, 1, 0); PG8_LDB(B1, 1, 1); PG8_SCHED; PG8_LDA(At, 1, 0); PG8_STAGE(PG8_SA(0, 1), a2 + hstepA, voffA);
;             PG8_WAIT_V(8); PG8_WAIT_L(0); PG8_BAR; PG8_MMA(0, 0, At, B0); PG8_MMA(0, 1, At, B1); PG8_BAR; PG8_SCHED;
	v_mfma_f32_16x16x32_bf16 v[64:67], v[132:135], v[164:167], v[64:67]
	v_mfma_f32_16x16x32_bf16 v[64:67], v[136:139], v[168:171], v[64:67]
	v_mfma_f32_16x16x32_bf16 v[60:63], v[140:143], v[164:167], v[60:63]
	v_mfma_f32_16x16x32_bf16 v[60:63], v[144:147], v[168:171], v[60:63]
	v_mfma_f32_16x16x32_bf16 v[44:47], v[140:143], v[210:213], v[44:47]
	v_mfma_f32_16x16x32_bf16 v[44:47], v[144:147], v[214:217], v[44:47]
	v_mfma_f32_16x16x32_bf16 v[48:51], v[132:135], v[210:213], v[48:51]
	v_mfma_f32_16x16x32_bf16 v[48:51], v[136:139], v[214:217], v[48:51]
	v_mfma_f32_16x16x32_bf16 v[32:35], v[132:135], v[218:221], v[32:35]
	v_mfma_f32_16x16x32_bf16 v[32:35], v[136:139], v[222:225], v[32:35]
	v_mfma_f32_16x16x32_bf16 v[28:31], v[140:143], v[218:221], v[28:31]
	v_mfma_f32_16x16x32_bf16 v[28:31], v[144:147], v[222:225], v[28:31]
	v_mfma_f32_16x16x32_bf16 v[12:15], v[140:143], v[226:229], v[12:15]
	v_mfma_f32_16x16x32_bf16 v[12:15], v[144:147], v[230:233], v[12:15]
	v_mfma_f32_16x16x32_bf16 v[16:19], v[132:135], v[226:229], v[16:19]
	v_mfma_f32_16x16x32_bf16 v[16:19], v[136:139], v[230:233], v[16:19]
	v_mfma_f32_16x16x32_bf16 v[56:59], v[148:151], v[164:167], v[56:59]
	v_mfma_f32_16x16x32_bf16 v[56:59], v[152:155], v[168:171], v[56:59]
	v_mfma_f32_16x16x32_bf16 v[52:55], v[156:159], v[164:167], v[52:55]
	v_mfma_f32_16x16x32_bf16 v[52:55], v[160:163], v[168:171], v[52:55]
	v_mfma_f32_16x16x32_bf16 v[36:39], v[156:159], v[210:213], v[36:39]
	v_mfma_f32_16x16x32_bf16 v[36:39], v[160:163], v[214:217], v[36:39]
	v_mfma_f32_16x16x32_bf16 v[40:43], v[148:151], v[210:213], v[40:43]
	v_mfma_f32_16x16x32_bf16 v[40:43], v[152:155], v[214:217], v[40:43]
	v_mfma_f32_16x16x32_bf16 v[24:27], v[148:151], v[218:221], v[24:27]
	v_mfma_f32_16x16x32_bf16 v[24:27], v[152:155], v[222:225], v[24:27]
	v_mfma_f32_16x16x32_bf16 v[20:23], v[156:159], v[218:221], v[20:23]
	v_mfma_f32_16x16x32_bf16 v[20:23], v[160:163], v[222:225], v[20:23]
	v_mfma_f32_16x16x32_bf16 v[4:7], v[156:159], v[226:229], v[4:7]
	v_mfma_f32_16x16x32_bf16 v[4:7], v[160:163], v[230:233], v[4:7]
	v_mfma_f32_16x16x32_bf16 v[8:11], v[148:151], v[226:229], v[8:11]
	v_mfma_f32_16x16x32_bf16 v[8:11], v[152:155], v[230:233], v[8:11]
	s_barrier
	s_setprio 0
	v_add_u32_e32 v144, s52, v206
	v_add_u32_e32 v160, s53, v206
	ds_read_b128 v[132:135], v144
	ds_read_b128 v[136:139], v144 offset:1024
	ds_read_b128 v[140:143], v144 offset:2048
	ds_read_b128 v[144:147], v144 offset:3072
	ds_read_b128 v[148:151], v160
	ds_read_b128 v[152:155], v160 offset:1024
	ds_read_b128 v[156:159], v160 offset:2048
	ds_read_b128 v[160:163], v160 offset:3072
	s_add_u32 s30, s30, 0x2b0000
	s_addc_u32 s31, s31, 0
	s_mov_b32 m0, s55
	v_lshl_add_u64 v[242:243], s[30:31], 0, v[172:173]
	ds_read_b128 v[164:167], v207 offset:32768
	ds_read_b128 v[168:171], v207 offset:33792
	ds_read_b128 v[210:213], v207 offset:34816
	ds_read_b128 v[214:217], v207 offset:35840
	ds_read_b128 v[218:221], v207 offset:36864
	ds_read_b128 v[222:225], v207 offset:37888
	ds_read_b128 v[226:229], v207 offset:38912
	ds_read_b128 v[230:233], v207 offset:39936
	global_load_lds_dwordx4 v[242:243], off
	v_lshl_add_u64 v[242:243], s[30:31], 0, v[176:177]
	s_mov_b32 m0, s56
	s_nop 0
	global_load_lds_dwordx4 v[242:243], off
	s_waitcnt vmcnt(8)
	s_waitcnt lgkmcnt(0)
	s_setprio 3
	s_barrier
	v_mfma_f32_16x16x32_bf16 v[128:131], v[132:135], v[164:167], v[128:131]
	v_mfma_f32_16x16x32_bf16 v[128:131], v[136:139], v[168:171], v[128:131]
	v_mfma_f32_16x16x32_bf16 v[124:127], v[140:143], v[164:167], v[124:127]
	v_mfma_f32_16x16x32_bf16 v[124:127], v[144:147], v[168:171], v[124:127]
	v_mfma_f32_16x16x32_bf16 v[96:99], v[140:143], v[210:213], v[96:99]
	v_mfma_f32_16x16x32_bf16 v[96:99], v[144:147], v[214:217], v[96:99]
	v_mfma_f32_16x16x32_bf16 v[100:103], v[132:135], v[210:213], v[100:103]
	v_mfma_f32_16x16x32_bf16 v[100:103], v[136:139], v[214:217], v[100:103]
	v_mfma_f32_16x16x32_bf16 v[112:115], v[132:135], v[218:221], v[112:115]
	v_mfma_f32_16x16x32_bf16 v[112:115], v[136:139], v[222:225], v[112:115]
	v_mfma_f32_16x16x32_bf16 v[108:111], v[140:143], v[218:221], v[108:111]
	v_mfma_f32_16x16x32_bf16 v[108:111], v[144:147], v[222:225], v[108:111]
	v_mfma_f32_16x16x32_bf16 v[76:79], v[140:143], v[226:229], v[76:79]
	v_mfma_f32_16x16x32_bf16 v[76:79], v[144:147], v[230:233], v[76:79]
	v_mfma_f32_16x16x32_bf16 v[80:83], v[132:135], v[226:229], v[80:83]
	v_mfma_f32_16x16x32_bf16 v[80:83], v[136:139], v[230:233], v[80:83]
	v_mfma_f32_16x16x32_bf16 v[120:123], v[148:151], v[164:167], v[120:123]
	v_mfma_f32_16x16x32_bf16 v[120:123], v[152:155], v[168:171], v[120:123]
	v_mfma_f32_16x16x32_bf16 v[116:119], v[156:159], v[164:167], v[116:119]
	v_mfma_f32_16x16x32_bf16 v[116:119], v[160:163], v[168:171], v[116:119]
	v_mfma_f32_16x16x32_bf16 v[88:91], v[156:159], v[210:213], v[88:91]
	v_mfma_f32_16x16x32_bf16 v[88:91], v[160:163], v[214:217], v[88:91]
	v_mfma_f32_16x16x32_bf16 v[92:95], v[148:151], v[210:213], v[92:95]
	v_mfma_f32_16x16x32_bf16 v[92:95], v[152:155], v[214:217], v[92:95]
	v_mfma_f32_16x16x32_bf16 v[104:107], v[148:151], v[218:221], v[104:107]
	v_mfma_f32_16x16x32_bf16 v[104:107], v[152:155], v[222:225], v[104:107]
	v_mfma_f32_16x16x32_bf16 v[84:87], v[156:159], v[218:221], v[84:87]
	v_mfma_f32_16x16x32_bf16 v[84:87], v[160:163], v[222:225], v[84:87]
	v_mfma_f32_16x16x32_bf16 v[68:71], v[156:159], v[226:229], v[68:71]
	v_mfma_f32_16x16x32_bf16 v[68:71], v[160:163], v[230:233], v[68:71]
	v_mfma_f32_16x16x32_bf16 v[72:75], v[148:151], v[226:229], v[72:75]
	v_mfma_f32_16x16x32_bf16 v[72:75], v[152:155], v[230:233], v[72:75]
	s_barrier
; #define PG8_STAGE(bufoff, gbase, voff) do { _Pragma("unroll") for (int _i = 0; _i < 2; ++_i) \
;         __builtin_amdgcn_global_load_lds((const unsigned*)((const char*)(gbase) + (voff)[_i]), (PG8_LAS unsigned*)(lds + (bufoff) + ldsw + _i * 8192), 16, 0, 0); } while (0)
; #define PG8_LDA(dst, b, h) do { _Pragma("unroll") for (int m = 0; m < 4; ++m) _Pragma("unroll") for (int k = 0; k < 2; ++k) dst[m][k] = *(const PG8_LAS bf16x8*)(lds + PG8_SA(b, h) + aoff + m * 2048 + k * 1024); } while (0)
; #define PG8_MMA(ai, bj, At, Bt) do { __builtin_amdgcn_s_setprio(3); _Pragma("unroll") for (int m = 0; m < 4; ++m) _Pragma("unroll") for (int n = 0; n < 2; ++n) _Pragma("unroll") for (int k = 0; k < 2; ++k) \
;         acc[ai][bj][m][n] = __builtin_amdgcn_mfma_f32_16x16x32_bf16(Bt[n][k], At[m][k], acc[ai][bj][m][n], 0, 0, 0); __builtin_amdgcn_s_setprio(0); } while (0)
; #define PG8_WAIT_V(n) asm volatile("s_waitcnt vmcnt(" #n ")" ::: "memory")
; #define PG8_WAIT_L(n) asm volatile("s_waitcnt lgkmcnt(" #n ")" ::: "memory")
; #define PG8_BAR __builtin_amdgcn_s_barrier()
; #define PG8_SCHED __builtin_amdgcn_sched_barrier(0)
; template <class Epi, class Sched, bool ALIGN_EPI = false, bool SP2 = false>
; __device__ __forceinline__ void gemm_phase(PG8_LAS unsigned char* lds, const Gemm g, const Sched& S, const Epi& E) {
;     ...
;             PG8_LDA(At, 1, 1); PG8_STAGE(PG8_SB(1, 0), b3, voffB); PG8_STAGE(PG8_SB(1, 1), b3 + hstepB, voffB); PG8_STAGE(PG8_SA(1, 0), a3, voffA);
;             PG8_WAIT_V(8); PG8_WAIT_L(0); PG8_BAR; PG8_MMA(1, 0, At, B0); PG8_MMA(1, 1, At, B1); PG8_BAR; PG8_SCHED;
	s_setprio 0
	s_mov_b32 m0, s77
	v_lshl_add_u64 v[234:235], v[234:235], 0, s[4:5]
	s_add_u32 s28, s28, 0x2b0080
	ds_read_b128 v[164:167], v207 offset:49152
	ds_read_b128 v[168:171], v207 offset:50176
	ds_read_b128 v[210:213], v207 offset:51200
	ds_read_b128 v[214:217], v207 offset:52224
	ds_read_b128 v[218:221], v207 offset:53248
	ds_read_b128 v[222:225], v207 offset:54272
	ds_read_b128 v[226:229], v207 offset:55296
	ds_read_b128 v[230:233], v207 offset:56320
	global_load_lds_dwordx4 v[234:235], off
	v_lshl_add_u64 v[234:235], v[236:237], 0, s[4:5]
	s_mov_b32 m0, s78
	s_addc_u32 s29, s29, 0
	global_load_lds_dwordx4 v[234:235], off
	v_lshl_add_u64 v[234:235], s[28:29], 0, v[174:175]
	s_mov_b32 m0, s79
	s_nop 0
	global_load_lds_dwordx4 v[234:235], off
	v_lshl_add_u64 v[234:235], s[28:29], 0, v[178:179]
	s_mov_b32 m0, s80
	s_nop 0
	global_load_lds_dwordx4 v[234:235], off
	v_lshl_add_u64 v[234:235], v[238:239], 0, s[4:5]
	s_mov_b32 m0, s57
	s_nop 0
	global_load_lds_dwordx4 v[234:235], off
	v_lshl_add_u64 v[234:235], v[240:241], 0, s[4:5]
	s_mov_b32 m0, s58
	s_nop 0
	global_load_lds_dwordx4 v[234:235], off
	s_waitcnt vmcnt(8)
	s_waitcnt lgkmcnt(0)
	s_setprio 3
	s_barrier
	v_mfma_f32_16x16x32_bf16 v[64:67], v[132:135], v[164:167], v[64:67]
	v_mfma_f32_16x16x32_bf16 v[64:67], v[136:139], v[168:171], v[64:67]
	v_mfma_f32_16x16x32_bf16 v[60:63], v[140:143], v[164:167], v[60:63]
	v_mfma_f32_16x16x32_bf16 v[60:63], v[144:147], v[168:171], v[60:63]
	v_mfma_f32_16x16x32_bf16 v[44:47], v[140:143], v[210:213], v[44:47]
	v_mfma_f32_16x16x32_bf16 v[44:47], v[144:147], v[214:217], v[44:47]
	v_mfma_f32_16x16x32_bf16 v[48:51], v[132:135], v[210:213], v[48:51]
	v_mfma_f32_16x16x32_bf16 v[48:51], v[136:139], v[214:217], v[48:51]
	v_mfma_f32_16x16x32_bf16 v[32:35], v[132:135], v[218:221], v[32:35]
	v_mfma_f32_16x16x32_bf16 v[32:35], v[136:139], v[222:225], v[32:35]
	v_mfma_f32_16x16x32_bf16 v[28:31], v[140:143], v[218:221], v[28:31]
	v_mfma_f32_16x16x32_bf16 v[28:31], v[144:147], v[222:225], v[28:31]
	v_mfma_f32_16x16x32_bf16 v[12:15], v[140:143], v[226:229], v[12:15]
	v_mfma_f32_16x16x32_bf16 v[12:15], v[144:147], v[230:233], v[12:15]
	v_mfma_f32_16x16x32_bf16 v[16:19], v[132:135], v[226:229], v[16:19]
	v_mfma_f32_16x16x32_bf16 v[16:19], v[136:139], v[230:233], v[16:19]
	v_mfma_f32_16x16x32_bf16 v[56:59], v[148:151], v[164:167], v[56:59]
	v_mfma_f32_16x16x32_bf16 v[56:59], v[152:155], v[168:171], v[56:59]
	v_mfma_f32_16x16x32_bf16 v[52:55], v[156:159], v[164:167], v[52:55]
	v_mfma_f32_16x16x32_bf16 v[52:55], v[160:163], v[168:171], v[52:55]
	v_mfma_f32_16x16x32_bf16 v[36:39], v[156:159], v[210:213], v[36:39]
	v_mfma_f32_16x16x32_bf16 v[36:39], v[160:163], v[214:217], v[36:39]
	v_mfma_f32_16x16x32_bf16 v[40:43], v[148:151], v[210:213], v[40:43]
	v_mfma_f32_16x16x32_bf16 v[40:43], v[152:155], v[214:217], v[40:43]
	v_mfma_f32_16x16x32_bf16 v[24:27], v[148:151], v[218:221], v[24:27]
	v_mfma_f32_16x16x32_bf16 v[24:27], v[152:155], v[222:225], v[24:27]
	v_mfma_f32_16x16x32_bf16 v[20:23], v[156:159], v[218:221], v[20:23]
	v_mfma_f32_16x16x32_bf16 v[20:23], v[160:163], v[222:225], v[20:23]
	v_mfma_f32_16x16x32_bf16 v[4:7], v[156:159], v[226:229], v[4:7]
	v_mfma_f32_16x16x32_bf16 v[4:7], v[160:163], v[230:233], v[4:7]
	v_mfma_f32_16x16x32_bf16 v[8:11], v[148:151], v[226:229], v[8:11]
	v_mfma_f32_16x16x32_bf16 v[8:11], v[152:155], v[230:233], v[8:11]
	s_barrier
	s_setprio 0
	s_add_i32 s61, s61, 2
	s_add_u32 s12, s12, 0x100
	s_addc_u32 s13, s13, 0
	s_cmpk_gt_u32 s61, 0xa9
	s_cbranch_scc1 .LBB0_978

; #define PG8_STAGE(bufoff, gbase, voff) do { _Pragma("unroll") for (int _i = 0; _i < 2; ++_i) \
;         __builtin_amdgcn_global_load_lds((const unsigned*)((const char*)(gbase) + (voff)[_i]), (PG8_LAS unsigned*)(lds + (bufoff) + ldsw + _i * 8192), 16, 0, 0); } while (0)
; #define PG8_LDA(dst, b, h) do { _Pragma("unroll") for (int m = 0; m < 4; ++m) _Pragma("unroll") for (int k = 0; k < 2; ++k) dst[m][k] = *(const PG8_LAS bf16x8*)(lds + PG8_SA(b, h) + aoff + m * 2048 + k * 1024); } while (0)
; #define PG8_LDB(dst, b, h) do { _Pragma("unroll") for (int n = 0; n < 2; ++n) _Pragma("unroll") for (int k = 0; k < 2; ++k) dst[n][k] = *(const PG8_LAS bf16x8*)(lds + PG8_SB(b, h) + boff + n * 2048 + k * 1024); } while (0)
; #define PG8_MMA(ai, bj, At, Bt) do { __builtin_amdgcn_s_setprio(3); _Pragma("unroll") for (int m = 0; m < 4; ++m) _Pragma("unroll") for (int n = 0; n < 2; ++n) _Pragma("unroll") for (int k = 0; k < 2; ++k) \
;         acc[ai][bj][m][n] = __builtin_amdgcn_mfma_f32_16x16x32_bf16(Bt[n][k], At[m][k], acc[ai][bj][m][n], 0, 0, 0); __builtin_amdgcn_s_setprio(0); } while (0)
; #define PG8_WAIT_V(n) asm volatile("s_waitcnt vmcnt(" #n ")" ::: "memory")
; template <class Epi, class Sched, bool ALIGN_EPI = false, bool SP2 = false>
; __device__ __forceinline__ void gemm_phase(PG8_LAS unsigned char* lds, const Gemm g, const Sched& S, const Epi& E) {
;     ...
;             const bool last = (t == nt - 2);
;             const char* a1 = cA + (size_t)(t + 1) * kstep;
;             const char* a2 = last ? nA : cA + (size_t)(t + 2) * kstep; const char* b2 = last ? nB : cB + (size_t)(t + 2) * kstep;
;             const char* a3 = a2 + kstep; const char* b3 = b2 + kstep;
;             if (last && has_next) S.a_ready(nxt);
;             if constexpr (Epi::MIDK) { if (t == E.midk_step(nt)) E.midk(acc, cur, wr, wc, fr, fq); }
;             if constexpr (SP2) {
;             PG8_LDB(B0, 0, 0); PG8_LDB(B1, 0, 1); PG8_SCHED; PG8_LDA(At, 0, 0); PG8_STAGE(PG8_SA(1, 1), a1 + hstepA, voffA);
;             PG8_WAIT_V(8); PG8_WAIT_L(0); PG8_BAR; PG8_MMA(0, 0, At, B0); PG8_MMA(0, 1, At, B1); PG8_BAR; PG8_SCHED;
;             PG8_LDA(At, 0, 1); PG8_STAGE(PG8_SB(0, 0), b2, voffB); PG8_STAGE(PG8_SB(0, 1), b2 + hstepB, voffB); PG8_STAGE(PG8_SA(0, 0), a2, voffA);
;             PG8_WAIT_V(8); PG8_WAIT_L(0); PG8_BAR; PG8_MMA(1, 0, At, B0); PG8_MMA(1, 1, At, B1); PG8_BAR; PG8_SCHED;
.LBB0_1018:
	v_add_u32_e32 v142, s46, v189
	v_add_u32_e32 v158, s47, v189
	s_add_u32 s40, s20, s22
	ds_read_b128 v[130:133], v142
	ds_read_b128 v[134:137], v142 offset:1024
	ds_read_b128 v[138:141], v142 offset:2048
	ds_read_b128 v[142:145], v142 offset:3072
	ds_read_b128 v[146:149], v158
	ds_read_b128 v[150:153], v158 offset:1024
	ds_read_b128 v[154:157], v158 offset:2048
	ds_read_b128 v[158:161], v158 offset:3072
	s_addc_u32 s41, s21, s23
	s_add_u32 s40, s40, 0x21500100
	s_addc_u32 s41, s41, 0
	s_add_u32 s87, s44, s22
	s_addc_u32 s88, s45, s23
	s_cmpk_eq_i32 s22, 0x5500
	s_cselect_b32 s43, s17, s41
	s_cselect_b32 s42, s16, s40
	s_cselect_b32 s41, s11, s88
	s_cselect_b32 s40, s10, s87
	s_mov_b32 m0, s77
	v_lshl_add_u64 v[186:187], v[0:1], 0, s[22:23]
	ds_read_b128 v[162:165], v180
	ds_read_b128 v[166:169], v180 offset:1024
	ds_read_b128 v[182:185], v180 offset:2048
	ds_read_b128 v[190:193], v180 offset:3072
	ds_read_b128 v[194:197], v180 offset:4096
	ds_read_b128 v[208:211], v180 offset:5120
	ds_read_b128 v[212:215], v180 offset:6144
	ds_read_b128 v[216:219], v180 offset:7168
	global_load_lds_dwordx4 v[186:187], off
	v_lshl_add_u64 v[186:187], v[170:171], 0, s[22:23]
	s_mov_b32 m0, s78
	s_nop 0
	global_load_lds_dwordx4 v[186:187], off
	s_waitcnt vmcnt(8)
	s_waitcnt lgkmcnt(0)
	s_setprio 3
	s_barrier
	v_mfma_f32_16x16x32_bf16 v[126:129], v[130:133], v[162:165], v[126:129]
	v_mfma_f32_16x16x32_bf16 v[126:129], v[134:137], v[166:169], v[126:129]
	v_mfma_f32_16x16x32_bf16 v[122:125], v[138:141], v[162:165], v[122:125]
	v_mfma_f32_16x16x32_bf16 v[122:125], v[142:145], v[166:169], v[122:125]
	v_mfma_f32_16x16x32_bf16 v[94:97], v[138:141], v[182:185], v[94:97]
	v_mfma_f32_16x16x32_bf16 v[94:97], v[142:145], v[190:193], v[94:97]
	v_mfma_f32_16x16x32_bf16 v[98:101], v[130:133], v[182:185], v[98:101]
	v_mfma_f32_16x16x32_bf16 v[98:101], v[134:137], v[190:193], v[98:101]
	v_mfma_f32_16x16x32_bf16 v[110:113], v[130:133], v[194:197], v[110:113]
	v_mfma_f32_16x16x32_bf16 v[110:113], v[134:137], v[208:211], v[110:113]
	v_mfma_f32_16x16x32_bf16 v[106:109], v[138:141], v[194:197], v[106:109]
	v_mfma_f32_16x16x32_bf16 v[106:109], v[142:145], v[208:211], v[106:109]
	v_mfma_f32_16x16x32_bf16 v[74:77], v[138:141], v[212:215], v[74:77]
	v_mfma_f32_16x16x32_bf16 v[74:77], v[142:145], v[216:219], v[74:77]
	v_mfma_f32_16x16x32_bf16 v[78:81], v[130:133], v[212:215], v[78:81]
	v_mfma_f32_16x16x32_bf16 v[78:81], v[134:137], v[216:219], v[78:81]
	v_mfma_f32_16x16x32_bf16 v[118:121], v[146:149], v[162:165], v[118:121]
	v_mfma_f32_16x16x32_bf16 v[118:121], v[150:153], v[166:169], v[118:121]
	v_mfma_f32_16x16x32_bf16 v[114:117], v[154:157], v[162:165], v[114:117]
	v_mfma_f32_16x16x32_bf16 v[114:117], v[158:161], v[166:169], v[114:117]
	v_mfma_f32_16x16x32_bf16 v[86:89], v[154:157], v[182:185], v[86:89]
	v_mfma_f32_16x16x32_bf16 v[86:89], v[158:161], v[190:193], v[86:89]
	v_mfma_f32_16x16x32_bf16 v[90:93], v[146:149], v[182:185], v[90:93]
	v_mfma_f32_16x16x32_bf16 v[90:93], v[150:153], v[190:193], v[90:93]
	v_mfma_f32_16x16x32_bf16 v[102:105], v[146:149], v[194:197], v[102:105]
	v_mfma_f32_16x16x32_bf16 v[102:105], v[150:153], v[208:211], v[102:105]
	v_mfma_f32_16x16x32_bf16 v[82:85], v[154:157], v[194:197], v[82:85]
	v_mfma_f32_16x16x32_bf16 v[82:85], v[158:161], v[208:211], v[82:85]
	v_mfma_f32_16x16x32_bf16 v[66:69], v[154:157], v[212:215], v[66:69]
	v_mfma_f32_16x16x32_bf16 v[66:69], v[158:161], v[216:219], v[66:69]
	v_mfma_f32_16x16x32_bf16 v[70:73], v[146:149], v[212:215], v[70:73]
	v_mfma_f32_16x16x32_bf16 v[70:73], v[150:153], v[216:219], v[70:73]
	s_barrier
	s_setprio 0
	s_mov_b32 m0, s79
	v_lshl_add_u64 v[186:187], s[40:41], 0, v[174:175]
	s_add_u32 s88, s40, 0x2b0000
	ds_read_b128 v[162:165], v180 offset:16384
	ds_read_b128 v[166:169], v180 offset:17408
	ds_read_b128 v[182:185], v180 offset:18432
	ds_read_b128 v[190:193], v180 offset:19456
	ds_read_b128 v[194:197], v180 offset:20480
	ds_read_b128 v[208:211], v180 offset:21504
	ds_read_b128 v[212:215], v180 offset:22528
	ds_read_b128 v[216:219], v180 offset:23552
	global_load_lds_dwordx4 v[186:187], off
	v_lshl_add_u64 v[198:199], s[40:41], 0, v[178:179]
	s_mov_b32 m0, s80
	s_addc_u32 s89, s41, 0
	global_load_lds_dwordx4 v[198:199], off
	v_lshl_add_u64 v[204:205], s[88:89], 0, v[174:175]
	s_mov_b32 m0, s81
	v_lshl_add_u64 v[220:221], s[42:43], 0, v[176:177]
	global_load_lds_dwordx4 v[204:205], off
	v_lshl_add_u64 v[204:205], s[88:89], 0, v[178:179]
	s_mov_b32 m0, s82
	s_nop 0
	global_load_lds_dwordx4 v[204:205], off
	v_lshl_add_u64 v[204:205], s[42:43], 0, v[172:173]
	s_mov_b32 m0, s58
	s_nop 0
	global_load_lds_dwordx4 v[204:205], off
	s_mov_b32 m0, s60
	s_nop 0
	global_load_lds_dwordx4 v[220:221], off
	s_waitcnt vmcnt(8)
	s_waitcnt lgkmcnt(0)
	s_setprio 3
	s_barrier
; #define PG8_STAGE(bufoff, gbase, voff) do { _Pragma("unroll") for (int _i = 0; _i < 2; ++_i) \
;         __builtin_amdgcn_global_load_lds((const unsigned*)((const char*)(gbase) + (voff)[_i]), (PG8_LAS unsigned*)(lds + (bufoff) + ldsw + _i * 8192), 16, 0, 0); } while (0)
; #define PG8_LDA(dst, b, h) do { _Pragma("unroll") for (int m = 0; m < 4; ++m) _Pragma("unroll") for (int k = 0; k < 2; ++k) dst[m][k] = *(const PG8_LAS bf16x8*)(lds + PG8_SA(b, h) + aoff + m * 2048 + k * 1024); } while (0)
; #define PG8_LDB(dst, b, h) do { _Pragma("unroll") for (int n = 0; n < 2; ++n) _Pragma("unroll") for (int k = 0; k < 2; ++k) dst[n][k] = *(const PG8_LAS bf16x8*)(lds + PG8_SB(b, h) + boff + n * 2048 + k * 1024); } while (0)
; #define PG8_MMA(ai, bj, At, Bt) do { __builtin_amdgcn_s_setprio(3); _Pragma("unroll") for (int m = 0; m < 4; ++m) _Pragma("unroll") for (int n = 0; n < 2; ++n) _Pragma("unroll") for (int k = 0; k < 2; ++k) \
;         acc[ai][bj][m][n] = __builtin_amdgcn_mfma_f32_16x16x32_bf16(Bt[n][k], At[m][k], acc[ai][bj][m][n], 0, 0, 0); __builtin_amdgcn_s_setprio(0); } while (0)
; #define PG8_WAIT_V(n) asm volatile("s_waitcnt vmcnt(" #n ")" ::: "memory")
; #define PG8_WAIT_L(n) asm volatile("s_waitcnt lgkmcnt(" #n ")" ::: "memory")
; #define PG8_BAR __builtin_amdgcn_s_barrier()
; #define PG8_SCHED __builtin_amdgcn_sched_barrier(0)
; template <class Epi, class Sched, bool ALIGN_EPI = false, bool SP2 = false>
; __device__ __forceinline__ void gemm_phase(PG8_LAS unsigned char* lds, const Gemm g, const Sched& S, const Epi& E) {
;     ...
;             PG8_WAIT_V(8); PG8_WAIT_L(0); PG8_BAR; PG8_MMA(1, 0, At, B0); PG8_MMA(1, 1, At, B1); PG8_BAR; PG8_SCHED;
;             PG8_LDB(B0, 1, 0); PG8_LDB(B1, 1, 1); PG8_SCHED; PG8_LDA(At, 1, 0); PG8_STAGE(PG8_SA(0, 1), a2 + hstepA, voffA);
;             PG8_WAIT_V(8); PG8_WAIT_L(0); PG8_BAR; PG8_MMA(0, 0, At, B0); PG8_MMA(0, 1, At, B1); PG8_BAR; PG8_SCHED;
	v_mfma_f32_16x16x32_bf16 v[62:65], v[130:133], v[162:165], v[62:65]
	v_mfma_f32_16x16x32_bf16 v[62:65], v[134:137], v[166:169], v[62:65]
	v_mfma_f32_16x16x32_bf16 v[58:61], v[138:141], v[162:165], v[58:61]
	v_mfma_f32_16x16x32_bf16 v[58:61], v[142:145], v[166:169], v[58:61]
	v_mfma_f32_16x16x32_bf16 v[42:45], v[138:141], v[182:185], v[42:45]
	v_mfma_f32_16x16x32_bf16 v[42:45], v[142:145], v[190:193], v[42:45]
	v_mfma_f32_16x16x32_bf16 v[46:49], v[130:133], v[182:185], v[46:49]
	v_mfma_f32_16x16x32_bf16 v[46:49], v[134:137], v[190:193], v[46:49]
	v_mfma_f32_16x16x32_bf16 v[30:33], v[130:133], v[194:197], v[30:33]
	v_mfma_f32_16x16x32_bf16 v[30:33], v[134:137], v[208:211], v[30:33]
	v_mfma_f32_16x16x32_bf16 v[26:29], v[138:141], v[194:197], v[26:29]
	v_mfma_f32_16x16x32_bf16 v[26:29], v[142:145], v[208:211], v[26:29]
	v_mfma_f32_16x16x32_bf16 v[10:13], v[138:141], v[212:215], v[10:13]
	v_mfma_f32_16x16x32_bf16 v[10:13], v[142:145], v[216:219], v[10:13]
	v_mfma_f32_16x16x32_bf16 v[14:17], v[130:133], v[212:215], v[14:17]
	v_mfma_f32_16x16x32_bf16 v[14:17], v[134:137], v[216:219], v[14:17]
	v_mfma_f32_16x16x32_bf16 v[54:57], v[146:149], v[162:165], v[54:57]
	v_mfma_f32_16x16x32_bf16 v[54:57], v[150:153], v[166:169], v[54:57]
	v_mfma_f32_16x16x32_bf16 v[50:53], v[154:157], v[162:165], v[50:53]
	v_mfma_f32_16x16x32_bf16 v[50:53], v[158:161], v[166:169], v[50:53]
	v_mfma_f32_16x16x32_bf16 v[34:37], v[154:157], v[182:185], v[34:37]
	v_mfma_f32_16x16x32_bf16 v[34:37], v[158:161], v[190:193], v[34:37]
	v_mfma_f32_16x16x32_bf16 v[38:41], v[146:149], v[182:185], v[38:41]
	v_mfma_f32_16x16x32_bf16 v[38:41], v[150:153], v[190:193], v[38:41]
	v_mfma_f32_16x16x32_bf16 v[22:25], v[146:149], v[194:197], v[22:25]
	v_mfma_f32_16x16x32_bf16 v[22:25], v[150:153], v[208:211], v[22:25]
	v_mfma_f32_16x16x32_bf16 v[18:21], v[154:157], v[194:197], v[18:21]
	v_mfma_f32_16x16x32_bf16 v[18:21], v[158:161], v[208:211], v[18:21]
	v_mfma_f32_16x16x32_bf16 v[2:5], v[154:157], v[212:215], v[2:5]
	v_mfma_f32_16x16x32_bf16 v[2:5], v[158:161], v[216:219], v[2:5]
	v_mfma_f32_16x16x32_bf16 v[6:9], v[146:149], v[212:215], v[6:9]
	v_mfma_f32_16x16x32_bf16 v[6:9], v[150:153], v[216:219], v[6:9]
	s_barrier
	s_setprio 0
	v_add_u32_e32 v142, s52, v189
	v_add_u32_e32 v158, s53, v189
	ds_read_b128 v[130:133], v142
	ds_read_b128 v[134:137], v142 offset:1024
	ds_read_b128 v[138:141], v142 offset:2048
	ds_read_b128 v[142:145], v142 offset:3072
	ds_read_b128 v[146:149], v158
	ds_read_b128 v[150:153], v158 offset:1024
	ds_read_b128 v[154:157], v158 offset:2048
	ds_read_b128 v[158:161], v158 offset:3072
	s_add_u32 s42, s42, 0x2b0000
	s_addc_u32 s43, s43, 0
	s_mov_b32 m0, s61
	v_lshl_add_u64 v[222:223], s[42:43], 0, v[172:173]
	ds_read_b128 v[162:165], v180 offset:32768
	ds_read_b128 v[166:169], v180 offset:33792
	ds_read_b128 v[182:185], v180 offset:34816
	ds_read_b128 v[190:193], v180 offset:35840
	ds_read_b128 v[194:197], v180 offset:36864
	ds_read_b128 v[208:211], v180 offset:37888
	ds_read_b128 v[212:215], v180 offset:38912
	ds_read_b128 v[216:219], v180 offset:39936
	global_load_lds_dwordx4 v[222:223], off
	v_lshl_add_u64 v[222:223], s[42:43], 0, v[176:177]
	s_mov_b32 m0, s62
	s_nop 0
	global_load_lds_dwordx4 v[222:223], off
	s_waitcnt vmcnt(8)
	s_waitcnt lgkmcnt(0)
	s_setprio 3
	s_barrier
	v_mfma_f32_16x16x32_bf16 v[126:129], v[130:133], v[162:165], v[126:129]
	v_mfma_f32_16x16x32_bf16 v[126:129], v[134:137], v[166:169], v[126:129]
	v_mfma_f32_16x16x32_bf16 v[122:125], v[138:141], v[162:165], v[122:125]
	v_mfma_f32_16x16x32_bf16 v[122:125], v[142:145], v[166:169], v[122:125]
	v_mfma_f32_16x16x32_bf16 v[94:97], v[138:141], v[182:185], v[94:97]
	v_mfma_f32_16x16x32_bf16 v[94:97], v[142:145], v[190:193], v[94:97]
	v_mfma_f32_16x16x32_bf16 v[98:101], v[130:133], v[182:185], v[98:101]
	v_mfma_f32_16x16x32_bf16 v[98:101], v[134:137], v[190:193], v[98:101]
	v_mfma_f32_16x16x32_bf16 v[110:113], v[130:133], v[194:197], v[110:113]
	v_mfma_f32_16x16x32_bf16 v[110:113], v[134:137], v[208:211], v[110:113]
	v_mfma_f32_16x16x32_bf16 v[106:109], v[138:141], v[194:197], v[106:109]
	v_mfma_f32_16x16x32_bf16 v[106:109], v[142:145], v[208:211], v[106:109]
	v_mfma_f32_16x16x32_bf16 v[74:77], v[138:141], v[212:215], v[74:77]
	v_mfma_f32_16x16x32_bf16 v[74:77], v[142:145], v[216:219], v[74:77]
	v_mfma_f32_16x16x32_bf16 v[78:81], v[130:133], v[212:215], v[78:81]
	v_mfma_f32_16x16x32_bf16 v[78:81], v[134:137], v[216:219], v[78:81]
	v_mfma_f32_16x16x32_bf16 v[118:121], v[146:149], v[162:165], v[118:121]
	v_mfma_f32_16x16x32_bf16 v[118:121], v[150:153], v[166:169], v[118:121]
	v_mfma_f32_16x16x32_bf16 v[114:117], v[154:157], v[162:165], v[114:117]
	v_mfma_f32_16x16x32_bf16 v[114:117], v[158:161], v[166:169], v[114:117]
	v_mfma_f32_16x16x32_bf16 v[86:89], v[154:157], v[182:185], v[86:89]
	v_mfma_f32_16x16x32_bf16 v[86:89], v[158:161], v[190:193], v[86:89]
	v_mfma_f32_16x16x32_bf16 v[90:93], v[146:149], v[182:185], v[90:93]
	v_mfma_f32_16x16x32_bf16 v[90:93], v[150:153], v[190:193], v[90:93]
	v_mfma_f32_16x16x32_bf16 v[102:105], v[146:149], v[194:197], v[102:105]
	v_mfma_f32_16x16x32_bf16 v[102:105], v[150:153], v[208:211], v[102:105]
	v_mfma_f32_16x16x32_bf16 v[82:85], v[154:157], v[194:197], v[82:85]
	v_mfma_f32_16x16x32_bf16 v[82:85], v[158:161], v[208:211], v[82:85]
	v_mfma_f32_16x16x32_bf16 v[66:69], v[154:157], v[212:215], v[66:69]
	v_mfma_f32_16x16x32_bf16 v[66:69], v[158:161], v[216:219], v[66:69]
	v_mfma_f32_16x16x32_bf16 v[70:73], v[146:149], v[212:215], v[70:73]
	v_mfma_f32_16x16x32_bf16 v[70:73], v[150:153], v[216:219], v[70:73]
	s_barrier
; #define PG8_STAGE(bufoff, gbase, voff) do { _Pragma("unroll") for (int _i = 0; _i < 2; ++_i) \
;         __builtin_amdgcn_global_load_lds((const unsigned*)((const char*)(gbase) + (voff)[_i]), (PG8_LAS unsigned*)(lds + (bufoff) + ldsw + _i * 8192), 16, 0, 0); } while (0)
; #define PG8_LDA(dst, b, h) do { _Pragma("unroll") for (int m = 0; m < 4; ++m) _Pragma("unroll") for (int k = 0; k < 2; ++k) dst[m][k] = *(const PG8_LAS bf16x8*)(lds + PG8_SA(b, h) + aoff + m * 2048 + k * 1024); } while (0)
; #define PG8_MMA(ai, bj, At, Bt) do { __builtin_amdgcn_s_setprio(3); _Pragma("unroll") for (int m = 0; m < 4; ++m) _Pragma("unroll") for (int n = 0; n < 2; ++n) _Pragma("unroll") for (int k = 0; k < 2; ++k) \
;         acc[ai][bj][m][n] = __builtin_amdgcn_mfma_f32_16x16x32_bf16(Bt[n][k], At[m][k], acc[ai][bj][m][n], 0, 0, 0); __builtin_amdgcn_s_setprio(0); } while (0)
; #define PG8_WAIT_V(n) asm volatile("s_waitcnt vmcnt(" #n ")" ::: "memory")
; #define PG8_WAIT_L(n) asm volatile("s_waitcnt lgkmcnt(" #n ")" ::: "memory")
; #define PG8_BAR __builtin_amdgcn_s_barrier()
; #define PG8_SCHED __builtin_amdgcn_sched_barrier(0)
; template <class Epi, class Sched, bool ALIGN_EPI = false, bool SP2 = false>
; __device__ __forceinline__ void gemm_phase(PG8_LAS unsigned char* lds, const Gemm g, const Sched& S, const Epi& E) {
;     ...
;             PG8_LDA(At, 1, 1); PG8_STAGE(PG8_SB(1, 0), b3, voffB); PG8_STAGE(PG8_SB(1, 1), b3 + hstepB, voffB); PG8_STAGE(PG8_SA(1, 0), a3, voffA);
;             PG8_WAIT_V(8); PG8_WAIT_L(0); PG8_BAR; PG8_MMA(1, 0, At, B0); PG8_MMA(1, 1, At, B1); PG8_BAR; PG8_SCHED;
	s_setprio 0
	s_mov_b32 m0, s83
	v_lshl_add_u64 v[186:187], v[186:187], 0, s[18:19]
	s_add_u32 s40, s40, 0x2b0080
	ds_read_b128 v[162:165], v180 offset:49152
	ds_read_b128 v[166:169], v180 offset:50176
	ds_read_b128 v[182:185], v180 offset:51200
	ds_read_b128 v[190:193], v180 offset:52224
	ds_read_b128 v[194:197], v180 offset:53248
	ds_read_b128 v[208:211], v180 offset:54272
	ds_read_b128 v[212:215], v180 offset:55296
	ds_read_b128 v[216:219], v180 offset:56320
	global_load_lds_dwordx4 v[186:187], off
	v_lshl_add_u64 v[186:187], v[198:199], 0, s[18:19]
	s_mov_b32 m0, s84
	s_addc_u32 s41, s41, 0
	global_load_lds_dwordx4 v[186:187], off
	v_lshl_add_u64 v[186:187], s[40:41], 0, v[174:175]
	s_mov_b32 m0, s85
	s_nop 0
	global_load_lds_dwordx4 v[186:187], off
	v_lshl_add_u64 v[186:187], s[40:41], 0, v[178:179]
	s_mov_b32 m0, s86
	s_nop 0
	global_load_lds_dwordx4 v[186:187], off
	v_lshl_add_u64 v[186:187], v[204:205], 0, s[18:19]
	s_mov_b32 m0, s63
	s_nop 0
	global_load_lds_dwordx4 v[186:187], off
	v_lshl_add_u64 v[186:187], v[220:221], 0, s[18:19]
	s_mov_b32 m0, s64
	s_nop 0
	global_load_lds_dwordx4 v[186:187], off
	s_waitcnt vmcnt(8)
	s_waitcnt lgkmcnt(0)
	s_setprio 3
	s_barrier
	v_mfma_f32_16x16x32_bf16 v[62:65], v[130:133], v[162:165], v[62:65]
	v_mfma_f32_16x16x32_bf16 v[62:65], v[134:137], v[166:169], v[62:65]
	v_mfma_f32_16x16x32_bf16 v[58:61], v[138:141], v[162:165], v[58:61]
	v_mfma_f32_16x16x32_bf16 v[58:61], v[142:145], v[166:169], v[58:61]
	v_mfma_f32_16x16x32_bf16 v[42:45], v[138:141], v[182:185], v[42:45]
	v_mfma_f32_16x16x32_bf16 v[42:45], v[142:145], v[190:193], v[42:45]
	v_mfma_f32_16x16x32_bf16 v[46:49], v[130:133], v[182:185], v[46:49]
	v_mfma_f32_16x16x32_bf16 v[46:49], v[134:137], v[190:193], v[46:49]
	v_mfma_f32_16x16x32_bf16 v[30:33], v[130:133], v[194:197], v[30:33]
	v_mfma_f32_16x16x32_bf16 v[30:33], v[134:137], v[208:211], v[30:33]
	v_mfma_f32_16x16x32_bf16 v[26:29], v[138:141], v[194:197], v[26:29]
	v_mfma_f32_16x16x32_bf16 v[26:29], v[142:145], v[208:211], v[26:29]
	v_mfma_f32_16x16x32_bf16 v[10:13], v[138:141], v[212:215], v[10:13]
	v_mfma_f32_16x16x32_bf16 v[10:13], v[142:145], v[216:219], v[10:13]
	v_mfma_f32_16x16x32_bf16 v[14:17], v[130:133], v[212:215], v[14:17]
	v_mfma_f32_16x16x32_bf16 v[14:17], v[134:137], v[216:219], v[14:17]
	v_mfma_f32_16x16x32_bf16 v[54:57], v[146:149], v[162:165], v[54:57]
	v_mfma_f32_16x16x32_bf16 v[54:57], v[150:153], v[166:169], v[54:57]
	v_mfma_f32_16x16x32_bf16 v[50:53], v[154:157], v[162:165], v[50:53]
	v_mfma_f32_16x16x32_bf16 v[50:53], v[158:161], v[166:169], v[50:53]
	v_mfma_f32_16x16x32_bf16 v[34:37], v[154:157], v[182:185], v[34:37]
	v_mfma_f32_16x16x32_bf16 v[34:37], v[158:161], v[190:193], v[34:37]
	v_mfma_f32_16x16x32_bf16 v[38:41], v[146:149], v[182:185], v[38:41]
	v_mfma_f32_16x16x32_bf16 v[38:41], v[150:153], v[190:193], v[38:41]
	v_mfma_f32_16x16x32_bf16 v[22:25], v[146:149], v[194:197], v[22:25]
	v_mfma_f32_16x16x32_bf16 v[22:25], v[150:153], v[208:211], v[22:25]
	v_mfma_f32_16x16x32_bf16 v[18:21], v[154:157], v[194:197], v[18:21]
	v_mfma_f32_16x16x32_bf16 v[18:21], v[158:161], v[208:211], v[18:21]
	v_mfma_f32_16x16x32_bf16 v[2:5], v[154:157], v[212:215], v[2:5]
	v_mfma_f32_16x16x32_bf16 v[2:5], v[158:161], v[216:219], v[2:5]
	v_mfma_f32_16x16x32_bf16 v[6:9], v[146:149], v[212:215], v[6:9]
	v_mfma_f32_16x16x32_bf16 v[6:9], v[150:153], v[216:219], v[6:9]
	s_barrier
	s_setprio 0
	s_add_i32 s67, s67, 2
	s_add_u32 s22, s22, 0x100
	s_addc_u32 s23, s23, 0
	s_cmpk_gt_u32 s67, 0xa9
	s_cbranch_scc1 .LBB0_1021
